# attA loop instruction diet (packed row sums, merged waits, saddr DMA) + saddr form for 61 GEMM LDS-DMA loads
# speedup vs baseline: 1.2409x; 1.0054x over previous
;     __device__ __forceinline__ size_t boff(const Unit& u, size_t tstepB) const { return (size_t)u.pn * tstepB; }
; #define PG8_STAGE(bufoff, gbase, voff) do { _Pragma("unroll") for (int _i = 0; _i < 2; ++_i) \
;         __builtin_amdgcn_global_load_lds((const unsigned*)((const char*)(gbase) + (voff)[_i]), (PG8_LAS unsigned*)(lds + (bufoff) + ldsw + _i * 8192), 16, 0, 0); } while (0)
; #define PG8_WAIT_V(n) asm volatile("s_waitcnt vmcnt(" #n ")" ::: "memory")
; #define PG8_BAR __builtin_amdgcn_s_barrier()
; template <class Epi, class Sched, bool ALIGN_EPI = false, bool SP2 = false>
; __device__ __forceinline__ void gemm_phase(PG8_LAS unsigned char* lds, const Gemm g, const Sched& S, const Epi& E) {
;     const int tid = threadIdx.x, wid = __builtin_amdgcn_readfirstlane(tid >> 6), lane = tid & 63, wr = wid >> 2, wc = wid & 3, fr = lane & 15, fq = lane >> 4;
;     const int K = g.K, nt = K / BK;
;     unsigned voffA[2], voffB[2];
; #pragma unroll
;     for (int i = 0; i < 2; ++i) { int R, C; stage_rc(tid * 16 + i * 8192, R, C); const int Rb = Epi::PERM ? ((R & ~31) + perm32(R & 31)) : R;
;         voffA[i] = (unsigned)(R * g.lda + C) * 2u; voffB[i] = (unsigned)(Rb * g.ldb + C) * 2u; }
;     const size_t kstep = (size_t)(BK * 2);
;     const size_t hstepA = (size_t)HALF * g.lda * 2, hstepB = (size_t)HALF * g.ldb * 2;
;     const size_t tstepA = (size_t)g.arows * g.lda * 2, tstepB = 2 * hstepB;
;     const unsigned ldsw = (unsigned)wid * 1024u;
;     const int aoff = lds_byte(wr * 64 + fr, fq * 8), boff = lds_byte(wc * 32 + fr, fq * 8);
;     ...
;         PG8_STAGE(PG8_SB(0, 0), cB, voffB); PG8_STAGE(PG8_SB(0, 1), cB + hstepB, voffB); PG8_STAGE(PG8_SA(0, 0), cA, voffA); PG8_STAGE(PG8_SA(0, 1), cA + hstepA, voffA);
;         if (wr == 1) PG8_BAR;
;         PG8_WAIT_V(2); PG8_BAR;
;         PG8_STAGE(PG8_SB(1, 0), cB + kstep, voffB); PG8_STAGE(PG8_SA(1, 0), cA + kstep, voffA); PG8_STAGE(PG8_SB(1, 1), cB + hstepB + kstep, voffB);
;         PG8_WAIT_V(6); PG8_BAR;
.LBB0_144:
	s_mov_b64 s[38:39], 0x80
	s_and_b32 s1, s3, 3
	s_add_i32 m0, s31, 0x18000
	v_lshl_add_u64 v[6:7], v[6:7], 0, s[38:39]
	s_lshl_b32 s42, s0, 13
	s_lshl_b32 s43, s1, 12
	s_waitcnt vmcnt(2)
	s_barrier
	global_load_lds_dwordx4 v[6:7], off
	v_lshl_add_u64 v[4:5], v[4:5], 0, s[38:39]
	s_add_i32 m0, s31, 0x1a000
	s_add_i32 s56, s31, 0x8000
	s_add_i32 s57, s31, 0xa000
	global_load_lds_dwordx4 v[4:5], off
	v_lshl_add_u64 v[0:1], v[0:1], 0, s[38:39]
	s_mov_b32 m0, s56
	s_add_u32 s40, s50, 0x40080
	global_load_lds_dwordx4 v[0:1], off
	v_lshl_add_u64 v[0:1], v[2:3], 0, s[38:39]
	s_mov_b32 m0, s57
	s_addc_u32 s41, s51, 0
	global_load_lds_dwordx4 v[0:1], off
	s_add_i32 m0, s31, 0x1c000
	global_load_lds_dwordx4 v130, s[40:41]
	v_lshl_add_u64 v[0:1], s[40:41], 0, v[134:135]
	s_add_i32 m0, s31, 0x1e000
	v_lshl_or_b32 v158, s0, 6, v156
	global_load_lds_dwordx4 v[0:1], off
	v_and_b32_e32 v0, 3, v153
	v_lshlrev_b32_e32 v1, 3, v0
	v_lshlrev_b32_e32 v2, 4, v0
	v_or_b32_e32 v0, v0, v156
	v_lshl_or_b32 v160, s1, 5, v1
	v_cmp_eq_u32_e64 s[0:1], 0, v0
	v_lshlrev_b32_e32 v0, 8, v176
	v_and_b32_e32 v0, 0x38000, v0
	v_lshlrev_b32_e32 v1, 11, v152
	s_cmpk_lt_u32 s2, 0x100
	v_or3_b32 v0, v150, v0, v1
	s_cselect_b64 s[40:41], -1, 0
	s_bfe_u32 s3, s3, 0x10001
	s_lshr_b32 s2, s2, 4
	v_add_u32_e32 v138, v0, v151
	v_lshlrev_b32_e32 v0, 4, v154
	v_lshlrev_b32_e32 v4, 2, v156
	s_or_b32 s58, s3, 0x7ffffff0
	s_or_b32 s59, s3, 0x7ffffff2
	s_ashr_i32 s70, s90, 31
	s_ashr_i32 s71, s97, 31
	s_and_b32 s2, s2, 4
	v_and_b32_e32 v0, 0x78000, v0
	v_lshl_or_b32 v3, v156, 6, v2
	v_and_b32_e32 v4, 32, v4
	v_or_b32_e32 v2, v2, v155
	s_waitcnt vmcnt(6)
	s_add_u32 s72, s68, s2
	v_or3_b32 v0, v150, v0, v1
	v_bitop3_b32 v3, v3, s42, v4 bitop3:0xde
	v_bitop3_b32 v159, s43, v2, v157 bitop3:0xf6
	s_addc_u32 s73, s69, 0
	v_add_u32_e32 v140, v0, v151
	s_add_i32 s74, 0, 0x10000
	s_add_i32 s75, 0, 0x14000
	v_mbcnt_lo_u32_b32 v0, -1, 0
	v_mov_b32_e32 v139, v136
	v_mov_b32_e32 v141, v136
	v_mov_b64_e32 v[142:143], 0x680
	v_mov_b64_e32 v[144:145], 0x67f
	v_add_u32_e32 v161, s74, v159
	v_add_u32_e32 v162, s75, v159
	v_add_u32_e32 v163, 0, v3
	s_movk_i32 s76, 0x3400
	v_mbcnt_hi_u32_b32 v164, -1, v0
	s_barrier
	s_branch .LBB0_147

; #define PG8_STAGE(bufoff, gbase, voff) do { _Pragma("unroll") for (int _i = 0; _i < 2; ++_i) \
;         __builtin_amdgcn_global_load_lds((const unsigned*)((const char*)(gbase) + (voff)[_i]), (PG8_LAS unsigned*)(lds + (bufoff) + ldsw + _i * 8192), 16, 0, 0); } while (0)
; #define PG8_LDA(dst, b, h) do { _Pragma("unroll") for (int m = 0; m < 4; ++m) _Pragma("unroll") for (int k = 0; k < 2; ++k) dst[m][k] = *(const PG8_LAS bf16x8*)(lds + PG8_SA(b, h) + aoff + m * 2048 + k * 1024); } while (0)
; #define PG8_LDB(dst, b, h) do { _Pragma("unroll") for (int n = 0; n < 2; ++n) _Pragma("unroll") for (int k = 0; k < 2; ++k) dst[n][k] = *(const PG8_LAS bf16x8*)(lds + PG8_SB(b, h) + boff + n * 2048 + k * 1024); } while (0)
; #define PG8_MMA(ai, bj, At, Bt) do { __builtin_amdgcn_s_setprio(1); _Pragma("unroll") for (int m = 0; m < 4; ++m) _Pragma("unroll") for (int n = 0; n < 2; ++n) _Pragma("unroll") for (int k = 0; k < 2; ++k) \
;         acc[ai][bj][m][n] = __builtin_amdgcn_mfma_f32_16x16x32_bf16(Bt[n][k], At[m][k], acc[ai][bj][m][n], 0, 0, 0); __builtin_amdgcn_s_setprio(0); } while (0)
; #define PG8_WAIT_V(n) asm volatile("s_waitcnt vmcnt(" #n ")" ::: "memory")
; #define PG8_WAIT_L(n) asm volatile("s_waitcnt lgkmcnt(" #n ")" ::: "memory")
; #define PG8_BAR __builtin_amdgcn_s_barrier()
; #define PG8_SCHED __builtin_amdgcn_sched_barrier(0)
; template <class Epi, class Sched, bool ALIGN_EPI = false, bool SP2 = false>
; __device__ __forceinline__ void gemm_phase(PG8_LAS unsigned char* lds, const Gemm g, const Sched& S, const Epi& E) {
;     ...
;             PG8_LDB(B0, 0, 0); PG8_LDB(B1, 0, 1); PG8_SCHED; PG8_LDA(At, 0, 0); PG8_STAGE(PG8_SA(1, 1), a1 + hstepA, voffA);
;             PG8_WAIT_V(8); PG8_WAIT_L(0); PG8_BAR; PG8_MMA(0, 0, At, B0); PG8_MMA(0, 1, At, B1); PG8_BAR; PG8_SCHED;
;             PG8_LDA(At, 0, 1); PG8_STAGE(PG8_SB(0, 0), b2, voffB); PG8_STAGE(PG8_SB(0, 1), b2 + hstepB, voffB); PG8_STAGE(PG8_SA(0, 0), a2, voffA);
;             PG8_WAIT_V(8); PG8_WAIT_L(0); PG8_BAR; PG8_MMA(1, 0, At, B0); PG8_MMA(1, 1, At, B1); PG8_BAR; PG8_SCHED;
.LBB0_150:
	ds_read_b128 v[146:149], v161
	ds_read_b128 v[166:169], v161 offset:1024
	ds_read_b128 v[170:173], v161 offset:2048
	ds_read_b128 v[178:181], v161 offset:3072
	ds_read_b128 v[182:185], v162
	ds_read_b128 v[186:189], v162 offset:1024
	ds_read_b128 v[190:193], v162 offset:2048
	ds_read_b128 v[194:197], v162 offset:3072
	s_add_u32 s50, s4, 0xfffc0080
	s_addc_u32 s51, s5, -1
	s_cmp_eq_u32 s84, 12
	s_cselect_b32 s53, s45, s51
	s_cselect_b32 s52, s77, s50
	s_cselect_b32 s51, s43, s83
	s_cselect_b32 s50, s81, s82
	s_add_i32 m0, s31, 0xc000
	ds_read_b128 v[202:205], v163
	ds_read_b128 v[206:209], v163 offset:1024
	ds_read_b128 v[210:213], v163 offset:2048
	ds_read_b128 v[214:217], v163 offset:3072
	ds_read_b128 v[218:221], v163 offset:4096
	ds_read_b128 v[222:225], v163 offset:5120
	ds_read_b128 v[226:229], v163 offset:6144
	ds_read_b128 v[230:233], v163 offset:7168
	global_load_lds_dwordx4 v138, s[4:5]
	s_add_i32 m0, s31, 0xe000
	s_nop 0
	global_load_lds_dwordx4 v140, s[4:5]
	s_waitcnt vmcnt(8)
	s_waitcnt lgkmcnt(0)
	s_barrier
	s_setprio 1
	s_waitcnt lgkmcnt(0)
	v_mfma_f32_16x16x32_bf16 v[124:127], v[146:149], v[202:205], v[124:127]
	v_mfma_f32_16x16x32_bf16 v[120:123], v[170:173], v[202:205], v[120:123]
	v_mfma_f32_16x16x32_bf16 v[108:111], v[146:149], v[210:213], v[108:111]
	v_mfma_f32_16x16x32_bf16 v[104:107], v[170:173], v[210:213], v[104:107]
	v_mfma_f32_16x16x32_bf16 v[92:95], v[146:149], v[218:221], v[92:95]
	v_mfma_f32_16x16x32_bf16 v[88:91], v[170:173], v[218:221], v[88:91]
	v_mfma_f32_16x16x32_bf16 v[76:79], v[146:149], v[226:229], v[76:79]
	v_mfma_f32_16x16x32_bf16 v[72:75], v[170:173], v[226:229], v[72:75]
	v_mfma_f32_16x16x32_bf16 v[124:127], v[166:169], v[206:209], v[124:127]
	v_mfma_f32_16x16x32_bf16 v[120:123], v[178:181], v[206:209], v[120:123]
	v_mfma_f32_16x16x32_bf16 v[108:111], v[166:169], v[214:217], v[108:111]
	v_mfma_f32_16x16x32_bf16 v[104:107], v[178:181], v[214:217], v[104:107]
	v_mfma_f32_16x16x32_bf16 v[92:95], v[166:169], v[222:225], v[92:95]
	v_mfma_f32_16x16x32_bf16 v[88:91], v[178:181], v[222:225], v[88:91]
	v_mfma_f32_16x16x32_bf16 v[76:79], v[166:169], v[230:233], v[76:79]
	v_mfma_f32_16x16x32_bf16 v[72:75], v[178:181], v[230:233], v[72:75]
	s_setprio 0
	s_setprio 1
	v_mfma_f32_16x16x32_bf16 v[116:119], v[182:185], v[202:205], v[116:119]
	v_mfma_f32_16x16x32_bf16 v[112:115], v[190:193], v[202:205], v[112:115]
	v_mfma_f32_16x16x32_bf16 v[100:103], v[182:185], v[210:213], v[100:103]
	v_mfma_f32_16x16x32_bf16 v[96:99], v[190:193], v[210:213], v[96:99]
	v_mfma_f32_16x16x32_bf16 v[84:87], v[182:185], v[218:221], v[84:87]
	v_mfma_f32_16x16x32_bf16 v[80:83], v[190:193], v[218:221], v[80:83]
	v_mfma_f32_16x16x32_bf16 v[68:71], v[182:185], v[226:229], v[68:71]
	v_mfma_f32_16x16x32_bf16 v[64:67], v[190:193], v[226:229], v[64:67]
	v_mfma_f32_16x16x32_bf16 v[116:119], v[186:189], v[206:209], v[116:119]
	v_mfma_f32_16x16x32_bf16 v[112:115], v[194:197], v[206:209], v[112:115]
	v_mfma_f32_16x16x32_bf16 v[100:103], v[186:189], v[214:217], v[100:103]
	v_mfma_f32_16x16x32_bf16 v[96:99], v[194:197], v[214:217], v[96:99]
	v_mfma_f32_16x16x32_bf16 v[84:87], v[186:189], v[222:225], v[84:87]
	v_mfma_f32_16x16x32_bf16 v[80:83], v[194:197], v[222:225], v[80:83]
	v_mfma_f32_16x16x32_bf16 v[68:71], v[186:189], v[230:233], v[68:71]
	v_mfma_f32_16x16x32_bf16 v[64:67], v[194:197], v[230:233], v[64:67]
	s_setprio 0
	s_barrier
	s_add_i32 s85, s74, s11
	v_lshl_add_u64 v[174:175], s[50:51], 0, v[130:131]
	s_mov_b32 m0, s85
	ds_read_b128 v[202:205], v163 offset:16384
	ds_read_b128 v[206:209], v163 offset:17408
	ds_read_b128 v[210:213], v163 offset:18432
	ds_read_b128 v[214:217], v163 offset:19456
	ds_read_b128 v[218:221], v163 offset:20480
	ds_read_b128 v[222:225], v163 offset:21504
	ds_read_b128 v[226:229], v163 offset:22528
	ds_read_b128 v[230:233], v163 offset:23552
	global_load_lds_dwordx4 v[174:175], off
	s_add_i32 m0, s85, 0x2000
	s_add_u32 s86, s50, 0x40000
	v_lshl_add_u64 v[198:199], s[50:51], 0, v[134:135]
	s_addc_u32 s87, s51, 0
	s_add_i32 s85, s75, s11
	global_load_lds_dwordx4 v[198:199], off
	s_mov_b32 m0, s85
	v_lshl_add_u64 v[236:237], s[52:53], 0, v[132:133]
	global_load_lds_dwordx4 v130, s[86:87]
	s_add_i32 m0, s85, 0x2000
	s_nop 0
	global_load_lds_dwordx4 v134, s[86:87]
	v_lshl_add_u64 v[234:235], s[52:53], 0, v[128:129]
	s_mov_b32 m0, s31
	s_nop 0
	global_load_lds_dwordx4 v[234:235], off
	s_mov_b32 m0, s33
	s_nop 0
	global_load_lds_dwordx4 v[236:237], off
	s_waitcnt vmcnt(8)
	s_waitcnt lgkmcnt(0)
	s_barrier
; #define PG8_STAGE(bufoff, gbase, voff) do { _Pragma("unroll") for (int _i = 0; _i < 2; ++_i) \
;         __builtin_amdgcn_global_load_lds((const unsigned*)((const char*)(gbase) + (voff)[_i]), (PG8_LAS unsigned*)(lds + (bufoff) + ldsw + _i * 8192), 16, 0, 0); } while (0)
; #define PG8_LDA(dst, b, h) do { _Pragma("unroll") for (int m = 0; m < 4; ++m) _Pragma("unroll") for (int k = 0; k < 2; ++k) dst[m][k] = *(const PG8_LAS bf16x8*)(lds + PG8_SA(b, h) + aoff + m * 2048 + k * 1024); } while (0)
; #define PG8_LDB(dst, b, h) do { _Pragma("unroll") for (int n = 0; n < 2; ++n) _Pragma("unroll") for (int k = 0; k < 2; ++k) dst[n][k] = *(const PG8_LAS bf16x8*)(lds + PG8_SB(b, h) + boff + n * 2048 + k * 1024); } while (0)
; #define PG8_MMA(ai, bj, At, Bt) do { __builtin_amdgcn_s_setprio(1); _Pragma("unroll") for (int m = 0; m < 4; ++m) _Pragma("unroll") for (int n = 0; n < 2; ++n) _Pragma("unroll") for (int k = 0; k < 2; ++k) \
;         acc[ai][bj][m][n] = __builtin_amdgcn_mfma_f32_16x16x32_bf16(Bt[n][k], At[m][k], acc[ai][bj][m][n], 0, 0, 0); __builtin_amdgcn_s_setprio(0); } while (0)
; #define PG8_WAIT_V(n) asm volatile("s_waitcnt vmcnt(" #n ")" ::: "memory")
; #define PG8_WAIT_L(n) asm volatile("s_waitcnt lgkmcnt(" #n ")" ::: "memory")
; #define PG8_BAR __builtin_amdgcn_s_barrier()
; #define PG8_SCHED __builtin_amdgcn_sched_barrier(0)
; template <class Epi, class Sched, bool ALIGN_EPI = false, bool SP2 = false>
; __device__ __forceinline__ void gemm_phase(PG8_LAS unsigned char* lds, const Gemm g, const Sched& S, const Epi& E) {
;     ...
;             PG8_WAIT_V(8); PG8_WAIT_L(0); PG8_BAR; PG8_MMA(1, 0, At, B0); PG8_MMA(1, 1, At, B1); PG8_BAR; PG8_SCHED;
;             PG8_LDB(B0, 1, 0); PG8_LDB(B1, 1, 1); PG8_SCHED; PG8_LDA(At, 1, 0); PG8_STAGE(PG8_SA(0, 1), a2 + hstepA, voffA);
;             PG8_WAIT_V(8); PG8_WAIT_L(0); PG8_BAR; PG8_MMA(0, 0, At, B0); PG8_MMA(0, 1, At, B1); PG8_BAR; PG8_SCHED;
	s_setprio 1
	s_waitcnt lgkmcnt(0)
	v_mfma_f32_16x16x32_bf16 v[60:63], v[146:149], v[202:205], v[60:63]
	v_mfma_f32_16x16x32_bf16 v[56:59], v[170:173], v[202:205], v[56:59]
	v_mfma_f32_16x16x32_bf16 v[44:47], v[146:149], v[210:213], v[44:47]
	v_mfma_f32_16x16x32_bf16 v[40:43], v[170:173], v[210:213], v[40:43]
	v_mfma_f32_16x16x32_bf16 v[28:31], v[146:149], v[218:221], v[28:31]
	v_mfma_f32_16x16x32_bf16 v[24:27], v[170:173], v[218:221], v[24:27]
	v_mfma_f32_16x16x32_bf16 v[12:15], v[146:149], v[226:229], v[12:15]
	v_mfma_f32_16x16x32_bf16 v[8:11], v[170:173], v[226:229], v[8:11]
	v_mfma_f32_16x16x32_bf16 v[60:63], v[166:169], v[206:209], v[60:63]
	v_mfma_f32_16x16x32_bf16 v[56:59], v[178:181], v[206:209], v[56:59]
	v_mfma_f32_16x16x32_bf16 v[44:47], v[166:169], v[214:217], v[44:47]
	v_mfma_f32_16x16x32_bf16 v[40:43], v[178:181], v[214:217], v[40:43]
	v_mfma_f32_16x16x32_bf16 v[28:31], v[166:169], v[222:225], v[28:31]
	v_mfma_f32_16x16x32_bf16 v[24:27], v[178:181], v[222:225], v[24:27]
	v_mfma_f32_16x16x32_bf16 v[12:15], v[166:169], v[230:233], v[12:15]
	v_mfma_f32_16x16x32_bf16 v[8:11], v[178:181], v[230:233], v[8:11]
	s_setprio 0
	s_setprio 1
	v_mfma_f32_16x16x32_bf16 v[52:55], v[182:185], v[202:205], v[52:55]
	v_mfma_f32_16x16x32_bf16 v[48:51], v[190:193], v[202:205], v[48:51]
	v_mfma_f32_16x16x32_bf16 v[36:39], v[182:185], v[210:213], v[36:39]
	v_mfma_f32_16x16x32_bf16 v[32:35], v[190:193], v[210:213], v[32:35]
	v_mfma_f32_16x16x32_bf16 v[20:23], v[182:185], v[218:221], v[20:23]
	v_mfma_f32_16x16x32_bf16 v[16:19], v[190:193], v[218:221], v[16:19]
	v_mfma_f32_16x16x32_bf16 v[4:7], v[182:185], v[226:229], v[4:7]
	v_mfma_f32_16x16x32_bf16 v[0:3], v[190:193], v[226:229], v[0:3]
	v_mfma_f32_16x16x32_bf16 v[52:55], v[186:189], v[206:209], v[52:55]
	v_mfma_f32_16x16x32_bf16 v[48:51], v[194:197], v[206:209], v[48:51]
	v_mfma_f32_16x16x32_bf16 v[36:39], v[186:189], v[214:217], v[36:39]
	v_mfma_f32_16x16x32_bf16 v[32:35], v[194:197], v[214:217], v[32:35]
	v_mfma_f32_16x16x32_bf16 v[20:23], v[186:189], v[222:225], v[20:23]
	v_mfma_f32_16x16x32_bf16 v[16:19], v[194:197], v[222:225], v[16:19]
	v_mfma_f32_16x16x32_bf16 v[4:7], v[186:189], v[230:233], v[4:7]
	v_mfma_f32_16x16x32_bf16 v[0:3], v[194:197], v[230:233], v[0:3]
	s_setprio 0
	s_barrier
	s_add_i32 s85, 0, 0x18000
	v_add_u32_e32 v137, s85, v159
	s_add_i32 s86, 0, 0x1c000
	ds_read_b128 v[146:149], v137
	ds_read_b128 v[166:169], v137 offset:1024
	ds_read_b128 v[170:173], v137 offset:2048
	ds_read_b128 v[178:181], v137 offset:3072
	v_add_u32_e32 v137, s86, v159
	ds_read_b128 v[182:185], v137
	ds_read_b128 v[186:189], v137 offset:1024
	ds_read_b128 v[190:193], v137 offset:2048
	ds_read_b128 v[194:197], v137 offset:3072
	s_add_u32 s52, s52, 0x40000
	s_addc_u32 s53, s53, 0
	s_mov_b32 m0, s35
	ds_read_b128 v[202:205], v163 offset:32768
	ds_read_b128 v[206:209], v163 offset:33792
	ds_read_b128 v[210:213], v163 offset:34816
	ds_read_b128 v[214:217], v163 offset:35840
	ds_read_b128 v[218:221], v163 offset:36864
	ds_read_b128 v[222:225], v163 offset:37888
	ds_read_b128 v[226:229], v163 offset:38912
	ds_read_b128 v[230:233], v163 offset:39936
	global_load_lds_dwordx4 v128, s[52:53]
	v_lshl_add_u64 v[238:239], s[52:53], 0, v[132:133]
	s_mov_b32 m0, s54
	s_nop 0
	global_load_lds_dwordx4 v[238:239], off
	s_waitcnt vmcnt(8)
	s_waitcnt lgkmcnt(0)
	s_barrier
	s_setprio 1
	s_waitcnt lgkmcnt(0)
	v_mfma_f32_16x16x32_bf16 v[124:127], v[146:149], v[202:205], v[124:127]
	v_mfma_f32_16x16x32_bf16 v[120:123], v[170:173], v[202:205], v[120:123]
	v_mfma_f32_16x16x32_bf16 v[108:111], v[146:149], v[210:213], v[108:111]
	v_mfma_f32_16x16x32_bf16 v[104:107], v[170:173], v[210:213], v[104:107]
	v_mfma_f32_16x16x32_bf16 v[92:95], v[146:149], v[218:221], v[92:95]
	v_mfma_f32_16x16x32_bf16 v[88:91], v[170:173], v[218:221], v[88:91]
	v_mfma_f32_16x16x32_bf16 v[76:79], v[146:149], v[226:229], v[76:79]
	v_mfma_f32_16x16x32_bf16 v[72:75], v[170:173], v[226:229], v[72:75]
	v_mfma_f32_16x16x32_bf16 v[124:127], v[166:169], v[206:209], v[124:127]
	v_mfma_f32_16x16x32_bf16 v[120:123], v[178:181], v[206:209], v[120:123]
	v_mfma_f32_16x16x32_bf16 v[108:111], v[166:169], v[214:217], v[108:111]
	v_mfma_f32_16x16x32_bf16 v[104:107], v[178:181], v[214:217], v[104:107]
	v_mfma_f32_16x16x32_bf16 v[92:95], v[166:169], v[222:225], v[92:95]
	v_mfma_f32_16x16x32_bf16 v[88:91], v[178:181], v[222:225], v[88:91]
	v_mfma_f32_16x16x32_bf16 v[76:79], v[166:169], v[230:233], v[76:79]
	v_mfma_f32_16x16x32_bf16 v[72:75], v[178:181], v[230:233], v[72:75]
	s_setprio 0
	s_setprio 1
	v_mfma_f32_16x16x32_bf16 v[116:119], v[182:185], v[202:205], v[116:119]
	v_mfma_f32_16x16x32_bf16 v[112:115], v[190:193], v[202:205], v[112:115]
	v_mfma_f32_16x16x32_bf16 v[100:103], v[182:185], v[210:213], v[100:103]
	v_mfma_f32_16x16x32_bf16 v[96:99], v[190:193], v[210:213], v[96:99]
	v_mfma_f32_16x16x32_bf16 v[84:87], v[182:185], v[218:221], v[84:87]
	v_mfma_f32_16x16x32_bf16 v[80:83], v[190:193], v[218:221], v[80:83]
	v_mfma_f32_16x16x32_bf16 v[68:71], v[182:185], v[226:229], v[68:71]
	v_mfma_f32_16x16x32_bf16 v[64:67], v[190:193], v[226:229], v[64:67]
	v_mfma_f32_16x16x32_bf16 v[116:119], v[186:189], v[206:209], v[116:119]
	v_mfma_f32_16x16x32_bf16 v[112:115], v[194:197], v[206:209], v[112:115]
	v_mfma_f32_16x16x32_bf16 v[100:103], v[186:189], v[214:217], v[100:103]
	v_mfma_f32_16x16x32_bf16 v[96:99], v[194:197], v[214:217], v[96:99]
	v_mfma_f32_16x16x32_bf16 v[84:87], v[186:189], v[222:225], v[84:87]
	v_mfma_f32_16x16x32_bf16 v[80:83], v[194:197], v[222:225], v[80:83]
	v_mfma_f32_16x16x32_bf16 v[68:71], v[186:189], v[230:233], v[68:71]
	v_mfma_f32_16x16x32_bf16 v[64:67], v[194:197], v[230:233], v[64:67]
	s_setprio 0
	s_barrier
; #define PG8_STAGE(bufoff, gbase, voff) do { _Pragma("unroll") for (int _i = 0; _i < 2; ++_i) \
;         __builtin_amdgcn_global_load_lds((const unsigned*)((const char*)(gbase) + (voff)[_i]), (PG8_LAS unsigned*)(lds + (bufoff) + ldsw + _i * 8192), 16, 0, 0); } while (0)
; #define PG8_LDA(dst, b, h) do { _Pragma("unroll") for (int m = 0; m < 4; ++m) _Pragma("unroll") for (int k = 0; k < 2; ++k) dst[m][k] = *(const PG8_LAS bf16x8*)(lds + PG8_SA(b, h) + aoff + m * 2048 + k * 1024); } while (0)
; #define PG8_MMA(ai, bj, At, Bt) do { __builtin_amdgcn_s_setprio(1); _Pragma("unroll") for (int m = 0; m < 4; ++m) _Pragma("unroll") for (int n = 0; n < 2; ++n) _Pragma("unroll") for (int k = 0; k < 2; ++k) \
;         acc[ai][bj][m][n] = __builtin_amdgcn_mfma_f32_16x16x32_bf16(Bt[n][k], At[m][k], acc[ai][bj][m][n], 0, 0, 0); __builtin_amdgcn_s_setprio(0); } while (0)
; #define PG8_WAIT_V(n) asm volatile("s_waitcnt vmcnt(" #n ")" ::: "memory")
; #define PG8_WAIT_L(n) asm volatile("s_waitcnt lgkmcnt(" #n ")" ::: "memory")
; #define PG8_BAR __builtin_amdgcn_s_barrier()
; #define PG8_SCHED __builtin_amdgcn_sched_barrier(0)
; template <class Epi, class Sched, bool ALIGN_EPI = false, bool SP2 = false>
; __device__ __forceinline__ void gemm_phase(PG8_LAS unsigned char* lds, const Gemm g, const Sched& S, const Epi& E) {
;     ...
;         for (int t = 0; t < nt; t += 2) {
;     ...
;             PG8_LDA(At, 1, 1); PG8_STAGE(PG8_SB(1, 0), b3, voffB); PG8_STAGE(PG8_SB(1, 1), b3 + hstepB, voffB); PG8_STAGE(PG8_SA(1, 0), a3, voffA);
;             PG8_WAIT_V(8); PG8_WAIT_L(0); PG8_BAR; PG8_MMA(1, 0, At, B0); PG8_MMA(1, 1, At, B1); PG8_BAR; PG8_SCHED;
	s_add_i32 s52, s85, s11
	v_lshl_add_u64 v[174:175], v[174:175], 0, s[38:39]
	s_mov_b32 m0, s52
	ds_read_b128 v[202:205], v163 offset:49152
	ds_read_b128 v[206:209], v163 offset:50176
	ds_read_b128 v[210:213], v163 offset:51200
	ds_read_b128 v[214:217], v163 offset:52224
	ds_read_b128 v[218:221], v163 offset:53248
	ds_read_b128 v[222:225], v163 offset:54272
	ds_read_b128 v[226:229], v163 offset:55296
	ds_read_b128 v[230:233], v163 offset:56320
	global_load_lds_dwordx4 v[174:175], off
	s_add_i32 m0, s52, 0x2000
	s_add_u32 s50, s50, 0x40080
	v_lshl_add_u64 v[174:175], v[198:199], 0, s[38:39]
	s_addc_u32 s51, s51, 0
	s_add_i32 s52, s86, s11
	global_load_lds_dwordx4 v[174:175], off
	s_mov_b32 m0, s52
	s_nop 0
	global_load_lds_dwordx4 v130, s[50:51]
	s_add_i32 m0, s52, 0x2000
	s_nop 0
	global_load_lds_dwordx4 v134, s[50:51]
	v_lshl_add_u64 v[174:175], v[234:235], 0, s[38:39]
	s_mov_b32 m0, s56
	s_nop 0
	global_load_lds_dwordx4 v[174:175], off
	v_lshl_add_u64 v[174:175], v[236:237], 0, s[38:39]
	s_mov_b32 m0, s57
	s_nop 0
	global_load_lds_dwordx4 v[174:175], off
	s_waitcnt vmcnt(8)
	s_waitcnt lgkmcnt(0)
	s_barrier
	s_setprio 1
	s_waitcnt lgkmcnt(0)
	v_mfma_f32_16x16x32_bf16 v[60:63], v[146:149], v[202:205], v[60:63]
	v_mfma_f32_16x16x32_bf16 v[56:59], v[170:173], v[202:205], v[56:59]
	v_mfma_f32_16x16x32_bf16 v[44:47], v[146:149], v[210:213], v[44:47]
	v_mfma_f32_16x16x32_bf16 v[40:43], v[170:173], v[210:213], v[40:43]
	v_mfma_f32_16x16x32_bf16 v[28:31], v[146:149], v[218:221], v[28:31]
	v_mfma_f32_16x16x32_bf16 v[24:27], v[170:173], v[218:221], v[24:27]
	v_mfma_f32_16x16x32_bf16 v[12:15], v[146:149], v[226:229], v[12:15]
	v_mfma_f32_16x16x32_bf16 v[8:11], v[170:173], v[226:229], v[8:11]
	v_mfma_f32_16x16x32_bf16 v[60:63], v[166:169], v[206:209], v[60:63]
	v_mfma_f32_16x16x32_bf16 v[56:59], v[178:181], v[206:209], v[56:59]
	v_mfma_f32_16x16x32_bf16 v[44:47], v[166:169], v[214:217], v[44:47]
	v_mfma_f32_16x16x32_bf16 v[40:43], v[178:181], v[214:217], v[40:43]
	v_mfma_f32_16x16x32_bf16 v[28:31], v[166:169], v[222:225], v[28:31]
	v_mfma_f32_16x16x32_bf16 v[24:27], v[178:181], v[222:225], v[24:27]
	v_mfma_f32_16x16x32_bf16 v[12:15], v[166:169], v[230:233], v[12:15]
	v_mfma_f32_16x16x32_bf16 v[8:11], v[178:181], v[230:233], v[8:11]
	s_setprio 0
	s_setprio 1
	v_mfma_f32_16x16x32_bf16 v[52:55], v[182:185], v[202:205], v[52:55]
	v_mfma_f32_16x16x32_bf16 v[48:51], v[190:193], v[202:205], v[48:51]
	v_mfma_f32_16x16x32_bf16 v[36:39], v[182:185], v[210:213], v[36:39]
	v_mfma_f32_16x16x32_bf16 v[32:35], v[190:193], v[210:213], v[32:35]
	v_mfma_f32_16x16x32_bf16 v[20:23], v[182:185], v[218:221], v[20:23]
	v_mfma_f32_16x16x32_bf16 v[16:19], v[190:193], v[218:221], v[16:19]
	v_mfma_f32_16x16x32_bf16 v[4:7], v[182:185], v[226:229], v[4:7]
	v_mfma_f32_16x16x32_bf16 v[0:3], v[190:193], v[226:229], v[0:3]
	v_mfma_f32_16x16x32_bf16 v[52:55], v[186:189], v[206:209], v[52:55]
	v_mfma_f32_16x16x32_bf16 v[48:51], v[194:197], v[206:209], v[48:51]
	v_mfma_f32_16x16x32_bf16 v[36:39], v[186:189], v[214:217], v[36:39]
	v_mfma_f32_16x16x32_bf16 v[32:35], v[194:197], v[214:217], v[32:35]
	v_mfma_f32_16x16x32_bf16 v[20:23], v[186:189], v[222:225], v[20:23]
	v_mfma_f32_16x16x32_bf16 v[16:19], v[194:197], v[222:225], v[16:19]
	v_mfma_f32_16x16x32_bf16 v[4:7], v[186:189], v[230:233], v[4:7]
	v_mfma_f32_16x16x32_bf16 v[0:3], v[194:197], v[230:233], v[0:3]
	s_setprio 0
	s_barrier
	s_add_i32 s84, s84, 2
	s_add_u32 s4, s4, 0x100
	s_addc_u32 s5, s5, 0
	s_add_u32 s82, s82, 0x100
	s_addc_u32 s83, s83, 0
	s_cmp_gt_u32 s84, 13
	s_cbranch_scc0 .LBB0_150
	s_and_b64 vcc, exec, s[40:41]
	s_cbranch_vccz .LBB0_153
	s_barrier

;     __device__ __forceinline__ size_t boff(const Unit& u, size_t tstepB) const { return (size_t)u.pn * tstepB; }
; #define PG8_STAGE(bufoff, gbase, voff) do { _Pragma("unroll") for (int _i = 0; _i < 2; ++_i) \
;         __builtin_amdgcn_global_load_lds((const unsigned*)((const char*)(gbase) + (voff)[_i]), (PG8_LAS unsigned*)(lds + (bufoff) + ldsw + _i * 8192), 16, 0, 0); } while (0)
; #define PG8_WAIT_V(n) asm volatile("s_waitcnt vmcnt(" #n ")" ::: "memory")
; #define PG8_BAR __builtin_amdgcn_s_barrier()
; template <class Epi, class Sched, bool ALIGN_EPI = false, bool SP2 = false>
; __device__ __forceinline__ void gemm_phase(PG8_LAS unsigned char* lds, const Gemm g, const Sched& S, const Epi& E) {
;     const int tid = threadIdx.x, wid = __builtin_amdgcn_readfirstlane(tid >> 6), lane = tid & 63, wr = wid >> 2, wc = wid & 3, fr = lane & 15, fq = lane >> 4;
;     const int K = g.K, nt = K / BK;
;     unsigned voffA[2], voffB[2];
; #pragma unroll
;     for (int i = 0; i < 2; ++i) { int R, C; stage_rc(tid * 16 + i * 8192, R, C); const int Rb = Epi::PERM ? ((R & ~31) + perm32(R & 31)) : R;
;         voffA[i] = (unsigned)(R * g.lda + C) * 2u; voffB[i] = (unsigned)(Rb * g.ldb + C) * 2u; }
;     const size_t kstep = (size_t)(BK * 2);
;     const size_t hstepA = (size_t)HALF * g.lda * 2, hstepB = (size_t)HALF * g.ldb * 2;
;     const size_t tstepA = (size_t)g.arows * g.lda * 2, tstepB = 2 * hstepB;
;     const unsigned ldsw = (unsigned)wid * 1024u;
;     const int aoff = lds_byte(wr * 64 + fr, fq * 8), boff = lds_byte(wc * 32 + fr, fq * 8);
;     ...
;         PG8_STAGE(PG8_SB(0, 0), cB, voffB); PG8_STAGE(PG8_SB(0, 1), cB + hstepB, voffB); PG8_STAGE(PG8_SA(0, 0), cA, voffA); PG8_STAGE(PG8_SA(0, 1), cA + hstepA, voffA);
;         if (wr == 1) PG8_BAR;
;         PG8_WAIT_V(2); PG8_BAR;
;         PG8_STAGE(PG8_SB(1, 0), cB + kstep, voffB); PG8_STAGE(PG8_SA(1, 0), cA + kstep, voffA); PG8_STAGE(PG8_SB(1, 1), cB + hstepB + kstep, voffB);
;         PG8_WAIT_V(6); PG8_BAR;
.LBB0_207:
	s_lshl_b32 s4, s4, 5
	s_and_b32 s34, s4, 0x60
	s_mov_b64 s[4:5], 0x80
	s_add_i32 m0, s41, 0x18000
	v_lshl_add_u64 v[6:7], v[6:7], 0, s[4:5]
	s_lshl_b32 s29, s1, 13
	s_lshl_b32 s35, s34, 7
	s_waitcnt vmcnt(2)
	s_barrier
	global_load_lds_dwordx4 v[6:7], off
	v_lshl_add_u64 v[4:5], v[4:5], 0, s[4:5]
	s_add_i32 m0, s41, 0x1a000
	s_add_i32 s54, s41, 0x8000
	s_add_i32 s55, s41, 0xa000
	global_load_lds_dwordx4 v[4:5], off
	v_lshl_add_u64 v[0:1], v[0:1], 0, s[4:5]
	s_mov_b32 m0, s54
	s_add_u32 s30, s44, 0x40080
	global_load_lds_dwordx4 v[0:1], off
	v_lshl_add_u64 v[0:1], v[2:3], 0, s[4:5]
	s_mov_b32 m0, s55
	s_addc_u32 s31, s45, 0
	global_load_lds_dwordx4 v[0:1], off
	s_add_i32 m0, s41, 0x1c000
	global_load_lds_dwordx4 v130, s[30:31]
	v_lshl_add_u64 v[0:1], s[30:31], 0, v[134:135]
	s_add_i32 m0, s41, 0x1e000
	v_lshlrev_b32_e32 v3, 2, v156
	global_load_lds_dwordx4 v[0:1], off
	v_and_b32_e32 v0, 48, v176
	v_lshlrev_b32_e32 v1, 3, v153
	v_lshl_or_b32 v2, v156, 6, v0
	v_or_b32_e32 v0, v155, v0
	v_and_b32_e32 v3, 32, v3
	v_bitop3_b32 v149, s35, v0, v157 bitop3:0xf6
	v_lshlrev_b32_e32 v0, 2, v153
	v_and_or_b32 v153, v1, 16, s34
	v_lshlrev_b32_e32 v1, 8, v176
	v_bitop3_b32 v2, v2, s29, v3 bitop3:0xde
	v_and_b32_e32 v1, 0x38000, v1
	v_lshlrev_b32_e32 v3, 11, v152
	v_or3_b32 v1, v150, v1, v3
	v_add_u32_e32 v138, v1, v151
	v_lshlrev_b32_e32 v1, 4, v154
	s_waitcnt vmcnt(6)
	s_cmpk_lt_u32 s28, 0x100
	v_and_b32_e32 v1, 0x78000, v1
	s_cselect_b64 s[28:29], -1, 0
	v_and_b32_e32 v0, 4, v0
	v_or3_b32 v1, v150, v1, v3
	s_add_i32 s57, 0, 0x10000
	s_add_i32 s58, 0, 0x14000
	s_sext_i32_i16 s59, s0
	v_lshl_or_b32 v148, s1, 6, v156
	s_ashr_i32 s56, s90, 31
	v_mov_b32_e32 v139, v137
	v_add_u32_e32 v140, v1, v151
	v_mov_b32_e32 v141, v137
	v_mov_b64_e32 v[142:143], 0x100
	v_mov_b64_e32 v[144:145], 0xff
	v_add_u32_e32 v150, s57, v149
	v_add_u32_e32 v151, s58, v149
	v_add_u32_e32 v152, 0, v2
	v_lshlrev_b32_e32 v136, 1, v0
	s_barrier
	s_branch .LBB0_210

; #define PG8_STAGE(bufoff, gbase, voff) do { _Pragma("unroll") for (int _i = 0; _i < 2; ++_i) \
;         __builtin_amdgcn_global_load_lds((const unsigned*)((const char*)(gbase) + (voff)[_i]), (PG8_LAS unsigned*)(lds + (bufoff) + ldsw + _i * 8192), 16, 0, 0); } while (0)
; #define PG8_LDA(dst, b, h) do { _Pragma("unroll") for (int m = 0; m < 4; ++m) _Pragma("unroll") for (int k = 0; k < 2; ++k) dst[m][k] = *(const PG8_LAS bf16x8*)(lds + PG8_SA(b, h) + aoff + m * 2048 + k * 1024); } while (0)
; #define PG8_LDB(dst, b, h) do { _Pragma("unroll") for (int n = 0; n < 2; ++n) _Pragma("unroll") for (int k = 0; k < 2; ++k) dst[n][k] = *(const PG8_LAS bf16x8*)(lds + PG8_SB(b, h) + boff + n * 2048 + k * 1024); } while (0)
; #define PG8_MMA(ai, bj, At, Bt) do { __builtin_amdgcn_s_setprio(1); _Pragma("unroll") for (int m = 0; m < 4; ++m) _Pragma("unroll") for (int n = 0; n < 2; ++n) _Pragma("unroll") for (int k = 0; k < 2; ++k) \
;         acc[ai][bj][m][n] = __builtin_amdgcn_mfma_f32_16x16x32_bf16(Bt[n][k], At[m][k], acc[ai][bj][m][n], 0, 0, 0); __builtin_amdgcn_s_setprio(0); } while (0)
; #define PG8_WAIT_V(n) asm volatile("s_waitcnt vmcnt(" #n ")" ::: "memory")
; #define PG8_WAIT_L(n) asm volatile("s_waitcnt lgkmcnt(" #n ")" ::: "memory")
; #define PG8_BAR __builtin_amdgcn_s_barrier()
; #define PG8_SCHED __builtin_amdgcn_sched_barrier(0)
; template <class Epi, class Sched, bool ALIGN_EPI = false, bool SP2 = false>
; __device__ __forceinline__ void gemm_phase(PG8_LAS unsigned char* lds, const Gemm g, const Sched& S, const Epi& E) {
;     ...
;             PG8_LDB(B0, 0, 0); PG8_LDB(B1, 0, 1); PG8_SCHED; PG8_LDA(At, 0, 0); PG8_STAGE(PG8_SA(1, 1), a1 + hstepA, voffA);
;             PG8_WAIT_V(8); PG8_WAIT_L(0); PG8_BAR; PG8_MMA(0, 0, At, B0); PG8_MMA(0, 1, At, B1); PG8_BAR; PG8_SCHED;
;             PG8_LDA(At, 0, 1); PG8_STAGE(PG8_SB(0, 0), b2, voffB); PG8_STAGE(PG8_SB(0, 1), b2 + hstepB, voffB); PG8_STAGE(PG8_SA(0, 0), a2, voffA);
;             PG8_WAIT_V(8); PG8_WAIT_L(0); PG8_BAR; PG8_MMA(1, 0, At, B0); PG8_MMA(1, 1, At, B1); PG8_BAR; PG8_SCHED;
.LBB0_217:
	ds_read_b128 v[154:157], v150
	ds_read_b128 v[158:161], v150 offset:1024
	ds_read_b128 v[162:165], v150 offset:2048
	ds_read_b128 v[166:169], v150 offset:3072
	ds_read_b128 v[170:173], v151
	ds_read_b128 v[178:181], v151 offset:1024
	ds_read_b128 v[182:185], v151 offset:2048
	ds_read_b128 v[186:189], v151 offset:3072
	s_add_u32 s44, s42, 0xfffc0080
	s_addc_u32 s45, s43, -1
	s_cmp_eq_u32 s74, 12
	s_cselect_b32 s47, s35, s45
	s_cselect_b32 s46, s70, s44
	s_cselect_b32 s45, s31, s73
	s_cselect_b32 s44, s71, s72
	s_add_i32 m0, s41, 0xc000
	ds_read_b128 v[190:193], v152
	ds_read_b128 v[194:197], v152 offset:1024
	ds_read_b128 v[202:205], v152 offset:2048
	ds_read_b128 v[206:209], v152 offset:3072
	ds_read_b128 v[210:213], v152 offset:4096
	ds_read_b128 v[214:217], v152 offset:5120
	ds_read_b128 v[218:221], v152 offset:6144
	ds_read_b128 v[222:225], v152 offset:7168
	global_load_lds_dwordx4 v138, s[42:43]
	s_add_i32 m0, s41, 0xe000
	s_nop 0
	global_load_lds_dwordx4 v140, s[42:43]
	s_waitcnt vmcnt(8)
	s_waitcnt lgkmcnt(0)
	s_barrier
	s_setprio 1
	s_waitcnt lgkmcnt(0)
	v_mfma_f32_16x16x32_bf16 v[124:127], v[154:157], v[190:193], v[124:127]
	v_mfma_f32_16x16x32_bf16 v[120:123], v[162:165], v[190:193], v[120:123]
	v_mfma_f32_16x16x32_bf16 v[112:115], v[154:157], v[202:205], v[112:115]
	v_mfma_f32_16x16x32_bf16 v[104:107], v[162:165], v[202:205], v[104:107]
	v_mfma_f32_16x16x32_bf16 v[96:99], v[154:157], v[210:213], v[96:99]
	v_mfma_f32_16x16x32_bf16 v[88:91], v[162:165], v[210:213], v[88:91]
	v_mfma_f32_16x16x32_bf16 v[80:83], v[154:157], v[218:221], v[80:83]
	v_mfma_f32_16x16x32_bf16 v[72:75], v[162:165], v[218:221], v[72:75]
	v_mfma_f32_16x16x32_bf16 v[124:127], v[158:161], v[194:197], v[124:127]
	v_mfma_f32_16x16x32_bf16 v[120:123], v[166:169], v[194:197], v[120:123]
	v_mfma_f32_16x16x32_bf16 v[112:115], v[158:161], v[206:209], v[112:115]
	v_mfma_f32_16x16x32_bf16 v[104:107], v[166:169], v[206:209], v[104:107]
	v_mfma_f32_16x16x32_bf16 v[96:99], v[158:161], v[214:217], v[96:99]
	v_mfma_f32_16x16x32_bf16 v[88:91], v[166:169], v[214:217], v[88:91]
	v_mfma_f32_16x16x32_bf16 v[80:83], v[158:161], v[222:225], v[80:83]
	v_mfma_f32_16x16x32_bf16 v[72:75], v[166:169], v[222:225], v[72:75]
	s_setprio 0
	s_setprio 1
	v_mfma_f32_16x16x32_bf16 v[116:119], v[170:173], v[190:193], v[116:119]
	v_mfma_f32_16x16x32_bf16 v[108:111], v[182:185], v[190:193], v[108:111]
	v_mfma_f32_16x16x32_bf16 v[100:103], v[170:173], v[202:205], v[100:103]
	v_mfma_f32_16x16x32_bf16 v[92:95], v[182:185], v[202:205], v[92:95]
	v_mfma_f32_16x16x32_bf16 v[84:87], v[170:173], v[210:213], v[84:87]
	v_mfma_f32_16x16x32_bf16 v[76:79], v[182:185], v[210:213], v[76:79]
	v_mfma_f32_16x16x32_bf16 v[68:71], v[170:173], v[218:221], v[68:71]
	v_mfma_f32_16x16x32_bf16 v[64:67], v[182:185], v[218:221], v[64:67]
	v_mfma_f32_16x16x32_bf16 v[116:119], v[178:181], v[194:197], v[116:119]
	v_mfma_f32_16x16x32_bf16 v[108:111], v[186:189], v[194:197], v[108:111]
	v_mfma_f32_16x16x32_bf16 v[100:103], v[178:181], v[206:209], v[100:103]
	v_mfma_f32_16x16x32_bf16 v[92:95], v[186:189], v[206:209], v[92:95]
	v_mfma_f32_16x16x32_bf16 v[84:87], v[178:181], v[214:217], v[84:87]
	v_mfma_f32_16x16x32_bf16 v[76:79], v[186:189], v[214:217], v[76:79]
	v_mfma_f32_16x16x32_bf16 v[68:71], v[178:181], v[222:225], v[68:71]
	v_mfma_f32_16x16x32_bf16 v[64:67], v[186:189], v[222:225], v[64:67]
	s_setprio 0
	s_barrier
	s_add_i32 s75, s57, s49
	v_lshl_add_u64 v[146:147], s[44:45], 0, v[130:131]
	s_mov_b32 m0, s75
	ds_read_b128 v[190:193], v152 offset:16384
	ds_read_b128 v[194:197], v152 offset:17408
	ds_read_b128 v[202:205], v152 offset:18432
	ds_read_b128 v[206:209], v152 offset:19456
	ds_read_b128 v[210:213], v152 offset:20480
	ds_read_b128 v[214:217], v152 offset:21504
	ds_read_b128 v[218:221], v152 offset:22528
	ds_read_b128 v[222:225], v152 offset:23552
	global_load_lds_dwordx4 v[146:147], off
	s_add_i32 m0, s75, 0x2000
	s_add_u32 s76, s44, 0x40000
	v_lshl_add_u64 v[174:175], s[44:45], 0, v[134:135]
	s_addc_u32 s77, s45, 0
	s_add_i32 s75, s58, s49
	global_load_lds_dwordx4 v[174:175], off
	s_mov_b32 m0, s75
	v_lshl_add_u64 v[226:227], s[46:47], 0, v[132:133]
	global_load_lds_dwordx4 v130, s[76:77]
	s_add_i32 m0, s75, 0x2000
	s_nop 0
	global_load_lds_dwordx4 v134, s[76:77]
	v_lshl_add_u64 v[198:199], s[46:47], 0, v[128:129]
	s_mov_b32 m0, s41
	s_nop 0
	global_load_lds_dwordx4 v[198:199], off
	s_mov_b32 m0, s50
	s_nop 0
	global_load_lds_dwordx4 v[226:227], off
	s_waitcnt vmcnt(8)
	s_waitcnt lgkmcnt(0)
	s_barrier
; #define PG8_STAGE(bufoff, gbase, voff) do { _Pragma("unroll") for (int _i = 0; _i < 2; ++_i) \
;         __builtin_amdgcn_global_load_lds((const unsigned*)((const char*)(gbase) + (voff)[_i]), (PG8_LAS unsigned*)(lds + (bufoff) + ldsw + _i * 8192), 16, 0, 0); } while (0)
; #define PG8_LDA(dst, b, h) do { _Pragma("unroll") for (int m = 0; m < 4; ++m) _Pragma("unroll") for (int k = 0; k < 2; ++k) dst[m][k] = *(const PG8_LAS bf16x8*)(lds + PG8_SA(b, h) + aoff + m * 2048 + k * 1024); } while (0)
; #define PG8_LDB(dst, b, h) do { _Pragma("unroll") for (int n = 0; n < 2; ++n) _Pragma("unroll") for (int k = 0; k < 2; ++k) dst[n][k] = *(const PG8_LAS bf16x8*)(lds + PG8_SB(b, h) + boff + n * 2048 + k * 1024); } while (0)
; #define PG8_MMA(ai, bj, At, Bt) do { __builtin_amdgcn_s_setprio(1); _Pragma("unroll") for (int m = 0; m < 4; ++m) _Pragma("unroll") for (int n = 0; n < 2; ++n) _Pragma("unroll") for (int k = 0; k < 2; ++k) \
;         acc[ai][bj][m][n] = __builtin_amdgcn_mfma_f32_16x16x32_bf16(Bt[n][k], At[m][k], acc[ai][bj][m][n], 0, 0, 0); __builtin_amdgcn_s_setprio(0); } while (0)
; #define PG8_WAIT_V(n) asm volatile("s_waitcnt vmcnt(" #n ")" ::: "memory")
; #define PG8_WAIT_L(n) asm volatile("s_waitcnt lgkmcnt(" #n ")" ::: "memory")
; #define PG8_BAR __builtin_amdgcn_s_barrier()
; #define PG8_SCHED __builtin_amdgcn_sched_barrier(0)
; template <class Epi, class Sched, bool ALIGN_EPI = false, bool SP2 = false>
; __device__ __forceinline__ void gemm_phase(PG8_LAS unsigned char* lds, const Gemm g, const Sched& S, const Epi& E) {
;     ...
;             PG8_WAIT_V(8); PG8_WAIT_L(0); PG8_BAR; PG8_MMA(1, 0, At, B0); PG8_MMA(1, 1, At, B1); PG8_BAR; PG8_SCHED;
;             PG8_LDB(B0, 1, 0); PG8_LDB(B1, 1, 1); PG8_SCHED; PG8_LDA(At, 1, 0); PG8_STAGE(PG8_SA(0, 1), a2 + hstepA, voffA);
;             PG8_WAIT_V(8); PG8_WAIT_L(0); PG8_BAR; PG8_MMA(0, 0, At, B0); PG8_MMA(0, 1, At, B1); PG8_BAR; PG8_SCHED;
	s_setprio 1
	s_waitcnt lgkmcnt(0)
	v_mfma_f32_16x16x32_bf16 v[60:63], v[154:157], v[190:193], v[60:63]
	v_mfma_f32_16x16x32_bf16 v[56:59], v[162:165], v[190:193], v[56:59]
	v_mfma_f32_16x16x32_bf16 v[52:55], v[154:157], v[202:205], v[52:55]
	v_mfma_f32_16x16x32_bf16 v[44:47], v[162:165], v[202:205], v[44:47]
	v_mfma_f32_16x16x32_bf16 v[36:39], v[154:157], v[210:213], v[36:39]
	v_mfma_f32_16x16x32_bf16 v[28:31], v[162:165], v[210:213], v[28:31]
	v_mfma_f32_16x16x32_bf16 v[20:23], v[154:157], v[218:221], v[20:23]
	v_mfma_f32_16x16x32_bf16 v[12:15], v[162:165], v[218:221], v[12:15]
	v_mfma_f32_16x16x32_bf16 v[60:63], v[158:161], v[194:197], v[60:63]
	v_mfma_f32_16x16x32_bf16 v[56:59], v[166:169], v[194:197], v[56:59]
	v_mfma_f32_16x16x32_bf16 v[52:55], v[158:161], v[206:209], v[52:55]
	v_mfma_f32_16x16x32_bf16 v[44:47], v[166:169], v[206:209], v[44:47]
	v_mfma_f32_16x16x32_bf16 v[36:39], v[158:161], v[214:217], v[36:39]
	v_mfma_f32_16x16x32_bf16 v[28:31], v[166:169], v[214:217], v[28:31]
	v_mfma_f32_16x16x32_bf16 v[20:23], v[158:161], v[222:225], v[20:23]
	v_mfma_f32_16x16x32_bf16 v[12:15], v[166:169], v[222:225], v[12:15]
	s_setprio 0
	s_setprio 1
	v_mfma_f32_16x16x32_bf16 v[48:51], v[170:173], v[190:193], v[48:51]
	v_mfma_f32_16x16x32_bf16 v[40:43], v[182:185], v[190:193], v[40:43]
	v_mfma_f32_16x16x32_bf16 v[32:35], v[170:173], v[202:205], v[32:35]
	v_mfma_f32_16x16x32_bf16 v[24:27], v[182:185], v[202:205], v[24:27]
	v_mfma_f32_16x16x32_bf16 v[16:19], v[170:173], v[210:213], v[16:19]
	v_mfma_f32_16x16x32_bf16 v[8:11], v[182:185], v[210:213], v[8:11]
	v_mfma_f32_16x16x32_bf16 v[4:7], v[170:173], v[218:221], v[4:7]
	v_mfma_f32_16x16x32_bf16 v[0:3], v[182:185], v[218:221], v[0:3]
	v_mfma_f32_16x16x32_bf16 v[48:51], v[178:181], v[194:197], v[48:51]
	v_mfma_f32_16x16x32_bf16 v[40:43], v[186:189], v[194:197], v[40:43]
	v_mfma_f32_16x16x32_bf16 v[32:35], v[178:181], v[206:209], v[32:35]
	v_mfma_f32_16x16x32_bf16 v[24:27], v[186:189], v[206:209], v[24:27]
	v_mfma_f32_16x16x32_bf16 v[16:19], v[178:181], v[214:217], v[16:19]
	v_mfma_f32_16x16x32_bf16 v[8:11], v[186:189], v[214:217], v[8:11]
	v_mfma_f32_16x16x32_bf16 v[4:7], v[178:181], v[222:225], v[4:7]
	v_mfma_f32_16x16x32_bf16 v[0:3], v[186:189], v[222:225], v[0:3]
	s_setprio 0
	s_barrier
	s_add_i32 s75, 0, 0x18000
	s_add_i32 s76, 0, 0x1c000
	v_add_u32_e32 v166, s75, v149
	v_add_u32_e32 v177, s76, v149
	ds_read_b128 v[154:157], v166
	ds_read_b128 v[158:161], v166 offset:1024
	ds_read_b128 v[162:165], v166 offset:2048
	ds_read_b128 v[166:169], v166 offset:3072
	ds_read_b128 v[170:173], v177
	ds_read_b128 v[178:181], v177 offset:1024
	ds_read_b128 v[182:185], v177 offset:2048
	ds_read_b128 v[186:189], v177 offset:3072
	s_add_u32 s46, s46, 0x40000
	s_addc_u32 s47, s47, 0
	s_mov_b32 m0, s51
	ds_read_b128 v[190:193], v152 offset:32768
	ds_read_b128 v[194:197], v152 offset:33792
	ds_read_b128 v[202:205], v152 offset:34816
	ds_read_b128 v[206:209], v152 offset:35840
	ds_read_b128 v[210:213], v152 offset:36864
	ds_read_b128 v[214:217], v152 offset:37888
	ds_read_b128 v[218:221], v152 offset:38912
	ds_read_b128 v[222:225], v152 offset:39936
	global_load_lds_dwordx4 v128, s[46:47]
	v_lshl_add_u64 v[228:229], s[46:47], 0, v[132:133]
	s_mov_b32 m0, s52
	s_nop 0
	global_load_lds_dwordx4 v[228:229], off
	s_waitcnt vmcnt(8)
	s_waitcnt lgkmcnt(0)
	s_barrier
	s_setprio 1
	s_waitcnt lgkmcnt(0)
	v_mfma_f32_16x16x32_bf16 v[124:127], v[154:157], v[190:193], v[124:127]
	v_mfma_f32_16x16x32_bf16 v[120:123], v[162:165], v[190:193], v[120:123]
	v_mfma_f32_16x16x32_bf16 v[112:115], v[154:157], v[202:205], v[112:115]
	v_mfma_f32_16x16x32_bf16 v[104:107], v[162:165], v[202:205], v[104:107]
	v_mfma_f32_16x16x32_bf16 v[96:99], v[154:157], v[210:213], v[96:99]
	v_mfma_f32_16x16x32_bf16 v[88:91], v[162:165], v[210:213], v[88:91]
	v_mfma_f32_16x16x32_bf16 v[80:83], v[154:157], v[218:221], v[80:83]
	v_mfma_f32_16x16x32_bf16 v[72:75], v[162:165], v[218:221], v[72:75]
	v_mfma_f32_16x16x32_bf16 v[124:127], v[158:161], v[194:197], v[124:127]
	v_mfma_f32_16x16x32_bf16 v[120:123], v[166:169], v[194:197], v[120:123]
	v_mfma_f32_16x16x32_bf16 v[112:115], v[158:161], v[206:209], v[112:115]
	v_mfma_f32_16x16x32_bf16 v[104:107], v[166:169], v[206:209], v[104:107]
	v_mfma_f32_16x16x32_bf16 v[96:99], v[158:161], v[214:217], v[96:99]
	v_mfma_f32_16x16x32_bf16 v[88:91], v[166:169], v[214:217], v[88:91]
	v_mfma_f32_16x16x32_bf16 v[80:83], v[158:161], v[222:225], v[80:83]
	v_mfma_f32_16x16x32_bf16 v[72:75], v[166:169], v[222:225], v[72:75]
	s_setprio 0
	s_setprio 1
	v_mfma_f32_16x16x32_bf16 v[116:119], v[170:173], v[190:193], v[116:119]
	v_mfma_f32_16x16x32_bf16 v[108:111], v[182:185], v[190:193], v[108:111]
	v_mfma_f32_16x16x32_bf16 v[100:103], v[170:173], v[202:205], v[100:103]
	v_mfma_f32_16x16x32_bf16 v[92:95], v[182:185], v[202:205], v[92:95]
	v_mfma_f32_16x16x32_bf16 v[84:87], v[170:173], v[210:213], v[84:87]
	v_mfma_f32_16x16x32_bf16 v[76:79], v[182:185], v[210:213], v[76:79]
	v_mfma_f32_16x16x32_bf16 v[68:71], v[170:173], v[218:221], v[68:71]
	v_mfma_f32_16x16x32_bf16 v[64:67], v[182:185], v[218:221], v[64:67]
	v_mfma_f32_16x16x32_bf16 v[116:119], v[178:181], v[194:197], v[116:119]
	v_mfma_f32_16x16x32_bf16 v[108:111], v[186:189], v[194:197], v[108:111]
	v_mfma_f32_16x16x32_bf16 v[100:103], v[178:181], v[206:209], v[100:103]
	v_mfma_f32_16x16x32_bf16 v[92:95], v[186:189], v[206:209], v[92:95]
	v_mfma_f32_16x16x32_bf16 v[84:87], v[178:181], v[214:217], v[84:87]
	v_mfma_f32_16x16x32_bf16 v[76:79], v[186:189], v[214:217], v[76:79]
	v_mfma_f32_16x16x32_bf16 v[68:71], v[178:181], v[222:225], v[68:71]
	v_mfma_f32_16x16x32_bf16 v[64:67], v[186:189], v[222:225], v[64:67]
	s_setprio 0
	s_barrier
; #define PG8_STAGE(bufoff, gbase, voff) do { _Pragma("unroll") for (int _i = 0; _i < 2; ++_i) \
;         __builtin_amdgcn_global_load_lds((const unsigned*)((const char*)(gbase) + (voff)[_i]), (PG8_LAS unsigned*)(lds + (bufoff) + ldsw + _i * 8192), 16, 0, 0); } while (0)
; #define PG8_LDA(dst, b, h) do { _Pragma("unroll") for (int m = 0; m < 4; ++m) _Pragma("unroll") for (int k = 0; k < 2; ++k) dst[m][k] = *(const PG8_LAS bf16x8*)(lds + PG8_SA(b, h) + aoff + m * 2048 + k * 1024); } while (0)
; #define PG8_MMA(ai, bj, At, Bt) do { __builtin_amdgcn_s_setprio(1); _Pragma("unroll") for (int m = 0; m < 4; ++m) _Pragma("unroll") for (int n = 0; n < 2; ++n) _Pragma("unroll") for (int k = 0; k < 2; ++k) \
;         acc[ai][bj][m][n] = __builtin_amdgcn_mfma_f32_16x16x32_bf16(Bt[n][k], At[m][k], acc[ai][bj][m][n], 0, 0, 0); __builtin_amdgcn_s_setprio(0); } while (0)
; #define PG8_WAIT_V(n) asm volatile("s_waitcnt vmcnt(" #n ")" ::: "memory")
; #define PG8_WAIT_L(n) asm volatile("s_waitcnt lgkmcnt(" #n ")" ::: "memory")
; #define PG8_BAR __builtin_amdgcn_s_barrier()
; #define PG8_SCHED __builtin_amdgcn_sched_barrier(0)
; template <class Epi, class Sched, bool ALIGN_EPI = false, bool SP2 = false>
; __device__ __forceinline__ void gemm_phase(PG8_LAS unsigned char* lds, const Gemm g, const Sched& S, const Epi& E) {
;     ...
;         for (int t = 0; t < nt; t += 2) {
;     ...
;             PG8_LDA(At, 1, 1); PG8_STAGE(PG8_SB(1, 0), b3, voffB); PG8_STAGE(PG8_SB(1, 1), b3 + hstepB, voffB); PG8_STAGE(PG8_SA(1, 0), a3, voffA);
;             PG8_WAIT_V(8); PG8_WAIT_L(0); PG8_BAR; PG8_MMA(1, 0, At, B0); PG8_MMA(1, 1, At, B1); PG8_BAR; PG8_SCHED;
	s_add_i32 s46, s75, s49
	v_lshl_add_u64 v[146:147], v[146:147], 0, s[4:5]
	s_mov_b32 m0, s46
	ds_read_b128 v[190:193], v152 offset:49152
	ds_read_b128 v[194:197], v152 offset:50176
	ds_read_b128 v[202:205], v152 offset:51200
	ds_read_b128 v[206:209], v152 offset:52224
	ds_read_b128 v[210:213], v152 offset:53248
	ds_read_b128 v[214:217], v152 offset:54272
	ds_read_b128 v[218:221], v152 offset:55296
	ds_read_b128 v[222:225], v152 offset:56320
	global_load_lds_dwordx4 v[146:147], off
	s_add_i32 m0, s46, 0x2000
	s_add_u32 s44, s44, 0x40080
	v_lshl_add_u64 v[146:147], v[174:175], 0, s[4:5]
	s_addc_u32 s45, s45, 0
	s_add_i32 s46, s76, s49
	global_load_lds_dwordx4 v[146:147], off
	s_mov_b32 m0, s46
	s_nop 0
	global_load_lds_dwordx4 v130, s[44:45]
	s_add_i32 m0, s46, 0x2000
	s_nop 0
	global_load_lds_dwordx4 v134, s[44:45]
	v_lshl_add_u64 v[146:147], v[198:199], 0, s[4:5]
	s_mov_b32 m0, s54
	s_nop 0
	global_load_lds_dwordx4 v[146:147], off
	v_lshl_add_u64 v[146:147], v[226:227], 0, s[4:5]
	s_mov_b32 m0, s55
	s_nop 0
	global_load_lds_dwordx4 v[146:147], off
	s_waitcnt vmcnt(8)
	s_waitcnt lgkmcnt(0)
	s_barrier
	s_setprio 1
	s_waitcnt lgkmcnt(0)
	v_mfma_f32_16x16x32_bf16 v[60:63], v[154:157], v[190:193], v[60:63]
	v_mfma_f32_16x16x32_bf16 v[56:59], v[162:165], v[190:193], v[56:59]
	v_mfma_f32_16x16x32_bf16 v[52:55], v[154:157], v[202:205], v[52:55]
	v_mfma_f32_16x16x32_bf16 v[44:47], v[162:165], v[202:205], v[44:47]
	v_mfma_f32_16x16x32_bf16 v[36:39], v[154:157], v[210:213], v[36:39]
	v_mfma_f32_16x16x32_bf16 v[28:31], v[162:165], v[210:213], v[28:31]
	v_mfma_f32_16x16x32_bf16 v[20:23], v[154:157], v[218:221], v[20:23]
	v_mfma_f32_16x16x32_bf16 v[12:15], v[162:165], v[218:221], v[12:15]
	v_mfma_f32_16x16x32_bf16 v[60:63], v[158:161], v[194:197], v[60:63]
	v_mfma_f32_16x16x32_bf16 v[56:59], v[166:169], v[194:197], v[56:59]
	v_mfma_f32_16x16x32_bf16 v[52:55], v[158:161], v[206:209], v[52:55]
	v_mfma_f32_16x16x32_bf16 v[44:47], v[166:169], v[206:209], v[44:47]
	v_mfma_f32_16x16x32_bf16 v[36:39], v[158:161], v[214:217], v[36:39]
	v_mfma_f32_16x16x32_bf16 v[28:31], v[166:169], v[214:217], v[28:31]
	v_mfma_f32_16x16x32_bf16 v[20:23], v[158:161], v[222:225], v[20:23]
	v_mfma_f32_16x16x32_bf16 v[12:15], v[166:169], v[222:225], v[12:15]
	s_setprio 0
	s_setprio 1
	v_mfma_f32_16x16x32_bf16 v[48:51], v[170:173], v[190:193], v[48:51]
	v_mfma_f32_16x16x32_bf16 v[40:43], v[182:185], v[190:193], v[40:43]
	v_mfma_f32_16x16x32_bf16 v[32:35], v[170:173], v[202:205], v[32:35]
	v_mfma_f32_16x16x32_bf16 v[24:27], v[182:185], v[202:205], v[24:27]
	v_mfma_f32_16x16x32_bf16 v[16:19], v[170:173], v[210:213], v[16:19]
	v_mfma_f32_16x16x32_bf16 v[8:11], v[182:185], v[210:213], v[8:11]
	v_mfma_f32_16x16x32_bf16 v[4:7], v[170:173], v[218:221], v[4:7]
	v_mfma_f32_16x16x32_bf16 v[0:3], v[182:185], v[218:221], v[0:3]
	v_mfma_f32_16x16x32_bf16 v[48:51], v[178:181], v[194:197], v[48:51]
	v_mfma_f32_16x16x32_bf16 v[40:43], v[186:189], v[194:197], v[40:43]
	v_mfma_f32_16x16x32_bf16 v[32:35], v[178:181], v[206:209], v[32:35]
	v_mfma_f32_16x16x32_bf16 v[24:27], v[186:189], v[206:209], v[24:27]
	v_mfma_f32_16x16x32_bf16 v[16:19], v[178:181], v[214:217], v[16:19]
	v_mfma_f32_16x16x32_bf16 v[8:11], v[186:189], v[214:217], v[8:11]
	v_mfma_f32_16x16x32_bf16 v[4:7], v[178:181], v[222:225], v[4:7]
	v_mfma_f32_16x16x32_bf16 v[0:3], v[186:189], v[222:225], v[0:3]
	s_setprio 0
	s_barrier
	s_add_i32 s74, s74, 2
	s_add_u32 s42, s42, 0x100
	s_addc_u32 s43, s43, 0
	s_add_u32 s72, s72, 0x100
	s_addc_u32 s73, s73, 0
	s_cmp_gt_u32 s74, 13
	s_cbranch_scc0 .LBB0_217
	s_and_b64 vcc, exec, s[28:29]
	s_cbranch_vccz .LBB0_220
	s_barrier

; __device__ __forceinline__ void unit(LAS unsigned char* lds, bf16_t* P1, const bf16_t* vaT, int b, int h, int qblk, float lam, const float* subln_w, const float* khalf) {
;     const int tid = threadIdx.x, lane = tid & 63, wid = __builtin_amdgcn_readfirstlane(tid >> 6), r32 = lane & 31, hi = lane >> 5;
;     const int mi = wid >> 2, qs = wid & 3;
;     const int qrow = qblk * 128 + qs * 32 + r32;
;     const size_t rowbase = (size_t)b * SEQ;
;     bf16x8 qf[4];
;     { const bf16_t* qp = P1 + (rowbase + qrow) * LDP + C_QA + (2 * h + mi) * 64 + hi * 8;
; #pragma unroll
;       for (int ks = 0; ks < 4; ++ks) qf[ks] = *(const bf16x8*)(qp + ks * 16); }
;     const float sl2 = ex2(-(float)(h + 1)) * LOG2E;
;     const float sl2h = sl2 * (float)(4 * hi);
;     float qbound;
;     { float q2 = 0.f;
; #pragma unroll
;       for (int ks = 0; ks < 4; ++ks)
; #pragma unroll
;           for (int e = 0; e < 8; ++e) { const float v = __uint_as_float((unsigned)(unsigned short)qf[ks][e] << 16); q2 += v * v; }
;       q2 += __shfl_xor(q2, 32);
;       const float* kh = khalf + (b * 16 + 2 * h + mi) * 2;
;       qbound = sqrtf(q2 * (kh[0] + kh[1])) * 1.01f + 0.05f; }
;     volatile LAS int* dflag = (volatile LAS int*)(lds + 4 * STG);
;     f32x16 O[4];
; #pragma unroll
;     for (int d = 0; d < 4; ++d)
; #pragma unroll
;         for (int r = 0; r < 16; ++r) O[d][r] = 0.f;
;     float m = -INFINITY, l = 0.f;
;     const int NT = 2 * qblk + 2;
;     const char* kbase = (const char*)(P1 + rowbase * LDP + C_KA + h * 128);
;     const char* vbase = (const char*)(vaT + (size_t)(h * 128) * MTOK + rowbase);
;     unsigned kso0, kso1, vso0, vso1;
;     { const int rk0 = (2 * wid) * 4 + (lane >> 4), rk1 = rk0 + 4, sl = lane & 15;
;       kso0 = (unsigned)((rk0 * LDP + ((sl ^ (rk0 & 15)) * 8)) * 2); kso1 = (unsigned)((rk1 * LDP + ((sl ^ (rk1 & 15)) * 8)) * 2);
;       const int d0 = (2 * wid) * 8 + (lane >> 3), d1 = d0 + 8, sv = lane & 7;
;       vso0 = (unsigned)((d0 * MTOK + ((sv ^ ((d0 >> 1) & 7)) * 8)) * 2); vso1 = (unsigned)((d1 * MTOK + ((sv ^ ((d1 >> 1) & 7)) * 8)) * 2); }
;     ...
;     unsigned koff[4], voff[4];
; #pragma unroll
;     for (int ks = 0; ks < 4; ++ks) koff[ks] = (unsigned)(r32 * 256 + (((mi * 8 + 2 * ks + hi) ^ (r32 & 15)) * 16));
; #pragma unroll
;     for (int q = 0; q < 4; ++q) voff[q] = (unsigned)(VOFF + r32 * 128 + (((2 * q + hi) ^ ((r32 >> 1) & 7)) * 16));
.LBB0_395:
	v_readfirstlane_b32 s61, v176
	s_and_b32 s2, s5, 31
	s_lshr_b32 s10, s61, 1
	s_xor_b32 s3, s2, 31
	s_and_b32 s76, s10, 0x60
	s_lshl_b32 s59, s3, 7
	v_or_b32_e32 v123, s76, v114
	v_or_b32_e32 v125, s59, v123
	s_lshl_b32 s60, s72, 12
	v_or_b32_e32 v0, s60, v125
	s_lshr_b32 s70, s61, 8
	v_mul_u32_u24_e32 v0, 0x1a00, v0
	s_lshl_b32 s10, s4, 1
	v_lshlrev_b32_e32 v0, 1, v0
	s_add_i32 s42, s70, s10
	v_lshl_add_u64 v[2:3], s[78:79], 0, v[0:1]
	s_lshl_b32 s10, s42, 7
	v_lshl_add_u64 v[2:3], v[2:3], 0, s[10:11]
	v_lshlrev_b32_e32 v0, 1, v116
	v_lshl_add_u64 v[2:3], v[2:3], 0, v[0:1]
	global_load_dwordx4 v[98:101], v[2:3], off
	global_load_dwordx4 v[102:105], v[2:3], off offset:32
	global_load_dwordx4 v[106:109], v[2:3], off offset:64
	global_load_dwordx4 v[110:113], v[2:3], off offset:96
	s_lshl_b32 s10, s72, 4
	s_add_i32 s42, s42, s10
	s_lshl_b32 s10, s42, 1
	s_lshr_b32 s77, s61, 6
	s_lshl_b64 s[42:43], s[10:11], 2
	s_add_u32 s42, s68, s42
	s_addc_u32 s43, s69, s43
	s_lshl_b32 s71, s3, 1
	s_mul_i32 s80, s72, 0x3400000
	s_add_u32 s73, s78, s80
	s_addc_u32 s74, s79, 0
	s_lshl_b32 s10, s4, 7
	s_lshl_b64 s[44:45], s[10:11], 15
	global_load_dwordx2 v[2:3], v1, s[42:43] offset:2304
	s_add_u32 s75, s6, s44
	v_lshl_or_b32 v0, s77, 3, v147
	s_movk_i32 s42, 0x3400
	s_addc_u32 s82, s7, s45
	v_mul_lo_u32 v6, v0, s42
	s_lshl_b64 s[42:43], s[10:11], 1
	v_or_b32_e32 v4, 4, v0
	v_bitop3_b32 v5, v0, v148, 11 bitop3:0x6c
	v_bitop3_b32 v0, v0, v176, 4 bitop3:0x36
	s_add_u32 s73, s73, s42
	v_lshlrev_b32_e32 v0, 3, v0
	s_addc_u32 s74, s74, s43
	s_lshl_b32 s81, s72, 13
	v_and_b32_e32 v10, 0x78, v0
	v_lshl_or_b32 v0, s77, 4, v149
	s_add_u32 s75, s75, s81
	v_mul_lo_u32 v4, v4, s47
	v_or_b32_e32 v9, 8, v0
	s_addc_u32 s82, s82, 0
	s_lshl_b32 s10, s77, 11
	v_or_b32_e32 v7, v10, v4
	v_lshl_or_b32 v4, v0, 15, v150
	v_lshrrev_b32_e32 v0, 1, v9
	s_add_i32 s72, s10, 0
	s_or_b32 s10, s59, 64
	v_xor_b32_e32 v0, v0, v176
	s_mul_i32 s83, s10, 0x3400
	v_lshlrev_b32_e32 v0, 4, v0
	v_lshlrev_b32_e32 v11, 4, v5
	s_add_u32 s84, s73, s83
	v_and_b32_e32 v12, 0x70, v0
	v_or_b32_e32 v0, v11, v6
	s_addc_u32 s85, s74, 0
	v_lshl_add_u64 v[14:15], s[84:85], 0, v[0:1]
	v_lshlrev_b32_e32 v8, 1, v7
	v_lshl_or_b32 v6, v9, 15, v12
	s_lshl_b32 s10, s10, 1
	v_lshl_add_u64 v[14:15], v[14:15], 0, s[18:19]
	s_mov_b32 m0, s72
	v_mov_b32_e32 v9, v1
	s_add_u32 s86, s75, s10
	global_load_lds_dwordx4 v[14:15], off
	v_lshl_add_u64 v[14:15], s[84:85], 0, v[8:9]
	s_addc_u32 s87, s82, 0
	v_lshl_add_u64 v[14:15], v[14:15], 0, s[18:19]
	s_add_i32 m0, s72, 0x400
	s_mul_i32 s10, s3, 0x1a0000
	global_load_lds_dwordx4 v[14:15], off
	s_add_i32 m0, s72, 0x4000
	s_waitcnt vmcnt(0)
	v_and_b32_e32 v7, 0xffff0000, v98
	global_load_lds_dwordx4 v4, s[86:87]
	s_add_i32 m0, s72, 0x4400
	v_lshlrev_b32_e32 v5, 16, v98
	global_load_lds_dwordx4 v6, s[86:87]
	s_add_i32 m0, s72, 0x8000
	s_add_u32 s84, s73, s10
	s_addc_u32 s85, s74, 0
	v_lshl_add_u64 v[14:15], s[84:85], 0, v[0:1]
	s_lshl_b32 s3, s3, 8
	v_lshl_add_u64 v[14:15], v[14:15], 0, s[18:19]
	s_add_u32 s86, s75, s3
	global_load_lds_dwordx4 v[14:15], off
	v_lshl_add_u64 v[14:15], s[84:85], 0, v[8:9]
	s_addc_u32 s87, s82, 0
	v_lshl_add_u64 v[14:15], v[14:15], 0, s[18:19]
	s_add_i32 m0, s72, 0x8400
	v_mul_f32_e32 v13, v7, v7
	global_load_lds_dwordx4 v[14:15], off
	s_add_i32 m0, s72, 0xc000
	v_fmac_f32_e32 v13, v5, v5
	global_load_lds_dwordx4 v4, s[86:87]
	s_add_i32 m0, s72, 0xc400
	v_lshlrev_b32_e32 v5, 16, v99
	global_load_lds_dwordx4 v6, s[86:87]
	v_fmac_f32_e32 v13, v5, v5
	v_and_b32_e32 v5, 0xffff0000, v99
	v_fmac_f32_e32 v13, v5, v5
	v_lshlrev_b32_e32 v5, 16, v100
	v_fmac_f32_e32 v13, v5, v5
	v_and_b32_e32 v5, 0xffff0000, v100
	v_fmac_f32_e32 v13, v5, v5
	v_lshlrev_b32_e32 v5, 16, v101
	v_fmac_f32_e32 v13, v5, v5
	v_and_b32_e32 v5, 0xffff0000, v101
	v_fmac_f32_e32 v13, v5, v5
	v_lshlrev_b32_e32 v5, 16, v102
	v_fmac_f32_e32 v13, v5, v5
	v_and_b32_e32 v5, 0xffff0000, v102
	v_fmac_f32_e32 v13, v5, v5
	v_lshlrev_b32_e32 v5, 16, v103
	v_fmac_f32_e32 v13, v5, v5
	v_and_b32_e32 v5, 0xffff0000, v103
	v_fmac_f32_e32 v13, v5, v5
	v_lshlrev_b32_e32 v5, 16, v104
	v_fmac_f32_e32 v13, v5, v5
	v_and_b32_e32 v5, 0xffff0000, v104
	v_fmac_f32_e32 v13, v5, v5
	v_lshlrev_b32_e32 v5, 16, v105
	v_fmac_f32_e32 v13, v5, v5
	v_and_b32_e32 v5, 0xffff0000, v105
	v_fmac_f32_e32 v13, v5, v5
	v_lshlrev_b32_e32 v5, 16, v106
	v_fmac_f32_e32 v13, v5, v5
	v_and_b32_e32 v5, 0xffff0000, v106
	v_fmac_f32_e32 v13, v5, v5
	v_lshlrev_b32_e32 v5, 16, v107
	v_fmac_f32_e32 v13, v5, v5
	v_and_b32_e32 v5, 0xffff0000, v107
	v_fmac_f32_e32 v13, v5, v5
	v_lshlrev_b32_e32 v5, 16, v108
	v_fmac_f32_e32 v13, v5, v5
	v_and_b32_e32 v5, 0xffff0000, v108
	v_fmac_f32_e32 v13, v5, v5
	v_lshlrev_b32_e32 v5, 16, v109
	v_fmac_f32_e32 v13, v5, v5
	v_and_b32_e32 v5, 0xffff0000, v109
	v_fmac_f32_e32 v13, v5, v5
	v_lshlrev_b32_e32 v5, 16, v110
	v_fmac_f32_e32 v13, v5, v5
	v_and_b32_e32 v5, 0xffff0000, v110
	v_fmac_f32_e32 v13, v5, v5
	v_lshlrev_b32_e32 v5, 16, v111
	v_fmac_f32_e32 v13, v5, v5
	v_and_b32_e32 v5, 0xffff0000, v111
	v_fmac_f32_e32 v13, v5, v5
	v_lshlrev_b32_e32 v5, 16, v112
	v_fmac_f32_e32 v13, v5, v5
	v_and_b32_e32 v5, 0xffff0000, v112
	v_fmac_f32_e32 v13, v5, v5
	v_lshlrev_b32_e32 v5, 16, v113
	v_fmac_f32_e32 v13, v5, v5
	v_and_b32_e32 v5, 0xffff0000, v113
	v_fmac_f32_e32 v13, v5, v5
	ds_bpermute_b32 v14, v115, v13
	s_cmp_eq_u32 s2, 31
	s_cbranch_scc1 .LBB0_397
	s_sub_i32 s10, s59, 64
	s_add_i32 m0, s72, 0x10000
	s_mul_i32 s2, s10, 0x3400
	s_mul_hi_u32 s3, s10, 0x3400
	s_add_u32 s2, s73, s2
	s_addc_u32 s3, s74, s3
	s_lshl_b64 s[84:85], s[10:11], 1
	v_lshl_add_u64 v[16:17], s[2:3], 0, v[0:1]
	s_add_u32 s74, s75, s84
	v_lshl_add_u64 v[16:17], v[16:17], 0, s[18:19]
	v_lshl_add_u64 v[8:9], s[2:3], 0, v[8:9]
	v_mov_b32_e32 v5, v1
	s_addc_u32 s75, s82, s85
	global_load_lds_dwordx4 v[16:17], off
	v_lshl_add_u64 v[8:9], v[8:9], 0, s[18:19]
	s_add_i32 m0, s72, 0x10400
	v_mov_b32_e32 v7, v1
	global_load_lds_dwordx4 v[8:9], off
	s_add_i32 m0, s72, 0x14000
	s_nop 0
	global_load_lds_dwordx4 v4, s[74:75]
	v_lshl_add_u64 v[4:5], s[74:75], 0, v[6:7]
	s_add_i32 m0, s72, 0x14400
	s_nop 0
	global_load_lds_dwordx4 v[4:5], off

; #define LAS __attribute__((address_space(3)))
; __device__ __forceinline__ int crow(int r, int hi) { return (r & 3) + 8 * (r >> 2) + 4 * hi; }
; #define MFMA32(a, b, c) __builtin_amdgcn_mfma_f32_32x32x16_bf16((a), (b), (c), 0, 0, 0)
; __device__ __forceinline__ void unit(LAS unsigned char* lds, bf16_t* P1, const bf16_t* vaT, int b, int h, int qblk, float lam, const float* subln_w, const float* khalf) {
;     ...
;     for (int jj = 0; jj < NT; ++jj) {
;         const int j = NT - 1 - jj;
;         { const bool done = __all(qbound + sl2 * (float)(64 * j + 63 - qrow) < m - 24.f);
;           if (lane == 0) dflag[(jj & 1) * 8 + wid] = done ? 1 : 0; }
;         if (jj + 2 < NT) asm volatile("s_waitcnt vmcnt(8) lgkmcnt(0)\n\ts_barrier" ::: "memory"); else if (jj + 1 < NT) asm volatile("s_waitcnt vmcnt(4) lgkmcnt(0)\n\ts_barrier" ::: "memory"); else asm volatile("s_waitcnt vmcnt(0) lgkmcnt(0)\n\ts_barrier" ::: "memory");
;         { typedef int i32x4 __attribute__((ext_vector_type(4)));
;           const i32x4 fa = *(const LAS i32x4*)(lds + 4 * STG + (jj & 1) * 32), fb = *(const LAS i32x4*)(lds + 4 * STG + (jj & 1) * 32 + 16);
;           if (((fa[0] + fa[1]) + (fa[2] + fa[3])) + ((fb[0] + fb[1]) + (fb[2] + fb[3])) == 8) break; }
;         if (jj + 3 < NT) { DMA_TILE(j - 3, (stg + 3) & 3); }
;         const LAS unsigned char* kb = lds + stg * STG;
;         stg = (stg + 1) & 3;
;         f32x16 S0, S1;
;         { float slv = sl2; asm volatile("" : "+v"(slv));
; #pragma unroll
;           for (int r = 0; r < 16; ++r) { S0[r] = __builtin_fmaf(slv, (float)((r & 3) + 8 * (r >> 2)), sl2h); S1[r] = S0[r]; } }
; #pragma unroll
;         for (int ks = 0; ks < 4; ++ks) {
;             const bf16x8 a0 = *(const LAS bf16x8*)(kb + koff[ks]);
;             const bf16x8 a1 = *(const LAS bf16x8*)(kb + koff[ks] + 32 * 256);
;             S0 = MFMA32(a0, qf[ks], S0); S1 = MFMA32(a1, qf[ks], S1);
;         }
;         const int kv0 = 64 * j;
;         if (j >= NT - 2) {
; #pragma unroll
;             for (int r = 0; r < 16; ++r) { const int kv = kv0 + crow(r, hi); if (kv > qrow) S0[r] = -INFINITY; if (kv + 32 > qrow) S1[r] = -INFINITY; }
.La_after_bar:
	s_and_b32 s2, s10, 32
	s_add_i32 s2, s2, 0x20000
	v_mov_b32_e32 v70, s2
	s_lshl_b32 s4, s80, 15
	s_add_i32 s82, s4, 0
	ds_read_b128 v[66:69], v70
	ds_read_b128 v[70:73], v70 offset:16
	v_add3_u32 v120, s82, v129, v151
	v_add3_u32 v201, s82, v185, v151
	ds_read_b128 v[192:195], v120
	ds_read_b128 v[196:199], v120 offset:8192
	v_add3_u32 v120, s82, v186, v151
	ds_read_b128 v[202:205], v201
	ds_read_b128 v[206:209], v201 offset:8192
	v_add3_u32 v201, s82, v187, v151
	ds_read_b128 v[210:213], v120
	ds_read_b128 v[214:217], v120 offset:8192
	ds_read_b128 v[218:221], v201
	ds_read_b128 v[222:225], v201 offset:8192
	s_waitcnt lgkmcnt(8)
	v_add3_u32 v66, v66, v67, v68
	v_add3_u32 v69, v69, v70, v71
	v_add_u32_e32 v72, v72, v73
	v_add3_u32 v66, v66, v69, v72
	v_cmp_eq_u32_e32 vcc, 8, v66
	s_cbranch_vccnz .LBB0_420
	s_add_i32 s5, s81, 3
	s_cmp_ge_u32 s5, s73
	s_cbranch_scc1 .La_qk_nodma
	s_add_i32 s5, s4, 0x18000
	s_and_b32 s5, s5, 0x18000
	s_add_i32 s5, s72, s5
	s_mov_b32 m0, s5
	s_waitcnt lgkmcnt(4)
	v_mfma_f32_32x32x16_bf16 v[82:97], v[192:195], v[98:101], v[226:241]
	global_load_lds_dwordx4 v[140:141], off
	s_add_i32 m0, s5, 0x400
	v_mfma_f32_32x32x16_bf16 v[66:81], v[196:199], v[98:101], v[226:241]
	global_load_lds_dwordx4 v[138:139], off
	s_add_i32 m0, s5, 0x4000
	v_mfma_f32_32x32x16_bf16 v[82:97], v[202:205], v[102:105], v[82:97]
	global_load_lds_dwordx4 v134, s[44:45]
	s_add_i32 m0, s5, 0x4400
	v_mfma_f32_32x32x16_bf16 v[66:81], v[206:209], v[102:105], v[66:81]
	global_load_lds_dwordx4 v136, s[44:45]
	s_waitcnt lgkmcnt(0)
	v_mfma_f32_32x32x16_bf16 v[82:97], v[210:213], v[106:109], v[82:97]
	v_mfma_f32_32x32x16_bf16 v[66:81], v[214:217], v[106:109], v[66:81]
	v_mfma_f32_32x32x16_bf16 v[82:97], v[218:221], v[110:113], v[82:97]
	v_mfma_f32_32x32x16_bf16 v[66:81], v[222:225], v[110:113], v[66:81]
	s_branch .La_qk_done
.La_qk_nodma:
	s_waitcnt lgkmcnt(4)
	v_mfma_f32_32x32x16_bf16 v[82:97], v[192:195], v[98:101], v[226:241]
	v_mfma_f32_32x32x16_bf16 v[66:81], v[196:199], v[98:101], v[226:241]
	v_mfma_f32_32x32x16_bf16 v[82:97], v[202:205], v[102:105], v[82:97]
	v_mfma_f32_32x32x16_bf16 v[66:81], v[206:209], v[102:105], v[66:81]
	s_waitcnt lgkmcnt(0)
	v_mfma_f32_32x32x16_bf16 v[82:97], v[210:213], v[106:109], v[82:97]
	v_mfma_f32_32x32x16_bf16 v[66:81], v[214:217], v[106:109], v[66:81]
	v_mfma_f32_32x32x16_bf16 v[82:97], v[218:221], v[110:113], v[82:97]
	v_mfma_f32_32x32x16_bf16 v[66:81], v[222:225], v[110:113], v[66:81]
.La_qk_done:
	v_add_u32_e32 v244, s82, v168
	v_add_u32_e32 v245, s82, v169
	v_add_u32_e32 v246, s82, v170
	v_add_u32_e32 v247, s82, v171
	ds_read_b128 v[192:195], v244 offset:16384
	ds_read_b128 v[196:199], v244 offset:20480
	ds_read_b128 v[202:205], v244 offset:24576
	ds_read_b128 v[206:209], v244 offset:28672
	ds_read_b128 v[210:213], v245 offset:16384
	ds_read_b128 v[214:217], v245 offset:20480
	ds_read_b128 v[218:221], v245 offset:24576
	ds_read_b128 v[222:225], v245 offset:28672
	s_cmp_gt_u32 s81, 1
	s_cbranch_scc1 .La_nomask
	v_add_u32_e32 v243, s76, v189
	v_add_u32_e32 v250, 0x60, v243
	v_add_u32_e32 v251, 64, v243
	v_cmp_le_i32_e32 vcc, v250, v125
	s_nop 6
	v_cndmask_b32_e32 v66, v184, v66, vcc
	v_cmp_lt_i32_e32 vcc, v251, v125
	s_nop 1
	v_cndmask_b32_e32 v83, v184, v83, vcc
	v_cmp_le_i32_e32 vcc, v251, v125
	v_add_u32_e32 v251, 0x61, v243
	s_nop 0
	v_cndmask_b32_e32 v82, v184, v82, vcc
	v_cmp_le_i32_e32 vcc, v251, v125
	v_add_u32_e32 v251, 0x42, v243
	s_nop 0
	v_cndmask_b32_e32 v67, v184, v67, vcc
	v_cmp_le_i32_e32 vcc, v251, v125
	v_add_u32_e32 v251, 0x62, v243
	s_nop 0
	v_cndmask_b32_e32 v84, v184, v84, vcc
	v_cmp_le_i32_e32 vcc, v251, v125
	v_add_u32_e32 v251, 0x43, v243
	s_nop 0
	v_cndmask_b32_e32 v68, v184, v68, vcc
	v_cmp_le_i32_e32 vcc, v251, v125
	v_add_u32_e32 v251, 0x63, v243
	s_nop 0
	v_cndmask_b32_e32 v85, v184, v85, vcc
	v_cmp_le_i32_e32 vcc, v251, v125
	v_add_u32_e32 v251, 0x48, v243
	s_nop 0
	v_cndmask_b32_e32 v69, v184, v69, vcc
	v_cmp_le_i32_e32 vcc, v251, v125
	v_add_u32_e32 v251, 0x68, v243
	s_nop 0
	v_cndmask_b32_e32 v86, v184, v86, vcc
	v_cmp_le_i32_e32 vcc, v251, v125
	v_add_u32_e32 v251, 0x49, v243
	s_nop 0
	v_cndmask_b32_e32 v70, v184, v70, vcc
	v_cmp_le_i32_e32 vcc, v251, v125
	v_add_u32_e32 v251, 0x69, v243
	s_nop 0
	v_cndmask_b32_e32 v87, v184, v87, vcc
	v_cmp_le_i32_e32 vcc, v251, v125
	v_add_u32_e32 v251, 0x4a, v243
	s_nop 0
	v_cndmask_b32_e32 v71, v184, v71, vcc
	v_cmp_le_i32_e32 vcc, v251, v125
	v_add_u32_e32 v251, 0x6a, v243
	s_nop 0
	v_cndmask_b32_e32 v88, v184, v88, vcc
	v_cmp_le_i32_e32 vcc, v251, v125
	v_add_u32_e32 v251, 0x4b, v243
	s_nop 0
	v_cndmask_b32_e32 v72, v184, v72, vcc
	v_cmp_le_i32_e32 vcc, v251, v125
	v_add_u32_e32 v251, 0x6b, v243
	s_nop 0
	v_cndmask_b32_e32 v89, v184, v89, vcc
	v_cmp_le_i32_e32 vcc, v251, v125
	v_add_u32_e32 v251, 0x50, v243
	s_nop 0
	v_cndmask_b32_e32 v73, v184, v73, vcc
	v_cmp_le_i32_e32 vcc, v251, v125
	v_add_u32_e32 v251, 0x70, v243
	s_nop 0
	v_cndmask_b32_e32 v90, v184, v90, vcc
	v_cmp_le_i32_e32 vcc, v251, v125
	v_add_u32_e32 v251, 0x51, v243
	s_nop 0
	v_cndmask_b32_e32 v74, v184, v74, vcc
	v_cmp_le_i32_e32 vcc, v251, v125
	v_add_u32_e32 v251, 0x71, v243
	s_nop 0
	v_cndmask_b32_e32 v91, v184, v91, vcc
	v_cmp_le_i32_e32 vcc, v251, v125
	v_add_u32_e32 v251, 0x52, v243
	s_nop 0
	v_cndmask_b32_e32 v75, v184, v75, vcc
	v_cmp_le_i32_e32 vcc, v251, v125
	v_add_u32_e32 v251, 0x72, v243
	s_nop 0
	v_cndmask_b32_e32 v92, v184, v92, vcc
	v_cmp_le_i32_e32 vcc, v251, v125
	v_add_u32_e32 v251, 0x53, v243
	s_nop 0
	v_cndmask_b32_e32 v76, v184, v76, vcc
	v_cmp_le_i32_e32 vcc, v251, v125
	v_add_u32_e32 v251, 0x73, v243
	s_nop 0
	v_cndmask_b32_e32 v93, v184, v93, vcc
	v_cmp_le_i32_e32 vcc, v251, v125
	v_add_u32_e32 v251, 0x58, v243
	s_nop 0
	v_cndmask_b32_e32 v77, v184, v77, vcc
	v_cmp_le_i32_e32 vcc, v251, v125
	v_add_u32_e32 v251, 0x78, v243
	s_nop 0
	v_cndmask_b32_e32 v94, v184, v94, vcc
	v_cmp_le_i32_e32 vcc, v251, v125
	v_add_u32_e32 v251, 0x59, v243
	s_nop 0
	v_cndmask_b32_e32 v78, v184, v78, vcc
	v_cmp_le_i32_e32 vcc, v251, v125
	v_add_u32_e32 v251, 0x79, v243
	s_nop 0
	v_cndmask_b32_e32 v95, v184, v95, vcc
	v_cmp_le_i32_e32 vcc, v251, v125
	v_add_u32_e32 v251, 0x5a, v243
	s_nop 0
	v_cndmask_b32_e32 v79, v184, v79, vcc
	v_cmp_le_i32_e32 vcc, v251, v125
	v_add_u32_e32 v251, 0x7a, v243
	s_nop 0
	v_cndmask_b32_e32 v96, v184, v96, vcc
	v_cmp_le_i32_e32 vcc, v251, v125
	v_add_u32_e32 v251, 0x5b, v243
	v_add_u32_e32 v243, 0x7b, v243
	v_cndmask_b32_e32 v80, v184, v80, vcc
	v_cmp_le_i32_e32 vcc, v251, v125
	s_nop 1
	v_cndmask_b32_e32 v97, v184, v97, vcc
	v_cmp_le_i32_e32 vcc, v243, v125
	s_nop 1
	v_cndmask_b32_e32 v81, v184, v81, vcc
; __device__ __forceinline__ int crow(int r, int hi) { return (r & 3) + 8 * (r >> 2) + 4 * hi; }
; __device__ __forceinline__ float ex2(float v) { return __builtin_amdgcn_exp2f(v); }
; __device__ __forceinline__ void unit(LAS unsigned char* lds, bf16_t* P1, const bf16_t* vaT, int b, int h, int qblk, float lam, const float* subln_w, const float* khalf) {
;     ...
;             for (int r = 0; r < 16; ++r) { const int kv = kv0 + crow(r, hi); if (kv > qrow) S0[r] = -INFINITY; if (kv + 32 > qrow) S1[r] = -INFINITY; }
;         }
;         const float tb0 = sl2 * (float)(kv0 - qrow), tb1 = tb0 + sl2 * 32.f;
;         float mx0 = S0[0], mx1 = S1[0];
; #pragma unroll
;         for (int r = 1; r < 16; ++r) { mx0 = fmaxf(mx0, S0[r]); mx1 = fmaxf(mx1, S1[r]); }
;         float mt = fmaxf(mx0 + tb0, mx1 + tb1); mt = fmaxf(mt, __shfl_xor(mt, 32));
;         const bool skip = __all((mt < m - 24.f) || (mt == -INFINITY));
;         if (!skip) {
;         const float mn = fmaxf(m, mt); const float alpha = ex2(m - mn); m = mn;
;         const float c0 = tb0 - mn, c1 = tb1 - mn;
;         f32x2 ps2 = (f32x2){0.f, 0.f};
; #pragma unroll
;         for (int r = 0; r < 16; r += 2) { f32x2 a = (f32x2){S0[r], S0[r + 1]} + c0, bq = (f32x2){S1[r], S1[r + 1]} + c1;
;             a.x = ex2(a.x); a.y = ex2(a.y); bq.x = ex2(bq.x); bq.y = ex2(bq.y); S0[r] = a.x; S0[r + 1] = a.y; S1[r] = bq.x; S1[r + 1] = bq.y; ps2 = ps2 + a; ps2 = ps2 + bq; }
;         l = l * alpha + (ps2.x + ps2.y);
;         if (__any(alpha != 1.f)) {
; #pragma unroll
;             for (int d = 0; d < 4; ++d) O[d] = O[d] * alpha;
.La_nomask:
	v_add_u32_e32 v0, 64, v0
	v_cvt_f32_i32_e32 v142, v0
	v_max3_f32 v0, v82, v83, v84
	v_max3_f32 v120, v66, v67, v68
	v_max3_f32 v0, v0, v85, v86
	v_max3_f32 v120, v120, v69, v70
	v_max3_f32 v0, v0, v87, v88
	v_max3_f32 v120, v120, v71, v72
	v_max3_f32 v0, v0, v89, v90
	v_max3_f32 v120, v120, v73, v74
	v_max3_f32 v0, v0, v91, v92
	v_max3_f32 v120, v120, v75, v76
	v_max3_f32 v0, v0, v93, v94
	v_max3_f32 v120, v120, v77, v78
	v_max3_f32 v0, v0, v95, v96
	v_max3_f32 v120, v120, v79, v80
	v_max_f32_e32 v0, v0, v97
	v_max_f32_e32 v120, v120, v81
	v_fma_f32 v248, v127, v142, v188
	v_fmac_f32_e32 v0, v127, v142
	v_add_f32_e32 v120, v248, v120
	v_max_f32_e32 v0, v0, v120
	ds_bpermute_b32 v120, v115, v0
	s_waitcnt lgkmcnt(0)
	v_max_f32_e32 v0, v0, v120
	v_cmp_lt_f32_e32 vcc, v0, v143
	v_cmp_eq_f32_e64 s[4:5], v0, v184
	s_or_b64 s[4:5], vcc, s[4:5]
	s_cmp_eq_u64 s[4:5], exec
	s_cbranch_scc1 .La_latch
	v_max_f32_e32 v120, v133, v0
	v_mul_f32_e32 v142, v127, v142
	v_sub_f32_e32 v0, v133, v120
	v_exp_f32_e32 v0, v0
	v_sub_f32_e32 v142, v142, v120
	v_sub_f32_e32 v248, v248, v120
	v_mov_b32_e32 v133, v120
	v_cmp_neq_f32_e32 vcc, 1.0, v0
	s_cbranch_vccz .La_norescale
	v_mul_f32_e32 v65, v0, v65
	v_mul_f32_e32 v64, v0, v64
	v_mul_f32_e32 v63, v0, v63
	v_mul_f32_e32 v62, v0, v62
	v_mul_f32_e32 v61, v0, v61
	v_mul_f32_e32 v60, v0, v60
	v_mul_f32_e32 v59, v0, v59
	v_mul_f32_e32 v58, v0, v58
	v_mul_f32_e32 v57, v0, v57
	v_mul_f32_e32 v56, v0, v56
	v_mul_f32_e32 v55, v0, v55
	v_mul_f32_e32 v54, v0, v54
	v_mul_f32_e32 v53, v0, v53
	v_mul_f32_e32 v52, v0, v52
	v_mul_f32_e32 v51, v0, v51
	v_mul_f32_e32 v50, v0, v50
	v_mul_f32_e32 v49, v0, v49
	v_mul_f32_e32 v48, v0, v48
	v_mul_f32_e32 v47, v0, v47
	v_mul_f32_e32 v46, v0, v46
	v_mul_f32_e32 v45, v0, v45
	v_mul_f32_e32 v44, v0, v44
	v_mul_f32_e32 v43, v0, v43
	v_mul_f32_e32 v42, v0, v42
	v_mul_f32_e32 v41, v0, v41
	v_mul_f32_e32 v40, v0, v40
	v_mul_f32_e32 v39, v0, v39
	v_mul_f32_e32 v38, v0, v38
	v_mul_f32_e32 v37, v0, v37
	v_mul_f32_e32 v36, v0, v36
	v_mul_f32_e32 v35, v0, v35
	v_mul_f32_e32 v34, v0, v34
	v_mul_f32_e32 v33, v0, v33
	v_mul_f32_e32 v32, v0, v32
	v_mul_f32_e32 v31, v0, v31
	v_mul_f32_e32 v30, v0, v30
	v_mul_f32_e32 v29, v0, v29
	v_mul_f32_e32 v28, v0, v28
	v_mul_f32_e32 v27, v0, v27
	v_mul_f32_e32 v26, v0, v26
	v_mul_f32_e32 v25, v0, v25
	v_mul_f32_e32 v24, v0, v24
	v_mul_f32_e32 v23, v0, v23
	v_mul_f32_e32 v22, v0, v22
	v_mul_f32_e32 v21, v0, v21
	v_mul_f32_e32 v20, v0, v20
	v_mul_f32_e32 v19, v0, v19
	v_mul_f32_e32 v18, v0, v18
	v_mul_f32_e32 v17, v0, v17
	v_mul_f32_e32 v16, v0, v16
	v_mul_f32_e32 v15, v0, v15
	v_mul_f32_e32 v14, v0, v14
	v_mul_f32_e32 v13, v0, v13
	v_mul_f32_e32 v12, v0, v12
	v_mul_f32_e32 v11, v0, v11
	v_mul_f32_e32 v10, v0, v10
	v_mul_f32_e32 v9, v0, v9
	v_mul_f32_e32 v8, v0, v8
	v_mul_f32_e32 v7, v0, v7
	v_mul_f32_e32 v6, v0, v6
	v_mul_f32_e32 v5, v0, v5
	v_mul_f32_e32 v4, v0, v4
	v_mul_f32_e32 v3, v0, v3
	v_mul_f32_e32 v2, v0, v2
; #define LAS __attribute__((address_space(3)))
; __device__ __forceinline__ unsigned cvtpk(float lo, float hi) { return pg8::cvt_pk_bf16(lo, hi); }
; __device__ __forceinline__ float ex2(float v) { return __builtin_amdgcn_exp2f(v); }
; #define MFMA32(a, b, c) __builtin_amdgcn_mfma_f32_32x32x16_bf16((a), (b), (c), 0, 0, 0)
; __device__ __forceinline__ void unit(LAS unsigned char* lds, bf16_t* P1, const bf16_t* vaT, int b, int h, int qblk, float lam, const float* subln_w, const float* khalf) {
;     ...
;         const float mn = fmaxf(m, mt); const float alpha = ex2(m - mn); m = mn;
;         const float c0 = tb0 - mn, c1 = tb1 - mn;
;         f32x2 ps2 = (f32x2){0.f, 0.f};
; #pragma unroll
;         for (int r = 0; r < 16; r += 2) { f32x2 a = (f32x2){S0[r], S0[r + 1]} + c0, bq = (f32x2){S1[r], S1[r + 1]} + c1;
;             a.x = ex2(a.x); a.y = ex2(a.y); bq.x = ex2(bq.x); bq.y = ex2(bq.y); S0[r] = a.x; S0[r + 1] = a.y; S1[r] = bq.x; S1[r + 1] = bq.y; ps2 = ps2 + a; ps2 = ps2 + bq; }
;         l = l * alpha + (ps2.x + ps2.y);
;         if (__any(alpha != 1.f)) {
; #pragma unroll
;             for (int d = 0; d < 4; ++d) O[d] = O[d] * alpha;
;         }
;         u32x4 pk[2][2];
; #pragma unroll
;         for (int s = 0; s < 2; ++s) {
;             pk[0][s] = (u32x4){cvtpk(S0[8 * s + 0], S0[8 * s + 1]), cvtpk(S0[8 * s + 2], S0[8 * s + 3]), cvtpk(S0[8 * s + 4], S0[8 * s + 5]), cvtpk(S0[8 * s + 6], S0[8 * s + 7])};
;             pk[1][s] = (u32x4){cvtpk(S1[8 * s + 0], S1[8 * s + 1]), cvtpk(S1[8 * s + 2], S1[8 * s + 3]), cvtpk(S1[8 * s + 4], S1[8 * s + 5]), cvtpk(S1[8 * s + 6], S1[8 * s + 7])};
;         }
; #pragma unroll
;         for (int d = 0; d < 4; ++d)
; #pragma unroll
;             for (int t2 = 0; t2 < 2; ++t2)
; #pragma unroll
;                 for (int s = 0; s < 2; ++s) {
;                     const bf16x8 vf = *(const LAS bf16x8*)(kb + voff[2 * t2 + s] + d * 32 * 128);
;                     O[d] = MFMA32(vf, __builtin_bit_cast(bf16x8, pk[t2][s]), O[d]);
;                 }
;         }
.La_norescale:
	v_pk_add_f32 v[82:83], v[82:83], v[142:143] op_sel_hi:[1,0]
	v_pk_add_f32 v[84:85], v[84:85], v[142:143] op_sel_hi:[1,0]
	v_pk_add_f32 v[86:87], v[86:87], v[142:143] op_sel_hi:[1,0]
	v_pk_add_f32 v[88:89], v[88:89], v[142:143] op_sel_hi:[1,0]
	v_exp_f32_e32 v82, v82
	v_exp_f32_e32 v83, v83
	v_exp_f32_e32 v84, v84
	v_exp_f32_e32 v85, v85
	v_exp_f32_e32 v86, v86
	v_exp_f32_e32 v87, v87
	v_exp_f32_e32 v88, v88
	v_exp_f32_e32 v89, v89
	v_pk_add_f32 v[252:253], v[82:83], v[84:85]
	v_cvt_pk_bf16_f32 v82, v82, v83
	v_cvt_pk_bf16_f32 v83, v84, v85
	v_cvt_pk_bf16_f32 v84, v86, v87
	v_cvt_pk_bf16_f32 v85, v88, v89
	v_pk_add_f32 v[252:253], v[252:253], v[86:87]
	v_pk_add_f32 v[252:253], v[252:253], v[88:89]
	v_mfma_f32_32x32x16_bf16 v[50:65], v[192:195], v[82:85], v[50:65]
	ds_read_b128 v[192:195], v246 offset:16384
	v_pk_add_f32 v[90:91], v[90:91], v[142:143] op_sel_hi:[1,0]
	v_pk_add_f32 v[92:93], v[92:93], v[142:143] op_sel_hi:[1,0]
	v_pk_add_f32 v[94:95], v[94:95], v[142:143] op_sel_hi:[1,0]
	v_pk_add_f32 v[96:97], v[96:97], v[142:143] op_sel_hi:[1,0]
	v_exp_f32_e32 v90, v90
	v_mfma_f32_32x32x16_bf16 v[34:49], v[196:199], v[82:85], v[34:49]
	ds_read_b128 v[196:199], v246 offset:20480
	v_exp_f32_e32 v91, v91
	v_exp_f32_e32 v92, v92
	v_exp_f32_e32 v93, v93
	v_exp_f32_e32 v94, v94
	v_exp_f32_e32 v95, v95
	v_mfma_f32_32x32x16_bf16 v[18:33], v[202:205], v[82:85], v[18:33]
	ds_read_b128 v[202:205], v246 offset:24576
	v_exp_f32_e32 v96, v96
	v_exp_f32_e32 v97, v97
	v_pk_add_f32 v[252:253], v[252:253], v[90:91]
	v_pk_add_f32 v[252:253], v[252:253], v[92:93]
	v_cvt_pk_bf16_f32 v90, v90, v91
	v_mfma_f32_32x32x16_bf16 v[2:17], v[206:209], v[82:85], v[2:17]
	ds_read_b128 v[206:209], v246 offset:28672
	v_cvt_pk_bf16_f32 v91, v92, v93
	v_cvt_pk_bf16_f32 v92, v94, v95
	v_cvt_pk_bf16_f32 v93, v96, v97
	v_pk_add_f32 v[252:253], v[252:253], v[94:95]
	v_pk_add_f32 v[252:253], v[252:253], v[96:97]
	v_mfma_f32_32x32x16_bf16 v[50:65], v[210:213], v[90:93], v[50:65]
	ds_read_b128 v[210:213], v247 offset:16384
	v_pk_add_f32 v[66:67], v[66:67], v[248:249] op_sel_hi:[1,0]
	v_pk_add_f32 v[68:69], v[68:69], v[248:249] op_sel_hi:[1,0]
	v_pk_add_f32 v[70:71], v[70:71], v[248:249] op_sel_hi:[1,0]
	v_pk_add_f32 v[72:73], v[72:73], v[248:249] op_sel_hi:[1,0]
	v_exp_f32_e32 v66, v66
	v_mfma_f32_32x32x16_bf16 v[34:49], v[214:217], v[90:93], v[34:49]
	ds_read_b128 v[214:217], v247 offset:20480
	v_exp_f32_e32 v67, v67
	v_exp_f32_e32 v68, v68
	v_exp_f32_e32 v69, v69
	v_exp_f32_e32 v70, v70
	v_exp_f32_e32 v71, v71
	v_mfma_f32_32x32x16_bf16 v[18:33], v[218:221], v[90:93], v[18:33]
	ds_read_b128 v[218:221], v247 offset:24576
	v_exp_f32_e32 v72, v72
	v_exp_f32_e32 v73, v73
	v_pk_add_f32 v[252:253], v[252:253], v[66:67]
	v_pk_add_f32 v[252:253], v[252:253], v[68:69]
	v_cvt_pk_bf16_f32 v66, v66, v67
	v_mfma_f32_32x32x16_bf16 v[2:17], v[222:225], v[90:93], v[2:17]
	ds_read_b128 v[222:225], v247 offset:28672
	v_cvt_pk_bf16_f32 v67, v68, v69
	v_cvt_pk_bf16_f32 v68, v70, v71
	v_cvt_pk_bf16_f32 v69, v72, v73
	v_pk_add_f32 v[252:253], v[252:253], v[70:71]
	v_pk_add_f32 v[252:253], v[252:253], v[72:73]
	s_waitcnt lgkmcnt(4)
	v_mfma_f32_32x32x16_bf16 v[50:65], v[192:195], v[66:69], v[50:65]
	v_pk_add_f32 v[74:75], v[74:75], v[248:249] op_sel_hi:[1,0]
	v_pk_add_f32 v[76:77], v[76:77], v[248:249] op_sel_hi:[1,0]
	v_pk_add_f32 v[78:79], v[78:79], v[248:249] op_sel_hi:[1,0]
	v_pk_add_f32 v[80:81], v[80:81], v[248:249] op_sel_hi:[1,0]
	v_exp_f32_e32 v74, v74
	v_mfma_f32_32x32x16_bf16 v[34:49], v[196:199], v[66:69], v[34:49]
	v_exp_f32_e32 v75, v75
	v_exp_f32_e32 v76, v76
	v_exp_f32_e32 v77, v77
	v_exp_f32_e32 v78, v78
	v_exp_f32_e32 v79, v79
	v_mfma_f32_32x32x16_bf16 v[18:33], v[202:205], v[66:69], v[18:33]
	v_exp_f32_e32 v80, v80
	v_exp_f32_e32 v81, v81
	v_pk_add_f32 v[252:253], v[252:253], v[74:75]
	v_pk_add_f32 v[252:253], v[252:253], v[76:77]
	v_cvt_pk_bf16_f32 v74, v74, v75
	v_mfma_f32_32x32x16_bf16 v[2:17], v[206:209], v[66:69], v[2:17]
	v_cvt_pk_bf16_f32 v75, v76, v77
	v_cvt_pk_bf16_f32 v76, v78, v79
	v_cvt_pk_bf16_f32 v77, v80, v81
	v_pk_add_f32 v[252:253], v[252:253], v[78:79]
	v_pk_add_f32 v[252:253], v[252:253], v[80:81]
	s_waitcnt lgkmcnt(0)
	v_mfma_f32_32x32x16_bf16 v[50:65], v[210:213], v[74:77], v[50:65]
	v_add_f32_e32 v250, v252, v253
	v_mfma_f32_32x32x16_bf16 v[34:49], v[214:217], v[74:77], v[34:49]
	v_fma_f32 v191, v191, v0, v250
	v_mfma_f32_32x32x16_bf16 v[18:33], v[218:221], v[74:77], v[18:33]
	v_mfma_f32_32x32x16_bf16 v[2:17], v[222:225], v[74:77], v[2:17]
.La_latch:
	s_add_i32 s80, s80, 1
	s_and_b32 s80, s80, 3
	s_add_i32 s4, s59, s76
	s_add_i32 s81, s81, 1
	s_add_i32 s77, s77, 8
	s_add_i32 s10, s10, 32
	s_sub_i32 s76, s76, 64
	s_add_u32 s44, s44, 0xffffff80
	s_addc_u32 s45, s45, -1
	v_lshl_add_u64 v[138:139], v[138:139], 0, s[38:39]
	v_lshl_add_u64 v[140:141], v[140:141], 0, s[38:39]
	s_cmpk_eq_i32 s4, 0xffc0
	s_cbranch_scc0 .La_top
	s_branch .LBB0_420

;     __device__ bool next(int i, Unit& u) const { if (i >= 2) return false; if (!S.next(0, u)) return false; u.pn += 4 * i; return true; }
; #define PG8_STAGE(bufoff, gbase, voff) do { _Pragma("unroll") for (int _i = 0; _i < 2; ++_i) \
;         __builtin_amdgcn_global_load_lds((const unsigned*)((const char*)(gbase) + (voff)[_i]), (PG8_LAS unsigned*)(lds + (bufoff) + ldsw + _i * 8192), 16, 0, 0); } while (0)
; #define PG8_WAIT_V(n) asm volatile("s_waitcnt vmcnt(" #n ")" ::: "memory")
; #define PG8_BAR __builtin_amdgcn_s_barrier()
;     __host__ __device__ bool next(int i, Unit& u) const {
;         const long L = (long)i * G + c; if (L >= nwg) return false;
;         int wgid = (int)L; { const int q = nwg / NXCD, r = nwg % NXCD, xcd = wgid % NXCD, off = wgid / NXCD; wgid = (xcd < r ? xcd * (q + 1) : r * (q + 1) + (xcd - r) * q) + off; }
;         const int nig = WGM * nN, gid = wgid / nig, fm = gid * WGM, gsz = (nM - fm) < WGM ? (nM - fm) : WGM;
;         u.pm = fm + ((wgid % nig) % gsz); u.pn = (wgid % nig) / gsz; return true;
;     }
; template <class Epi, class Sched, bool ALIGN_EPI = false, bool SP2 = false>
; __device__ __forceinline__ void gemm_phase(PG8_LAS unsigned char* lds, const Gemm g, const Sched& S, const Epi& E) {
;     ...
;         PG8_STAGE(PG8_SB(0, 0), cB, voffB); PG8_STAGE(PG8_SB(0, 1), cB + hstepB, voffB); PG8_STAGE(PG8_SA(0, 0), cA, voffA); PG8_STAGE(PG8_SA(0, 1), cA + hstepA, voffA);
;         if (wr == 1) PG8_BAR;
;         PG8_WAIT_V(2); PG8_BAR;
;         PG8_STAGE(PG8_SB(1, 0), cB + kstep, voffB); PG8_STAGE(PG8_SA(1, 0), cA + kstep, voffA); PG8_STAGE(PG8_SB(1, 1), cB + hstepB + kstep, voffB);
;         PG8_WAIT_V(6); PG8_BAR;
.LBB0_486:
	s_lshl_b32 s18, s18, 5
	s_and_b32 s29, s18, 0x60
	s_mov_b64 s[18:19], 0x80
	s_add_i32 m0, s31, 0x18000
	v_lshl_add_u64 v[6:7], v[6:7], 0, s[18:19]
	s_lshl_b32 s28, s25, 13
	s_waitcnt vmcnt(2)
	s_barrier
	global_load_lds_dwordx4 v[6:7], off
	v_lshl_add_u64 v[4:5], v[4:5], 0, s[18:19]
	s_add_i32 m0, s31, 0x1a000
	s_add_i32 s45, s31, 0x8000
	s_add_i32 s46, s31, 0xa000
	global_load_lds_dwordx4 v[4:5], off
	v_lshl_add_u64 v[0:1], v[0:1], 0, s[18:19]
	s_mov_b32 m0, s45
	s_add_u32 s26, s36, 0x40080
	global_load_lds_dwordx4 v[0:1], off
	v_lshl_add_u64 v[0:1], v[2:3], 0, s[18:19]
	s_mov_b32 m0, s46
	s_addc_u32 s27, s37, 0
	global_load_lds_dwordx4 v[0:1], off
	s_add_i32 m0, s31, 0x1c000
	global_load_lds_dwordx4 v144, s[26:27]
	v_lshl_add_u64 v[0:1], s[26:27], 0, v[146:147]
	s_add_i32 m0, s31, 0x1e000
	s_cmpk_lt_u32 s21, 0x100
	global_load_lds_dwordx4 v[0:1], off
	s_sext_i32_i8 s50, s20
	s_cselect_b64 s[20:21], -1, 0
	s_lshl_b32 s22, s22, 5
	s_and_b64 s[0:1], s[0:1], exec
	s_cselect_b32 s0, s23, s22
	s_add_i32 s0, s0, s24
	s_ashr_i32 s1, s0, 31
	s_lshr_b32 s1, s1, 27
	s_add_i32 s1, s0, s1
	s_ashr_i32 s22, s1, 5
	s_lshl_b32 s22, s22, 3
	s_sub_i32 s23, 64, s22
	v_lshlrev_b32_e32 v1, 2, v163
	s_min_i32 s23, s23, 8
	v_lshl_or_b32 v0, v163, 6, v164
	v_and_b32_e32 v1, 32, v1
	s_abs_i32 s24, s23
	v_bitop3_b32 v0, v0, s28, v1 bitop3:0xde
	v_cvt_f32_u32_e32 v1, s24
	s_sub_i32 s26, 0, s24
	s_andn2_b32 s1, s1, 31
	s_sub_i32 s0, s0, s1
	v_rcp_iflag_f32_e32 v1, v1
	v_lshl_or_b32 v171, s25, 6, v163
	s_abs_i32 s25, s0
	s_xor_b32 s1, s0, s23
	v_mul_f32_e32 v1, 0x4f7ffffe, v1
	v_cvt_u32_f32_e32 v1, v1
	s_ashr_i32 s1, s1, 31
	v_lshlrev_b32_e32 v2, 11, v8
	s_waitcnt vmcnt(6)
	v_readfirstlane_b32 s27, v1
	s_mul_i32 s26, s26, s27
	s_mul_hi_u32 s26, s27, s26
	s_add_i32 s27, s27, s26
	s_mul_hi_u32 s26, s25, s27
	s_mul_i32 s27, s26, s24
	s_sub_i32 s25, s25, s27
	s_add_i32 s27, s26, 1
	s_sub_i32 s28, s25, s24
	s_cmp_ge_u32 s25, s24
	s_cselect_b32 s26, s27, s26
	s_cselect_b32 s25, s28, s25
	s_add_i32 s27, s26, 1
	s_cmp_ge_u32 s25, s24
	v_lshlrev_b32_e32 v1, 8, v176
	s_cselect_b32 s24, s27, s26
	v_and_b32_e32 v1, 0x38000, v1
	s_xor_b32 s24, s24, s1
	v_or3_b32 v1, v160, v1, v2
	s_sub_i32 s1, s24, s1
	v_add_u32_e32 v152, v1, v161
	v_lshlrev_b32_e32 v1, 4, v9
	s_mul_i32 s23, s1, s23
	v_and_b32_e32 v1, 0x78000, v1
	v_lshl_or_b32 v172, s29, 7, v165
	s_sub_i32 s0, s0, s23
	v_or3_b32 v1, v160, v1, v2
	s_add_i32 s47, 0, 0x10000
	s_add_i32 s48, 0, 0x14000
	v_or_b32_e32 v173, s29, v162
	s_add_i32 s22, s22, s0
	s_add_i32 s24, s1, 4
	v_mov_b32_e32 v153, v145
	v_add_u32_e32 v154, v1, v161
	v_mov_b32_e32 v155, v145
	s_mov_b64 s[38:39], -1
	v_add_u32_e32 v174, s47, v172
	v_add_u32_e32 v175, s48, v172
	v_add_u32_e32 v177, 0, v0
	s_movk_i32 s49, 0x3400
	s_barrier
	s_branch .LBB0_489

; #define PG8_STAGE(bufoff, gbase, voff) do { _Pragma("unroll") for (int _i = 0; _i < 2; ++_i) \
;         __builtin_amdgcn_global_load_lds((const unsigned*)((const char*)(gbase) + (voff)[_i]), (PG8_LAS unsigned*)(lds + (bufoff) + ldsw + _i * 8192), 16, 0, 0); } while (0)
; #define PG8_LDA(dst, b, h) do { _Pragma("unroll") for (int m = 0; m < 4; ++m) _Pragma("unroll") for (int k = 0; k < 2; ++k) dst[m][k] = *(const PG8_LAS bf16x8*)(lds + PG8_SA(b, h) + aoff + m * 2048 + k * 1024); } while (0)
; #define PG8_LDB(dst, b, h) do { _Pragma("unroll") for (int n = 0; n < 2; ++n) _Pragma("unroll") for (int k = 0; k < 2; ++k) dst[n][k] = *(const PG8_LAS bf16x8*)(lds + PG8_SB(b, h) + boff + n * 2048 + k * 1024); } while (0)
; #define PG8_MMA(ai, bj, At, Bt) do { __builtin_amdgcn_s_setprio(1); _Pragma("unroll") for (int m = 0; m < 4; ++m) _Pragma("unroll") for (int n = 0; n < 2; ++n) _Pragma("unroll") for (int k = 0; k < 2; ++k) \
;         acc[ai][bj][m][n] = __builtin_amdgcn_mfma_f32_16x16x32_bf16(Bt[n][k], At[m][k], acc[ai][bj][m][n], 0, 0, 0); __builtin_amdgcn_s_setprio(0); } while (0)
; #define PG8_WAIT_V(n) asm volatile("s_waitcnt vmcnt(" #n ")" ::: "memory")
; #define PG8_WAIT_L(n) asm volatile("s_waitcnt lgkmcnt(" #n ")" ::: "memory")
; #define PG8_BAR __builtin_amdgcn_s_barrier()
; #define PG8_SCHED __builtin_amdgcn_sched_barrier(0)
; template <class Epi, class Sched, bool ALIGN_EPI = false, bool SP2 = false>
; __device__ __forceinline__ void gemm_phase(PG8_LAS unsigned char* lds, const Gemm g, const Sched& S, const Epi& E) {
;     ...
;             PG8_LDB(B0, 0, 0); PG8_LDB(B1, 0, 1); PG8_SCHED; PG8_LDA(At, 0, 0); PG8_STAGE(PG8_SA(1, 1), a1 + hstepA, voffA);
;             PG8_WAIT_V(8); PG8_WAIT_L(0); PG8_BAR; PG8_MMA(0, 0, At, B0); PG8_MMA(0, 1, At, B1); PG8_BAR; PG8_SCHED;
;             PG8_LDA(At, 0, 1); PG8_STAGE(PG8_SB(0, 0), b2, voffB); PG8_STAGE(PG8_SB(0, 1), b2 + hstepB, voffB); PG8_STAGE(PG8_SA(0, 0), a2, voffA);
;             PG8_WAIT_V(8); PG8_WAIT_L(0); PG8_BAR; PG8_MMA(1, 0, At, B0); PG8_MMA(1, 1, At, B1); PG8_BAR; PG8_SCHED;
.LBB0_490:
	ds_read_b128 v[100:103], v174
	ds_read_b128 v[104:107], v174 offset:1024
	ds_read_b128 v[112:115], v174 offset:2048
	ds_read_b128 v[116:119], v174 offset:3072
	ds_read_b128 v[156:159], v175
	ds_read_b128 v[178:181], v175 offset:1024
	ds_read_b128 v[182:185], v175 offset:2048
	ds_read_b128 v[186:189], v175 offset:3072
	s_add_u32 s36, s34, 0xfffc0080
	s_addc_u32 s37, s35, -1
	s_cmp_eq_u32 s55, 12
	s_cselect_b32 s39, s23, s37
	s_cselect_b32 s38, s51, s36
	s_cselect_b32 s37, s25, s54
	s_cselect_b32 s36, s52, s53
	s_add_i32 m0, s31, 0xc000
	ds_read_b128 v[190:193], v177
	ds_read_b128 v[194:197], v177 offset:1024
	ds_read_b128 v[202:205], v177 offset:2048
	ds_read_b128 v[206:209], v177 offset:3072
	ds_read_b128 v[210:213], v177 offset:4096
	ds_read_b128 v[214:217], v177 offset:5120
	ds_read_b128 v[218:221], v177 offset:6144
	ds_read_b128 v[222:225], v177 offset:7168
	global_load_lds_dwordx4 v152, s[34:35]
	s_add_i32 m0, s31, 0xe000
	s_nop 0
	global_load_lds_dwordx4 v154, s[34:35]
	s_waitcnt vmcnt(8)
	s_waitcnt lgkmcnt(0)
	s_barrier
	s_setprio 1
	s_waitcnt lgkmcnt(0)
	v_mfma_f32_16x16x32_bf16 v[140:143], v[100:103], v[190:193], v[140:143]
	v_mfma_f32_16x16x32_bf16 v[136:139], v[112:115], v[190:193], v[136:139]
	v_mfma_f32_16x16x32_bf16 v[124:127], v[100:103], v[202:205], v[124:127]
	v_mfma_f32_16x16x32_bf16 v[120:123], v[112:115], v[202:205], v[120:123]
	v_mfma_f32_16x16x32_bf16 v[92:95], v[100:103], v[210:213], v[92:95]
	v_mfma_f32_16x16x32_bf16 v[88:91], v[112:115], v[210:213], v[88:91]
	v_mfma_f32_16x16x32_bf16 v[76:79], v[100:103], v[218:221], v[76:79]
	v_mfma_f32_16x16x32_bf16 v[72:75], v[112:115], v[218:221], v[72:75]
	v_mfma_f32_16x16x32_bf16 v[140:143], v[104:107], v[194:197], v[140:143]
	v_mfma_f32_16x16x32_bf16 v[136:139], v[116:119], v[194:197], v[136:139]
	v_mfma_f32_16x16x32_bf16 v[124:127], v[104:107], v[206:209], v[124:127]
	v_mfma_f32_16x16x32_bf16 v[120:123], v[116:119], v[206:209], v[120:123]
	v_mfma_f32_16x16x32_bf16 v[92:95], v[104:107], v[214:217], v[92:95]
	v_mfma_f32_16x16x32_bf16 v[88:91], v[116:119], v[214:217], v[88:91]
	v_mfma_f32_16x16x32_bf16 v[76:79], v[104:107], v[222:225], v[76:79]
	v_mfma_f32_16x16x32_bf16 v[72:75], v[116:119], v[222:225], v[72:75]
	s_setprio 0
	s_setprio 1
	v_mfma_f32_16x16x32_bf16 v[132:135], v[156:159], v[190:193], v[132:135]
	v_mfma_f32_16x16x32_bf16 v[128:131], v[182:185], v[190:193], v[128:131]
	v_mfma_f32_16x16x32_bf16 v[108:111], v[156:159], v[202:205], v[108:111]
	v_mfma_f32_16x16x32_bf16 v[96:99], v[182:185], v[202:205], v[96:99]
	v_mfma_f32_16x16x32_bf16 v[84:87], v[156:159], v[210:213], v[84:87]
	v_mfma_f32_16x16x32_bf16 v[80:83], v[182:185], v[210:213], v[80:83]
	v_mfma_f32_16x16x32_bf16 v[68:71], v[156:159], v[218:221], v[68:71]
	v_mfma_f32_16x16x32_bf16 v[64:67], v[182:185], v[218:221], v[64:67]
	v_mfma_f32_16x16x32_bf16 v[132:135], v[178:181], v[194:197], v[132:135]
	v_mfma_f32_16x16x32_bf16 v[128:131], v[186:189], v[194:197], v[128:131]
	v_mfma_f32_16x16x32_bf16 v[108:111], v[178:181], v[206:209], v[108:111]
	v_mfma_f32_16x16x32_bf16 v[96:99], v[186:189], v[206:209], v[96:99]
	v_mfma_f32_16x16x32_bf16 v[84:87], v[178:181], v[214:217], v[84:87]
	v_mfma_f32_16x16x32_bf16 v[80:83], v[186:189], v[214:217], v[80:83]
	v_mfma_f32_16x16x32_bf16 v[68:71], v[178:181], v[222:225], v[68:71]
	v_mfma_f32_16x16x32_bf16 v[64:67], v[186:189], v[222:225], v[64:67]
	s_setprio 0
	s_barrier
	s_add_i32 s56, s47, s41
	v_lshl_add_u64 v[198:199], s[36:37], 0, v[144:145]
	s_mov_b32 m0, s56
	ds_read_b128 v[190:193], v177 offset:16384
	ds_read_b128 v[194:197], v177 offset:17408
	ds_read_b128 v[202:205], v177 offset:18432
	ds_read_b128 v[206:209], v177 offset:19456
	ds_read_b128 v[210:213], v177 offset:20480
	ds_read_b128 v[214:217], v177 offset:21504
	ds_read_b128 v[218:221], v177 offset:22528
	ds_read_b128 v[222:225], v177 offset:23552
	global_load_lds_dwordx4 v[198:199], off
	s_add_i32 m0, s56, 0x2000
	s_add_u32 s56, s36, 0x40000
	v_lshl_add_u64 v[226:227], s[36:37], 0, v[146:147]
	s_addc_u32 s57, s37, 0
	s_add_i32 s58, s48, s41
	global_load_lds_dwordx4 v[226:227], off
	s_mov_b32 m0, s58
	v_lshl_add_u64 v[230:231], s[38:39], 0, v[150:151]
	global_load_lds_dwordx4 v144, s[56:57]
	s_add_i32 m0, s58, 0x2000
	s_nop 0
	global_load_lds_dwordx4 v146, s[56:57]
	v_lshl_add_u64 v[228:229], s[38:39], 0, v[148:149]
	s_mov_b32 m0, s31
	s_nop 0
	global_load_lds_dwordx4 v[228:229], off
	s_mov_b32 m0, s42
	s_nop 0
	global_load_lds_dwordx4 v[230:231], off
	s_waitcnt vmcnt(8)
	s_waitcnt lgkmcnt(0)
	s_barrier
; #define PG8_STAGE(bufoff, gbase, voff) do { _Pragma("unroll") for (int _i = 0; _i < 2; ++_i) \
;         __builtin_amdgcn_global_load_lds((const unsigned*)((const char*)(gbase) + (voff)[_i]), (PG8_LAS unsigned*)(lds + (bufoff) + ldsw + _i * 8192), 16, 0, 0); } while (0)
; #define PG8_LDA(dst, b, h) do { _Pragma("unroll") for (int m = 0; m < 4; ++m) _Pragma("unroll") for (int k = 0; k < 2; ++k) dst[m][k] = *(const PG8_LAS bf16x8*)(lds + PG8_SA(b, h) + aoff + m * 2048 + k * 1024); } while (0)
; #define PG8_LDB(dst, b, h) do { _Pragma("unroll") for (int n = 0; n < 2; ++n) _Pragma("unroll") for (int k = 0; k < 2; ++k) dst[n][k] = *(const PG8_LAS bf16x8*)(lds + PG8_SB(b, h) + boff + n * 2048 + k * 1024); } while (0)
; #define PG8_MMA(ai, bj, At, Bt) do { __builtin_amdgcn_s_setprio(1); _Pragma("unroll") for (int m = 0; m < 4; ++m) _Pragma("unroll") for (int n = 0; n < 2; ++n) _Pragma("unroll") for (int k = 0; k < 2; ++k) \
;         acc[ai][bj][m][n] = __builtin_amdgcn_mfma_f32_16x16x32_bf16(Bt[n][k], At[m][k], acc[ai][bj][m][n], 0, 0, 0); __builtin_amdgcn_s_setprio(0); } while (0)
; #define PG8_WAIT_V(n) asm volatile("s_waitcnt vmcnt(" #n ")" ::: "memory")
; #define PG8_WAIT_L(n) asm volatile("s_waitcnt lgkmcnt(" #n ")" ::: "memory")
; #define PG8_BAR __builtin_amdgcn_s_barrier()
; #define PG8_SCHED __builtin_amdgcn_sched_barrier(0)
; template <class Epi, class Sched, bool ALIGN_EPI = false, bool SP2 = false>
; __device__ __forceinline__ void gemm_phase(PG8_LAS unsigned char* lds, const Gemm g, const Sched& S, const Epi& E) {
;     ...
;             PG8_WAIT_V(8); PG8_WAIT_L(0); PG8_BAR; PG8_MMA(1, 0, At, B0); PG8_MMA(1, 1, At, B1); PG8_BAR; PG8_SCHED;
;             PG8_LDB(B0, 1, 0); PG8_LDB(B1, 1, 1); PG8_SCHED; PG8_LDA(At, 1, 0); PG8_STAGE(PG8_SA(0, 1), a2 + hstepA, voffA);
;             PG8_WAIT_V(8); PG8_WAIT_L(0); PG8_BAR; PG8_MMA(0, 0, At, B0); PG8_MMA(0, 1, At, B1); PG8_BAR; PG8_SCHED;
	s_setprio 1
	s_waitcnt lgkmcnt(0)
	v_mfma_f32_16x16x32_bf16 v[60:63], v[100:103], v[190:193], v[60:63]
	v_mfma_f32_16x16x32_bf16 v[56:59], v[112:115], v[190:193], v[56:59]
	v_mfma_f32_16x16x32_bf16 v[44:47], v[100:103], v[202:205], v[44:47]
	v_mfma_f32_16x16x32_bf16 v[40:43], v[112:115], v[202:205], v[40:43]
	v_mfma_f32_16x16x32_bf16 v[28:31], v[100:103], v[210:213], v[28:31]
	v_mfma_f32_16x16x32_bf16 v[24:27], v[112:115], v[210:213], v[24:27]
	v_mfma_f32_16x16x32_bf16 v[12:15], v[100:103], v[218:221], v[12:15]
	v_mfma_f32_16x16x32_bf16 v[8:11], v[112:115], v[218:221], v[8:11]
	v_mfma_f32_16x16x32_bf16 v[60:63], v[104:107], v[194:197], v[60:63]
	v_mfma_f32_16x16x32_bf16 v[56:59], v[116:119], v[194:197], v[56:59]
	v_mfma_f32_16x16x32_bf16 v[44:47], v[104:107], v[206:209], v[44:47]
	v_mfma_f32_16x16x32_bf16 v[40:43], v[116:119], v[206:209], v[40:43]
	v_mfma_f32_16x16x32_bf16 v[28:31], v[104:107], v[214:217], v[28:31]
	v_mfma_f32_16x16x32_bf16 v[24:27], v[116:119], v[214:217], v[24:27]
	v_mfma_f32_16x16x32_bf16 v[12:15], v[104:107], v[222:225], v[12:15]
	v_mfma_f32_16x16x32_bf16 v[8:11], v[116:119], v[222:225], v[8:11]
	s_setprio 0
	s_setprio 1
	v_mfma_f32_16x16x32_bf16 v[52:55], v[156:159], v[190:193], v[52:55]
	v_mfma_f32_16x16x32_bf16 v[48:51], v[182:185], v[190:193], v[48:51]
	v_mfma_f32_16x16x32_bf16 v[36:39], v[156:159], v[202:205], v[36:39]
	v_mfma_f32_16x16x32_bf16 v[32:35], v[182:185], v[202:205], v[32:35]
	v_mfma_f32_16x16x32_bf16 v[20:23], v[156:159], v[210:213], v[20:23]
	v_mfma_f32_16x16x32_bf16 v[16:19], v[182:185], v[210:213], v[16:19]
	v_mfma_f32_16x16x32_bf16 v[4:7], v[156:159], v[218:221], v[4:7]
	v_mfma_f32_16x16x32_bf16 v[0:3], v[182:185], v[218:221], v[0:3]
	v_mfma_f32_16x16x32_bf16 v[52:55], v[178:181], v[194:197], v[52:55]
	v_mfma_f32_16x16x32_bf16 v[48:51], v[186:189], v[194:197], v[48:51]
	v_mfma_f32_16x16x32_bf16 v[36:39], v[178:181], v[206:209], v[36:39]
	v_mfma_f32_16x16x32_bf16 v[32:35], v[186:189], v[206:209], v[32:35]
	v_mfma_f32_16x16x32_bf16 v[20:23], v[178:181], v[214:217], v[20:23]
	v_mfma_f32_16x16x32_bf16 v[16:19], v[186:189], v[214:217], v[16:19]
	v_mfma_f32_16x16x32_bf16 v[4:7], v[178:181], v[222:225], v[4:7]
	v_mfma_f32_16x16x32_bf16 v[0:3], v[186:189], v[222:225], v[0:3]
	s_setprio 0
	s_barrier
	s_add_i32 s56, 0, 0x18000
	s_add_i32 s57, 0, 0x1c000
	v_add_u32_e32 v116, s56, v172
	v_add_u32_e32 v186, s57, v172
	ds_read_b128 v[100:103], v116
	ds_read_b128 v[104:107], v116 offset:1024
	ds_read_b128 v[112:115], v116 offset:2048
	ds_read_b128 v[116:119], v116 offset:3072
	ds_read_b128 v[156:159], v186
	ds_read_b128 v[178:181], v186 offset:1024
	ds_read_b128 v[182:185], v186 offset:2048
	ds_read_b128 v[186:189], v186 offset:3072
	s_add_u32 s38, s38, 0x40000
	s_addc_u32 s39, s39, 0
	s_mov_b32 m0, s43
	ds_read_b128 v[190:193], v177 offset:32768
	ds_read_b128 v[194:197], v177 offset:33792
	ds_read_b128 v[202:205], v177 offset:34816
	ds_read_b128 v[206:209], v177 offset:35840
	ds_read_b128 v[210:213], v177 offset:36864
	ds_read_b128 v[214:217], v177 offset:37888
	ds_read_b128 v[218:221], v177 offset:38912
	ds_read_b128 v[222:225], v177 offset:39936
	global_load_lds_dwordx4 v148, s[38:39]
	v_lshl_add_u64 v[232:233], s[38:39], 0, v[150:151]
	s_mov_b32 m0, s44
	s_nop 0
	global_load_lds_dwordx4 v[232:233], off
	s_waitcnt vmcnt(8)
	s_waitcnt lgkmcnt(0)
	s_barrier
	s_setprio 1
	s_waitcnt lgkmcnt(0)
	v_mfma_f32_16x16x32_bf16 v[140:143], v[100:103], v[190:193], v[140:143]
	v_mfma_f32_16x16x32_bf16 v[136:139], v[112:115], v[190:193], v[136:139]
	v_mfma_f32_16x16x32_bf16 v[124:127], v[100:103], v[202:205], v[124:127]
	v_mfma_f32_16x16x32_bf16 v[120:123], v[112:115], v[202:205], v[120:123]
	v_mfma_f32_16x16x32_bf16 v[92:95], v[100:103], v[210:213], v[92:95]
	v_mfma_f32_16x16x32_bf16 v[88:91], v[112:115], v[210:213], v[88:91]
	v_mfma_f32_16x16x32_bf16 v[76:79], v[100:103], v[218:221], v[76:79]
	v_mfma_f32_16x16x32_bf16 v[72:75], v[112:115], v[218:221], v[72:75]
	v_mfma_f32_16x16x32_bf16 v[140:143], v[104:107], v[194:197], v[140:143]
	v_mfma_f32_16x16x32_bf16 v[136:139], v[116:119], v[194:197], v[136:139]
	v_mfma_f32_16x16x32_bf16 v[124:127], v[104:107], v[206:209], v[124:127]
	v_mfma_f32_16x16x32_bf16 v[120:123], v[116:119], v[206:209], v[120:123]
	v_mfma_f32_16x16x32_bf16 v[92:95], v[104:107], v[214:217], v[92:95]
	v_mfma_f32_16x16x32_bf16 v[88:91], v[116:119], v[214:217], v[88:91]
	v_mfma_f32_16x16x32_bf16 v[76:79], v[104:107], v[222:225], v[76:79]
	v_mfma_f32_16x16x32_bf16 v[72:75], v[116:119], v[222:225], v[72:75]
	s_setprio 0
	s_setprio 1
	v_mfma_f32_16x16x32_bf16 v[132:135], v[156:159], v[190:193], v[132:135]
	v_mfma_f32_16x16x32_bf16 v[128:131], v[182:185], v[190:193], v[128:131]
	v_mfma_f32_16x16x32_bf16 v[108:111], v[156:159], v[202:205], v[108:111]
	v_mfma_f32_16x16x32_bf16 v[96:99], v[182:185], v[202:205], v[96:99]
	v_mfma_f32_16x16x32_bf16 v[84:87], v[156:159], v[210:213], v[84:87]
	v_mfma_f32_16x16x32_bf16 v[80:83], v[182:185], v[210:213], v[80:83]
	v_mfma_f32_16x16x32_bf16 v[68:71], v[156:159], v[218:221], v[68:71]
	v_mfma_f32_16x16x32_bf16 v[64:67], v[182:185], v[218:221], v[64:67]
	v_mfma_f32_16x16x32_bf16 v[132:135], v[178:181], v[194:197], v[132:135]
	v_mfma_f32_16x16x32_bf16 v[128:131], v[186:189], v[194:197], v[128:131]
	v_mfma_f32_16x16x32_bf16 v[108:111], v[178:181], v[206:209], v[108:111]
	v_mfma_f32_16x16x32_bf16 v[96:99], v[186:189], v[206:209], v[96:99]
	v_mfma_f32_16x16x32_bf16 v[84:87], v[178:181], v[214:217], v[84:87]
	v_mfma_f32_16x16x32_bf16 v[80:83], v[186:189], v[214:217], v[80:83]
	v_mfma_f32_16x16x32_bf16 v[68:71], v[178:181], v[222:225], v[68:71]
	v_mfma_f32_16x16x32_bf16 v[64:67], v[186:189], v[222:225], v[64:67]
	s_setprio 0
	s_barrier
; #define PG8_STAGE(bufoff, gbase, voff) do { _Pragma("unroll") for (int _i = 0; _i < 2; ++_i) \
;         __builtin_amdgcn_global_load_lds((const unsigned*)((const char*)(gbase) + (voff)[_i]), (PG8_LAS unsigned*)(lds + (bufoff) + ldsw + _i * 8192), 16, 0, 0); } while (0)
; #define PG8_LDA(dst, b, h) do { _Pragma("unroll") for (int m = 0; m < 4; ++m) _Pragma("unroll") for (int k = 0; k < 2; ++k) dst[m][k] = *(const PG8_LAS bf16x8*)(lds + PG8_SA(b, h) + aoff + m * 2048 + k * 1024); } while (0)
; #define PG8_MMA(ai, bj, At, Bt) do { __builtin_amdgcn_s_setprio(1); _Pragma("unroll") for (int m = 0; m < 4; ++m) _Pragma("unroll") for (int n = 0; n < 2; ++n) _Pragma("unroll") for (int k = 0; k < 2; ++k) \
;         acc[ai][bj][m][n] = __builtin_amdgcn_mfma_f32_16x16x32_bf16(Bt[n][k], At[m][k], acc[ai][bj][m][n], 0, 0, 0); __builtin_amdgcn_s_setprio(0); } while (0)
; #define PG8_WAIT_V(n) asm volatile("s_waitcnt vmcnt(" #n ")" ::: "memory")
; #define PG8_WAIT_L(n) asm volatile("s_waitcnt lgkmcnt(" #n ")" ::: "memory")
; #define PG8_BAR __builtin_amdgcn_s_barrier()
; #define PG8_SCHED __builtin_amdgcn_sched_barrier(0)
; template <class Epi, class Sched, bool ALIGN_EPI = false, bool SP2 = false>
; __device__ __forceinline__ void gemm_phase(PG8_LAS unsigned char* lds, const Gemm g, const Sched& S, const Epi& E) {
;     ...
;         for (int t = 0; t < nt; t += 2) {
;     ...
;             PG8_LDA(At, 1, 1); PG8_STAGE(PG8_SB(1, 0), b3, voffB); PG8_STAGE(PG8_SB(1, 1), b3 + hstepB, voffB); PG8_STAGE(PG8_SA(1, 0), a3, voffA);
;             PG8_WAIT_V(8); PG8_WAIT_L(0); PG8_BAR; PG8_MMA(1, 0, At, B0); PG8_MMA(1, 1, At, B1); PG8_BAR; PG8_SCHED;
	s_add_i32 s38, s56, s41
	v_lshl_add_u64 v[198:199], v[198:199], 0, s[18:19]
	s_mov_b32 m0, s38
	ds_read_b128 v[190:193], v177 offset:49152
	ds_read_b128 v[194:197], v177 offset:50176
	ds_read_b128 v[202:205], v177 offset:51200
	ds_read_b128 v[206:209], v177 offset:52224
	ds_read_b128 v[210:213], v177 offset:53248
	ds_read_b128 v[214:217], v177 offset:54272
	ds_read_b128 v[218:221], v177 offset:55296
	ds_read_b128 v[222:225], v177 offset:56320
	global_load_lds_dwordx4 v[198:199], off
	s_add_i32 m0, s38, 0x2000
	s_add_u32 s36, s36, 0x40080
	v_lshl_add_u64 v[198:199], v[226:227], 0, s[18:19]
	s_addc_u32 s37, s37, 0
	s_add_i32 s38, s57, s41
	global_load_lds_dwordx4 v[198:199], off
	s_mov_b32 m0, s38
	s_nop 0
	global_load_lds_dwordx4 v144, s[36:37]
	s_add_i32 m0, s38, 0x2000
	s_nop 0
	global_load_lds_dwordx4 v146, s[36:37]
	v_lshl_add_u64 v[198:199], v[228:229], 0, s[18:19]
	s_mov_b32 m0, s45
	s_nop 0
	global_load_lds_dwordx4 v[198:199], off
	v_lshl_add_u64 v[198:199], v[230:231], 0, s[18:19]
	s_mov_b32 m0, s46
	s_nop 0
	global_load_lds_dwordx4 v[198:199], off
	s_waitcnt vmcnt(8)
	s_waitcnt lgkmcnt(0)
	s_barrier
	s_setprio 1
	s_waitcnt lgkmcnt(0)
	v_mfma_f32_16x16x32_bf16 v[60:63], v[100:103], v[190:193], v[60:63]
	v_mfma_f32_16x16x32_bf16 v[56:59], v[112:115], v[190:193], v[56:59]
	v_mfma_f32_16x16x32_bf16 v[44:47], v[100:103], v[202:205], v[44:47]
	v_mfma_f32_16x16x32_bf16 v[40:43], v[112:115], v[202:205], v[40:43]
	v_mfma_f32_16x16x32_bf16 v[28:31], v[100:103], v[210:213], v[28:31]
	v_mfma_f32_16x16x32_bf16 v[24:27], v[112:115], v[210:213], v[24:27]
	v_mfma_f32_16x16x32_bf16 v[12:15], v[100:103], v[218:221], v[12:15]
	v_mfma_f32_16x16x32_bf16 v[8:11], v[112:115], v[218:221], v[8:11]
	v_mfma_f32_16x16x32_bf16 v[60:63], v[104:107], v[194:197], v[60:63]
	v_mfma_f32_16x16x32_bf16 v[56:59], v[116:119], v[194:197], v[56:59]
	v_mfma_f32_16x16x32_bf16 v[44:47], v[104:107], v[206:209], v[44:47]
	v_mfma_f32_16x16x32_bf16 v[40:43], v[116:119], v[206:209], v[40:43]
	v_mfma_f32_16x16x32_bf16 v[28:31], v[104:107], v[214:217], v[28:31]
	v_mfma_f32_16x16x32_bf16 v[24:27], v[116:119], v[214:217], v[24:27]
	v_mfma_f32_16x16x32_bf16 v[12:15], v[104:107], v[222:225], v[12:15]
	v_mfma_f32_16x16x32_bf16 v[8:11], v[116:119], v[222:225], v[8:11]
	s_setprio 0
	s_setprio 1
	v_mfma_f32_16x16x32_bf16 v[52:55], v[156:159], v[190:193], v[52:55]
	v_mfma_f32_16x16x32_bf16 v[48:51], v[182:185], v[190:193], v[48:51]
	v_mfma_f32_16x16x32_bf16 v[36:39], v[156:159], v[202:205], v[36:39]
	v_mfma_f32_16x16x32_bf16 v[32:35], v[182:185], v[202:205], v[32:35]
	v_mfma_f32_16x16x32_bf16 v[20:23], v[156:159], v[210:213], v[20:23]
	v_mfma_f32_16x16x32_bf16 v[16:19], v[182:185], v[210:213], v[16:19]
	v_mfma_f32_16x16x32_bf16 v[4:7], v[156:159], v[218:221], v[4:7]
	v_mfma_f32_16x16x32_bf16 v[0:3], v[182:185], v[218:221], v[0:3]
	v_mfma_f32_16x16x32_bf16 v[52:55], v[178:181], v[194:197], v[52:55]
	v_mfma_f32_16x16x32_bf16 v[48:51], v[186:189], v[194:197], v[48:51]
	v_mfma_f32_16x16x32_bf16 v[36:39], v[178:181], v[206:209], v[36:39]
	v_mfma_f32_16x16x32_bf16 v[32:35], v[186:189], v[206:209], v[32:35]
	v_mfma_f32_16x16x32_bf16 v[20:23], v[178:181], v[214:217], v[20:23]
	v_mfma_f32_16x16x32_bf16 v[16:19], v[186:189], v[214:217], v[16:19]
	v_mfma_f32_16x16x32_bf16 v[4:7], v[178:181], v[222:225], v[4:7]
	v_mfma_f32_16x16x32_bf16 v[0:3], v[186:189], v[222:225], v[0:3]
	s_setprio 0
	s_barrier
	s_add_i32 s55, s55, 2
	s_add_u32 s34, s34, 0x100
	s_addc_u32 s35, s35, 0
	s_add_u32 s53, s53, 0x100
	s_addc_u32 s54, s54, 0
	s_cmp_gt_u32 s55, 13
	s_cbranch_scc0 .LBB0_490
	s_and_b64 vcc, exec, s[20:21]
	s_cbranch_vccz .LBB0_493
	s_barrier

;     __device__ __forceinline__ size_t boff(const Unit& u, size_t tstepB) const { return (size_t)u.pn * tstepB; }
; #define PG8_STAGE(bufoff, gbase, voff) do { _Pragma("unroll") for (int _i = 0; _i < 2; ++_i) \
;         __builtin_amdgcn_global_load_lds((const unsigned*)((const char*)(gbase) + (voff)[_i]), (PG8_LAS unsigned*)(lds + (bufoff) + ldsw + _i * 8192), 16, 0, 0); } while (0)
; #define PG8_WAIT_V(n) asm volatile("s_waitcnt vmcnt(" #n ")" ::: "memory")
; #define PG8_BAR __builtin_amdgcn_s_barrier()
; template <class Epi, class Sched, bool ALIGN_EPI = false, bool SP2 = false>
; __device__ __forceinline__ void gemm_phase(PG8_LAS unsigned char* lds, const Gemm g, const Sched& S, const Epi& E) {
;     const int tid = threadIdx.x, wid = __builtin_amdgcn_readfirstlane(tid >> 6), lane = tid & 63, wr = wid >> 2, wc = wid & 3, fr = lane & 15, fq = lane >> 4;
;     const int K = g.K, nt = K / BK;
;     unsigned voffA[2], voffB[2];
; #pragma unroll
;     for (int i = 0; i < 2; ++i) { int R, C; stage_rc(tid * 16 + i * 8192, R, C); const int Rb = Epi::PERM ? ((R & ~31) + perm32(R & 31)) : R;
;         voffA[i] = (unsigned)(R * g.lda + C) * 2u; voffB[i] = (unsigned)(Rb * g.ldb + C) * 2u; }
;     const size_t kstep = (size_t)(BK * 2);
;     const size_t hstepA = (size_t)HALF * g.lda * 2, hstepB = (size_t)HALF * g.ldb * 2;
;     const size_t tstepA = (size_t)g.arows * g.lda * 2, tstepB = 2 * hstepB;
;     const unsigned ldsw = (unsigned)wid * 1024u;
;     const int aoff = lds_byte(wr * 64 + fr, fq * 8), boff = lds_byte(wc * 32 + fr, fq * 8);
;     ...
;         PG8_STAGE(PG8_SB(0, 0), cB, voffB); PG8_STAGE(PG8_SB(0, 1), cB + hstepB, voffB); PG8_STAGE(PG8_SA(0, 0), cA, voffA); PG8_STAGE(PG8_SA(0, 1), cA + hstepA, voffA);
;         if (wr == 1) PG8_BAR;
;         PG8_WAIT_V(2); PG8_BAR;
;         PG8_STAGE(PG8_SB(1, 0), cB + kstep, voffB); PG8_STAGE(PG8_SA(1, 0), cA + kstep, voffA); PG8_STAGE(PG8_SB(1, 1), cB + hstepB + kstep, voffB);
;         PG8_WAIT_V(6); PG8_BAR;
.LBB0_504:
	s_mov_b64 s[18:19], 0x80
	s_lshl_b32 s5, s5, 5
	s_add_i32 m0, s37, 0x18000
	v_lshl_add_u64 v[6:7], v[6:7], 0, s[18:19]
	s_lshl_b32 s22, s3, 13
	s_and_b32 s5, s5, 0x60
	s_waitcnt vmcnt(2)
	s_barrier
	global_load_lds_dwordx4 v[6:7], off
	v_lshl_add_u64 v[4:5], v[4:5], 0, s[18:19]
	s_add_i32 m0, s37, 0x1a000
	s_add_i32 s42, s37, 0x8000
	s_add_i32 s43, s37, 0xa000
	global_load_lds_dwordx4 v[4:5], off
	v_lshl_add_u64 v[0:1], v[0:1], 0, s[18:19]
	s_mov_b32 m0, s42
	s_add_u32 s20, s28, 0x40080
	global_load_lds_dwordx4 v[0:1], off
	v_lshl_add_u64 v[0:1], v[2:3], 0, s[18:19]
	s_mov_b32 m0, s43
	s_addc_u32 s21, s29, 0
	global_load_lds_dwordx4 v[0:1], off
	s_add_i32 m0, s37, 0x1c000
	global_load_lds_dwordx4 v144, s[20:21]
	v_lshl_add_u64 v[0:1], s[20:21], 0, v[146:147]
	s_add_i32 m0, s37, 0x1e000
	s_cmpk_lt_u32 s4, 0x100
	global_load_lds_dwordx4 v[0:1], off
	v_lshlrev_b32_e32 v1, 2, v163
	v_lshl_or_b32 v0, v163, 6, v164
	v_and_b32_e32 v1, 32, v1
	s_waitcnt vmcnt(6)
	v_bitop3_b32 v0, v0, s22, v1 bitop3:0xde
	v_lshl_or_b32 v151, s5, 7, v165
	s_cselect_b64 s[20:21], -1, 0
	s_add_i32 s45, 0, 0x10000
	s_add_i32 s46, 0, 0x14000
	s_sext_i32_i8 s50, s2
	v_lshl_or_b32 v150, s3, 6, v163
	s_ashr_i32 s44, s90, 31
	v_or_b32_e32 v152, s5, v162
	v_add3_u32 v132, v154, v160, v161
	v_mov_b32_e32 v133, v145
	v_add3_u32 v134, v153, v160, v161
	v_mov_b32_e32 v135, v145
	v_mov_b64_e32 v[136:137], 0x100
	v_mov_b64_e32 v[138:139], 0xff
	v_add_u32_e32 v155, s45, v151
	v_add_u32_e32 v156, s46, v151
	v_add_u32_e32 v157, 0, v0
	s_movk_i32 s47, 0x3400
	s_barrier
	s_branch .LBB0_507

; #define PG8_STAGE(bufoff, gbase, voff) do { _Pragma("unroll") for (int _i = 0; _i < 2; ++_i) \
;         __builtin_amdgcn_global_load_lds((const unsigned*)((const char*)(gbase) + (voff)[_i]), (PG8_LAS unsigned*)(lds + (bufoff) + ldsw + _i * 8192), 16, 0, 0); } while (0)
; #define PG8_LDA(dst, b, h) do { _Pragma("unroll") for (int m = 0; m < 4; ++m) _Pragma("unroll") for (int k = 0; k < 2; ++k) dst[m][k] = *(const PG8_LAS bf16x8*)(lds + PG8_SA(b, h) + aoff + m * 2048 + k * 1024); } while (0)
; #define PG8_LDB(dst, b, h) do { _Pragma("unroll") for (int n = 0; n < 2; ++n) _Pragma("unroll") for (int k = 0; k < 2; ++k) dst[n][k] = *(const PG8_LAS bf16x8*)(lds + PG8_SB(b, h) + boff + n * 2048 + k * 1024); } while (0)
; #define PG8_MMA(ai, bj, At, Bt) do { __builtin_amdgcn_s_setprio(1); _Pragma("unroll") for (int m = 0; m < 4; ++m) _Pragma("unroll") for (int n = 0; n < 2; ++n) _Pragma("unroll") for (int k = 0; k < 2; ++k) \
;         acc[ai][bj][m][n] = __builtin_amdgcn_mfma_f32_16x16x32_bf16(Bt[n][k], At[m][k], acc[ai][bj][m][n], 0, 0, 0); __builtin_amdgcn_s_setprio(0); } while (0)
; #define PG8_WAIT_V(n) asm volatile("s_waitcnt vmcnt(" #n ")" ::: "memory")
; #define PG8_WAIT_L(n) asm volatile("s_waitcnt lgkmcnt(" #n ")" ::: "memory")
; #define PG8_BAR __builtin_amdgcn_s_barrier()
; #define PG8_SCHED __builtin_amdgcn_sched_barrier(0)
; template <class Epi, class Sched, bool ALIGN_EPI = false, bool SP2 = false>
; __device__ __forceinline__ void gemm_phase(PG8_LAS unsigned char* lds, const Gemm g, const Sched& S, const Epi& E) {
;     ...
;             PG8_LDB(B0, 0, 0); PG8_LDB(B1, 0, 1); PG8_SCHED; PG8_LDA(At, 0, 0); PG8_STAGE(PG8_SA(1, 1), a1 + hstepA, voffA);
;             PG8_WAIT_V(8); PG8_WAIT_L(0); PG8_BAR; PG8_MMA(0, 0, At, B0); PG8_MMA(0, 1, At, B1); PG8_BAR; PG8_SCHED;
;             PG8_LDA(At, 0, 1); PG8_STAGE(PG8_SB(0, 0), b2, voffB); PG8_STAGE(PG8_SB(0, 1), b2 + hstepB, voffB); PG8_STAGE(PG8_SA(0, 0), a2, voffA);
;             PG8_WAIT_V(8); PG8_WAIT_L(0); PG8_BAR; PG8_MMA(1, 0, At, B0); PG8_MMA(1, 1, At, B1); PG8_BAR; PG8_SCHED;
.LBB0_516:
	ds_read_b128 v[140:143], v155
	ds_read_b128 v[170:173], v155 offset:1024
	ds_read_b128 v[178:181], v155 offset:2048
	ds_read_b128 v[182:185], v155 offset:3072
	ds_read_b128 v[186:189], v156
	ds_read_b128 v[190:193], v156 offset:1024
	ds_read_b128 v[194:197], v156 offset:2048
	ds_read_b128 v[202:205], v156 offset:3072
	s_add_u32 s28, s4, 0xffe60080
	s_addc_u32 s29, s5, -1
	s_cmp_eq_u32 s54, 12
	s_cselect_b32 s31, s25, s29
	s_cselect_b32 s30, s24, s28
	s_cselect_b32 s29, s23, s53
	s_cselect_b32 s28, s51, s52
	s_add_i32 m0, s37, 0xc000
	ds_read_b128 v[206:209], v157
	ds_read_b128 v[210:213], v157 offset:1024
	ds_read_b128 v[214:217], v157 offset:2048
	ds_read_b128 v[218:221], v157 offset:3072
	ds_read_b128 v[222:225], v157 offset:4096
	ds_read_b128 v[226:229], v157 offset:5120
	ds_read_b128 v[230:233], v157 offset:6144
	ds_read_b128 v[234:237], v157 offset:7168
	global_load_lds_dwordx4 v132, s[4:5]
	s_add_i32 m0, s37, 0xe000
	s_nop 0
	global_load_lds_dwordx4 v134, s[4:5]
	s_waitcnt vmcnt(8)
	s_waitcnt lgkmcnt(0)
	s_barrier
	s_setprio 1
	s_waitcnt lgkmcnt(0)
	v_mfma_f32_16x16x32_bf16 v[124:127], v[140:143], v[206:209], v[124:127]
	v_mfma_f32_16x16x32_bf16 v[120:123], v[178:181], v[206:209], v[120:123]
	v_mfma_f32_16x16x32_bf16 v[108:111], v[140:143], v[214:217], v[108:111]
	v_mfma_f32_16x16x32_bf16 v[104:107], v[178:181], v[214:217], v[104:107]
	v_mfma_f32_16x16x32_bf16 v[92:95], v[140:143], v[222:225], v[92:95]
	v_mfma_f32_16x16x32_bf16 v[88:91], v[178:181], v[222:225], v[88:91]
	v_mfma_f32_16x16x32_bf16 v[76:79], v[140:143], v[230:233], v[76:79]
	v_mfma_f32_16x16x32_bf16 v[72:75], v[178:181], v[230:233], v[72:75]
	v_mfma_f32_16x16x32_bf16 v[124:127], v[170:173], v[210:213], v[124:127]
	v_mfma_f32_16x16x32_bf16 v[120:123], v[182:185], v[210:213], v[120:123]
	v_mfma_f32_16x16x32_bf16 v[108:111], v[170:173], v[218:221], v[108:111]
	v_mfma_f32_16x16x32_bf16 v[104:107], v[182:185], v[218:221], v[104:107]
	v_mfma_f32_16x16x32_bf16 v[92:95], v[170:173], v[226:229], v[92:95]
	v_mfma_f32_16x16x32_bf16 v[88:91], v[182:185], v[226:229], v[88:91]
	v_mfma_f32_16x16x32_bf16 v[76:79], v[170:173], v[234:237], v[76:79]
	v_mfma_f32_16x16x32_bf16 v[72:75], v[182:185], v[234:237], v[72:75]
	s_setprio 0
	s_setprio 1
	v_mfma_f32_16x16x32_bf16 v[116:119], v[186:189], v[206:209], v[116:119]
	v_mfma_f32_16x16x32_bf16 v[112:115], v[194:197], v[206:209], v[112:115]
	v_mfma_f32_16x16x32_bf16 v[100:103], v[186:189], v[214:217], v[100:103]
	v_mfma_f32_16x16x32_bf16 v[96:99], v[194:197], v[214:217], v[96:99]
	v_mfma_f32_16x16x32_bf16 v[84:87], v[186:189], v[222:225], v[84:87]
	v_mfma_f32_16x16x32_bf16 v[80:83], v[194:197], v[222:225], v[80:83]
	v_mfma_f32_16x16x32_bf16 v[68:71], v[186:189], v[230:233], v[68:71]
	v_mfma_f32_16x16x32_bf16 v[64:67], v[194:197], v[230:233], v[64:67]
	v_mfma_f32_16x16x32_bf16 v[116:119], v[190:193], v[210:213], v[116:119]
	v_mfma_f32_16x16x32_bf16 v[112:115], v[202:205], v[210:213], v[112:115]
	v_mfma_f32_16x16x32_bf16 v[100:103], v[190:193], v[218:221], v[100:103]
	v_mfma_f32_16x16x32_bf16 v[96:99], v[202:205], v[218:221], v[96:99]
	v_mfma_f32_16x16x32_bf16 v[84:87], v[190:193], v[226:229], v[84:87]
	v_mfma_f32_16x16x32_bf16 v[80:83], v[202:205], v[226:229], v[80:83]
	v_mfma_f32_16x16x32_bf16 v[68:71], v[190:193], v[234:237], v[68:71]
	v_mfma_f32_16x16x32_bf16 v[64:67], v[202:205], v[234:237], v[64:67]
	s_setprio 0
	s_barrier
	s_add_i32 s55, s45, s36
	v_lshl_add_u64 v[148:149], s[28:29], 0, v[144:145]
	s_mov_b32 m0, s55
	ds_read_b128 v[206:209], v157 offset:16384
	ds_read_b128 v[210:213], v157 offset:17408
	ds_read_b128 v[214:217], v157 offset:18432
	ds_read_b128 v[218:221], v157 offset:19456
	ds_read_b128 v[222:225], v157 offset:20480
	ds_read_b128 v[226:229], v157 offset:21504
	ds_read_b128 v[230:233], v157 offset:22528
	ds_read_b128 v[234:237], v157 offset:23552
	global_load_lds_dwordx4 v[148:149], off
	s_add_i32 m0, s55, 0x2000
	s_add_u32 s56, s28, 0x40000
	v_lshl_add_u64 v[158:159], s[28:29], 0, v[146:147]
	s_addc_u32 s57, s29, 0
	s_add_i32 s55, s46, s36
	global_load_lds_dwordx4 v[158:159], off
	s_mov_b32 m0, s55
	v_lshl_add_u64 v[198:199], s[30:31], 0, v[130:131]
	global_load_lds_dwordx4 v144, s[56:57]
	s_add_i32 m0, s55, 0x2000
	s_nop 0
	global_load_lds_dwordx4 v146, s[56:57]
	v_lshl_add_u64 v[174:175], s[30:31], 0, v[128:129]
	s_mov_b32 m0, s37
	s_nop 0
	global_load_lds_dwordx4 v[174:175], off
	s_mov_b32 m0, s38
	s_nop 0
	global_load_lds_dwordx4 v[198:199], off
	s_waitcnt vmcnt(8)
	s_waitcnt lgkmcnt(0)
	s_barrier
; #define PG8_STAGE(bufoff, gbase, voff) do { _Pragma("unroll") for (int _i = 0; _i < 2; ++_i) \
;         __builtin_amdgcn_global_load_lds((const unsigned*)((const char*)(gbase) + (voff)[_i]), (PG8_LAS unsigned*)(lds + (bufoff) + ldsw + _i * 8192), 16, 0, 0); } while (0)
; #define PG8_LDA(dst, b, h) do { _Pragma("unroll") for (int m = 0; m < 4; ++m) _Pragma("unroll") for (int k = 0; k < 2; ++k) dst[m][k] = *(const PG8_LAS bf16x8*)(lds + PG8_SA(b, h) + aoff + m * 2048 + k * 1024); } while (0)
; #define PG8_LDB(dst, b, h) do { _Pragma("unroll") for (int n = 0; n < 2; ++n) _Pragma("unroll") for (int k = 0; k < 2; ++k) dst[n][k] = *(const PG8_LAS bf16x8*)(lds + PG8_SB(b, h) + boff + n * 2048 + k * 1024); } while (0)
; #define PG8_MMA(ai, bj, At, Bt) do { __builtin_amdgcn_s_setprio(1); _Pragma("unroll") for (int m = 0; m < 4; ++m) _Pragma("unroll") for (int n = 0; n < 2; ++n) _Pragma("unroll") for (int k = 0; k < 2; ++k) \
;         acc[ai][bj][m][n] = __builtin_amdgcn_mfma_f32_16x16x32_bf16(Bt[n][k], At[m][k], acc[ai][bj][m][n], 0, 0, 0); __builtin_amdgcn_s_setprio(0); } while (0)
; #define PG8_WAIT_V(n) asm volatile("s_waitcnt vmcnt(" #n ")" ::: "memory")
; #define PG8_WAIT_L(n) asm volatile("s_waitcnt lgkmcnt(" #n ")" ::: "memory")
; #define PG8_BAR __builtin_amdgcn_s_barrier()
; #define PG8_SCHED __builtin_amdgcn_sched_barrier(0)
; template <class Epi, class Sched, bool ALIGN_EPI = false, bool SP2 = false>
; __device__ __forceinline__ void gemm_phase(PG8_LAS unsigned char* lds, const Gemm g, const Sched& S, const Epi& E) {
;     ...
;             PG8_WAIT_V(8); PG8_WAIT_L(0); PG8_BAR; PG8_MMA(1, 0, At, B0); PG8_MMA(1, 1, At, B1); PG8_BAR; PG8_SCHED;
;             PG8_LDB(B0, 1, 0); PG8_LDB(B1, 1, 1); PG8_SCHED; PG8_LDA(At, 1, 0); PG8_STAGE(PG8_SA(0, 1), a2 + hstepA, voffA);
;             PG8_WAIT_V(8); PG8_WAIT_L(0); PG8_BAR; PG8_MMA(0, 0, At, B0); PG8_MMA(0, 1, At, B1); PG8_BAR; PG8_SCHED;
	s_setprio 1
	s_waitcnt lgkmcnt(0)
	v_mfma_f32_16x16x32_bf16 v[60:63], v[140:143], v[206:209], v[60:63]
	v_mfma_f32_16x16x32_bf16 v[56:59], v[178:181], v[206:209], v[56:59]
	v_mfma_f32_16x16x32_bf16 v[44:47], v[140:143], v[214:217], v[44:47]
	v_mfma_f32_16x16x32_bf16 v[40:43], v[178:181], v[214:217], v[40:43]
	v_mfma_f32_16x16x32_bf16 v[28:31], v[140:143], v[222:225], v[28:31]
	v_mfma_f32_16x16x32_bf16 v[24:27], v[178:181], v[222:225], v[24:27]
	v_mfma_f32_16x16x32_bf16 v[12:15], v[140:143], v[230:233], v[12:15]
	v_mfma_f32_16x16x32_bf16 v[8:11], v[178:181], v[230:233], v[8:11]
	v_mfma_f32_16x16x32_bf16 v[60:63], v[170:173], v[210:213], v[60:63]
	v_mfma_f32_16x16x32_bf16 v[56:59], v[182:185], v[210:213], v[56:59]
	v_mfma_f32_16x16x32_bf16 v[44:47], v[170:173], v[218:221], v[44:47]
	v_mfma_f32_16x16x32_bf16 v[40:43], v[182:185], v[218:221], v[40:43]
	v_mfma_f32_16x16x32_bf16 v[28:31], v[170:173], v[226:229], v[28:31]
	v_mfma_f32_16x16x32_bf16 v[24:27], v[182:185], v[226:229], v[24:27]
	v_mfma_f32_16x16x32_bf16 v[12:15], v[170:173], v[234:237], v[12:15]
	v_mfma_f32_16x16x32_bf16 v[8:11], v[182:185], v[234:237], v[8:11]
	s_setprio 0
	s_setprio 1
	v_mfma_f32_16x16x32_bf16 v[52:55], v[186:189], v[206:209], v[52:55]
	v_mfma_f32_16x16x32_bf16 v[48:51], v[194:197], v[206:209], v[48:51]
	v_mfma_f32_16x16x32_bf16 v[36:39], v[186:189], v[214:217], v[36:39]
	v_mfma_f32_16x16x32_bf16 v[32:35], v[194:197], v[214:217], v[32:35]
	v_mfma_f32_16x16x32_bf16 v[20:23], v[186:189], v[222:225], v[20:23]
	v_mfma_f32_16x16x32_bf16 v[16:19], v[194:197], v[222:225], v[16:19]
	v_mfma_f32_16x16x32_bf16 v[4:7], v[186:189], v[230:233], v[4:7]
	v_mfma_f32_16x16x32_bf16 v[0:3], v[194:197], v[230:233], v[0:3]
	v_mfma_f32_16x16x32_bf16 v[52:55], v[190:193], v[210:213], v[52:55]
	v_mfma_f32_16x16x32_bf16 v[48:51], v[202:205], v[210:213], v[48:51]
	v_mfma_f32_16x16x32_bf16 v[36:39], v[190:193], v[218:221], v[36:39]
	v_mfma_f32_16x16x32_bf16 v[32:35], v[202:205], v[218:221], v[32:35]
	v_mfma_f32_16x16x32_bf16 v[20:23], v[190:193], v[226:229], v[20:23]
	v_mfma_f32_16x16x32_bf16 v[16:19], v[202:205], v[226:229], v[16:19]
	v_mfma_f32_16x16x32_bf16 v[4:7], v[190:193], v[234:237], v[4:7]
	v_mfma_f32_16x16x32_bf16 v[0:3], v[202:205], v[234:237], v[0:3]
	s_setprio 0
	s_barrier
	s_add_i32 s55, 0, 0x18000
	v_add_u32_e32 v169, s55, v151
	s_add_i32 s56, 0, 0x1c000
	ds_read_b128 v[140:143], v169
	ds_read_b128 v[170:173], v169 offset:1024
	ds_read_b128 v[178:181], v169 offset:2048
	ds_read_b128 v[182:185], v169 offset:3072
	v_add_u32_e32 v169, s56, v151
	ds_read_b128 v[186:189], v169
	ds_read_b128 v[190:193], v169 offset:1024
	ds_read_b128 v[194:197], v169 offset:2048
	ds_read_b128 v[202:205], v169 offset:3072
	s_add_u32 s30, s30, 0x1a0000
	s_addc_u32 s31, s31, 0
	s_mov_b32 m0, s39
	ds_read_b128 v[206:209], v157 offset:32768
	ds_read_b128 v[210:213], v157 offset:33792
	ds_read_b128 v[214:217], v157 offset:34816
	ds_read_b128 v[218:221], v157 offset:35840
	ds_read_b128 v[222:225], v157 offset:36864
	ds_read_b128 v[226:229], v157 offset:37888
	ds_read_b128 v[230:233], v157 offset:38912
	ds_read_b128 v[234:237], v157 offset:39936
	global_load_lds_dwordx4 v128, s[30:31]
	v_lshl_add_u64 v[238:239], s[30:31], 0, v[130:131]
	s_mov_b32 m0, s40
	s_nop 0
	global_load_lds_dwordx4 v[238:239], off
	s_waitcnt vmcnt(8)
	s_waitcnt lgkmcnt(0)
	s_barrier
	s_setprio 1
	s_waitcnt lgkmcnt(0)
	v_mfma_f32_16x16x32_bf16 v[124:127], v[140:143], v[206:209], v[124:127]
	v_mfma_f32_16x16x32_bf16 v[120:123], v[178:181], v[206:209], v[120:123]
	v_mfma_f32_16x16x32_bf16 v[108:111], v[140:143], v[214:217], v[108:111]
	v_mfma_f32_16x16x32_bf16 v[104:107], v[178:181], v[214:217], v[104:107]
	v_mfma_f32_16x16x32_bf16 v[92:95], v[140:143], v[222:225], v[92:95]
	v_mfma_f32_16x16x32_bf16 v[88:91], v[178:181], v[222:225], v[88:91]
	v_mfma_f32_16x16x32_bf16 v[76:79], v[140:143], v[230:233], v[76:79]
	v_mfma_f32_16x16x32_bf16 v[72:75], v[178:181], v[230:233], v[72:75]
	v_mfma_f32_16x16x32_bf16 v[124:127], v[170:173], v[210:213], v[124:127]
	v_mfma_f32_16x16x32_bf16 v[120:123], v[182:185], v[210:213], v[120:123]
	v_mfma_f32_16x16x32_bf16 v[108:111], v[170:173], v[218:221], v[108:111]
	v_mfma_f32_16x16x32_bf16 v[104:107], v[182:185], v[218:221], v[104:107]
	v_mfma_f32_16x16x32_bf16 v[92:95], v[170:173], v[226:229], v[92:95]
	v_mfma_f32_16x16x32_bf16 v[88:91], v[182:185], v[226:229], v[88:91]
	v_mfma_f32_16x16x32_bf16 v[76:79], v[170:173], v[234:237], v[76:79]
	v_mfma_f32_16x16x32_bf16 v[72:75], v[182:185], v[234:237], v[72:75]
	s_setprio 0
	s_setprio 1
	v_mfma_f32_16x16x32_bf16 v[116:119], v[186:189], v[206:209], v[116:119]
	v_mfma_f32_16x16x32_bf16 v[112:115], v[194:197], v[206:209], v[112:115]
	v_mfma_f32_16x16x32_bf16 v[100:103], v[186:189], v[214:217], v[100:103]
	v_mfma_f32_16x16x32_bf16 v[96:99], v[194:197], v[214:217], v[96:99]
	v_mfma_f32_16x16x32_bf16 v[84:87], v[186:189], v[222:225], v[84:87]
	v_mfma_f32_16x16x32_bf16 v[80:83], v[194:197], v[222:225], v[80:83]
	v_mfma_f32_16x16x32_bf16 v[68:71], v[186:189], v[230:233], v[68:71]
	v_mfma_f32_16x16x32_bf16 v[64:67], v[194:197], v[230:233], v[64:67]
	v_mfma_f32_16x16x32_bf16 v[116:119], v[190:193], v[210:213], v[116:119]
	v_mfma_f32_16x16x32_bf16 v[112:115], v[202:205], v[210:213], v[112:115]
	v_mfma_f32_16x16x32_bf16 v[100:103], v[190:193], v[218:221], v[100:103]
	v_mfma_f32_16x16x32_bf16 v[96:99], v[202:205], v[218:221], v[96:99]
	v_mfma_f32_16x16x32_bf16 v[84:87], v[190:193], v[226:229], v[84:87]
	v_mfma_f32_16x16x32_bf16 v[80:83], v[202:205], v[226:229], v[80:83]
	v_mfma_f32_16x16x32_bf16 v[68:71], v[190:193], v[234:237], v[68:71]
	v_mfma_f32_16x16x32_bf16 v[64:67], v[202:205], v[234:237], v[64:67]
	s_setprio 0
	s_barrier
; #define PG8_STAGE(bufoff, gbase, voff) do { _Pragma("unroll") for (int _i = 0; _i < 2; ++_i) \
;         __builtin_amdgcn_global_load_lds((const unsigned*)((const char*)(gbase) + (voff)[_i]), (PG8_LAS unsigned*)(lds + (bufoff) + ldsw + _i * 8192), 16, 0, 0); } while (0)
; #define PG8_LDA(dst, b, h) do { _Pragma("unroll") for (int m = 0; m < 4; ++m) _Pragma("unroll") for (int k = 0; k < 2; ++k) dst[m][k] = *(const PG8_LAS bf16x8*)(lds + PG8_SA(b, h) + aoff + m * 2048 + k * 1024); } while (0)
; #define PG8_MMA(ai, bj, At, Bt) do { __builtin_amdgcn_s_setprio(1); _Pragma("unroll") for (int m = 0; m < 4; ++m) _Pragma("unroll") for (int n = 0; n < 2; ++n) _Pragma("unroll") for (int k = 0; k < 2; ++k) \
;         acc[ai][bj][m][n] = __builtin_amdgcn_mfma_f32_16x16x32_bf16(Bt[n][k], At[m][k], acc[ai][bj][m][n], 0, 0, 0); __builtin_amdgcn_s_setprio(0); } while (0)
; #define PG8_WAIT_V(n) asm volatile("s_waitcnt vmcnt(" #n ")" ::: "memory")
; #define PG8_WAIT_L(n) asm volatile("s_waitcnt lgkmcnt(" #n ")" ::: "memory")
; #define PG8_BAR __builtin_amdgcn_s_barrier()
; #define PG8_SCHED __builtin_amdgcn_sched_barrier(0)
; template <class Epi, class Sched, bool ALIGN_EPI = false, bool SP2 = false>
; __device__ __forceinline__ void gemm_phase(PG8_LAS unsigned char* lds, const Gemm g, const Sched& S, const Epi& E) {
;     ...
;             PG8_LDA(At, 1, 1); PG8_STAGE(PG8_SB(1, 0), b3, voffB); PG8_STAGE(PG8_SB(1, 1), b3 + hstepB, voffB); PG8_STAGE(PG8_SA(1, 0), a3, voffA);
;             PG8_WAIT_V(8); PG8_WAIT_L(0); PG8_BAR; PG8_MMA(1, 0, At, B0); PG8_MMA(1, 1, At, B1); PG8_BAR; PG8_SCHED;
	s_add_i32 s30, s55, s36
	v_lshl_add_u64 v[148:149], v[148:149], 0, s[18:19]
	s_mov_b32 m0, s30
	ds_read_b128 v[206:209], v157 offset:49152
	ds_read_b128 v[210:213], v157 offset:50176
	ds_read_b128 v[214:217], v157 offset:51200
	ds_read_b128 v[218:221], v157 offset:52224
	ds_read_b128 v[222:225], v157 offset:53248
	ds_read_b128 v[226:229], v157 offset:54272
	ds_read_b128 v[230:233], v157 offset:55296
	ds_read_b128 v[234:237], v157 offset:56320
	global_load_lds_dwordx4 v[148:149], off
	s_add_i32 m0, s30, 0x2000
	s_add_u32 s28, s28, 0x40080
	v_lshl_add_u64 v[148:149], v[158:159], 0, s[18:19]
	s_addc_u32 s29, s29, 0
	s_add_i32 s30, s56, s36
	global_load_lds_dwordx4 v[148:149], off
	s_mov_b32 m0, s30
	s_nop 0
	global_load_lds_dwordx4 v144, s[28:29]
	s_add_i32 m0, s30, 0x2000
	s_nop 0
	global_load_lds_dwordx4 v146, s[28:29]
	v_lshl_add_u64 v[148:149], v[174:175], 0, s[18:19]
	s_mov_b32 m0, s42
	s_nop 0
	global_load_lds_dwordx4 v[148:149], off
	v_lshl_add_u64 v[148:149], v[198:199], 0, s[18:19]
	s_mov_b32 m0, s43
	s_nop 0
	global_load_lds_dwordx4 v[148:149], off
	s_waitcnt vmcnt(8)
	s_waitcnt lgkmcnt(0)
	s_barrier
	s_setprio 1
	s_waitcnt lgkmcnt(0)
	v_mfma_f32_16x16x32_bf16 v[60:63], v[140:143], v[206:209], v[60:63]
	v_mfma_f32_16x16x32_bf16 v[56:59], v[178:181], v[206:209], v[56:59]
	v_mfma_f32_16x16x32_bf16 v[44:47], v[140:143], v[214:217], v[44:47]
	v_mfma_f32_16x16x32_bf16 v[40:43], v[178:181], v[214:217], v[40:43]
	v_mfma_f32_16x16x32_bf16 v[28:31], v[140:143], v[222:225], v[28:31]
	v_mfma_f32_16x16x32_bf16 v[24:27], v[178:181], v[222:225], v[24:27]
	v_mfma_f32_16x16x32_bf16 v[12:15], v[140:143], v[230:233], v[12:15]
	v_mfma_f32_16x16x32_bf16 v[8:11], v[178:181], v[230:233], v[8:11]
	v_mfma_f32_16x16x32_bf16 v[60:63], v[170:173], v[210:213], v[60:63]
	v_mfma_f32_16x16x32_bf16 v[56:59], v[182:185], v[210:213], v[56:59]
	v_mfma_f32_16x16x32_bf16 v[44:47], v[170:173], v[218:221], v[44:47]
	v_mfma_f32_16x16x32_bf16 v[40:43], v[182:185], v[218:221], v[40:43]
	v_mfma_f32_16x16x32_bf16 v[28:31], v[170:173], v[226:229], v[28:31]
	v_mfma_f32_16x16x32_bf16 v[24:27], v[182:185], v[226:229], v[24:27]
	v_mfma_f32_16x16x32_bf16 v[12:15], v[170:173], v[234:237], v[12:15]
	v_mfma_f32_16x16x32_bf16 v[8:11], v[182:185], v[234:237], v[8:11]
	s_setprio 0
	s_setprio 1
	v_mfma_f32_16x16x32_bf16 v[52:55], v[186:189], v[206:209], v[52:55]
	v_mfma_f32_16x16x32_bf16 v[48:51], v[194:197], v[206:209], v[48:51]
	v_mfma_f32_16x16x32_bf16 v[36:39], v[186:189], v[214:217], v[36:39]
	v_mfma_f32_16x16x32_bf16 v[32:35], v[194:197], v[214:217], v[32:35]
	v_mfma_f32_16x16x32_bf16 v[20:23], v[186:189], v[222:225], v[20:23]
	v_mfma_f32_16x16x32_bf16 v[16:19], v[194:197], v[222:225], v[16:19]
	v_mfma_f32_16x16x32_bf16 v[4:7], v[186:189], v[230:233], v[4:7]
	v_mfma_f32_16x16x32_bf16 v[0:3], v[194:197], v[230:233], v[0:3]
	v_mfma_f32_16x16x32_bf16 v[52:55], v[190:193], v[210:213], v[52:55]
	v_mfma_f32_16x16x32_bf16 v[48:51], v[202:205], v[210:213], v[48:51]
	v_mfma_f32_16x16x32_bf16 v[36:39], v[190:193], v[218:221], v[36:39]
	v_mfma_f32_16x16x32_bf16 v[32:35], v[202:205], v[218:221], v[32:35]
	v_mfma_f32_16x16x32_bf16 v[20:23], v[190:193], v[226:229], v[20:23]
	v_mfma_f32_16x16x32_bf16 v[16:19], v[202:205], v[226:229], v[16:19]
	v_mfma_f32_16x16x32_bf16 v[4:7], v[190:193], v[234:237], v[4:7]
	v_mfma_f32_16x16x32_bf16 v[0:3], v[202:205], v[234:237], v[0:3]
	s_setprio 0
	s_barrier
	s_add_i32 s54, s54, 2
	s_add_u32 s4, s4, 0x100
	s_addc_u32 s5, s5, 0
	s_add_u32 s52, s52, 0x100
	s_addc_u32 s53, s53, 0
	s_cmp_gt_u32 s54, 13
	s_cbranch_scc0 .LBB0_516
	s_and_b64 vcc, exec, s[20:21]
	s_cbranch_vccz .LBB0_519
	s_barrier

;     __device__ __forceinline__ size_t boff(const Unit& u, size_t tstepB) const { return (size_t)u.pn * tstepB; }
; #define PG8_STAGE(bufoff, gbase, voff) do { _Pragma("unroll") for (int _i = 0; _i < 2; ++_i) \
;         __builtin_amdgcn_global_load_lds((const unsigned*)((const char*)(gbase) + (voff)[_i]), (PG8_LAS unsigned*)(lds + (bufoff) + ldsw + _i * 8192), 16, 0, 0); } while (0)
; #define PG8_WAIT_V(n) asm volatile("s_waitcnt vmcnt(" #n ")" ::: "memory")
; #define PG8_BAR __builtin_amdgcn_s_barrier()
; template <class Epi, class Sched, bool ALIGN_EPI = false, bool SP2 = false>
; __device__ __forceinline__ void gemm_phase(PG8_LAS unsigned char* lds, const Gemm g, const Sched& S, const Epi& E) {
;     const int tid = threadIdx.x, wid = __builtin_amdgcn_readfirstlane(tid >> 6), lane = tid & 63, wr = wid >> 2, wc = wid & 3, fr = lane & 15, fq = lane >> 4;
;     const int K = g.K, nt = K / BK;
;     unsigned voffA[2], voffB[2];
; #pragma unroll
;     for (int i = 0; i < 2; ++i) { int R, C; stage_rc(tid * 16 + i * 8192, R, C); const int Rb = Epi::PERM ? ((R & ~31) + perm32(R & 31)) : R;
;         voffA[i] = (unsigned)(R * g.lda + C) * 2u; voffB[i] = (unsigned)(Rb * g.ldb + C) * 2u; }
;     const size_t kstep = (size_t)(BK * 2);
;     const size_t hstepA = (size_t)HALF * g.lda * 2, hstepB = (size_t)HALF * g.ldb * 2;
;     const size_t tstepA = (size_t)g.arows * g.lda * 2, tstepB = 2 * hstepB;
;     const unsigned ldsw = (unsigned)wid * 1024u;
;     const int aoff = lds_byte(wr * 64 + fr, fq * 8), boff = lds_byte(wc * 32 + fr, fq * 8);
;     ...
;         PG8_WAIT_V(2); PG8_BAR;
;         PG8_STAGE(PG8_SB(1, 0), cB + kstep, voffB); PG8_STAGE(PG8_SA(1, 0), cA + kstep, voffA); PG8_STAGE(PG8_SB(1, 1), cB + hstepB + kstep, voffB);
;         PG8_WAIT_V(6); PG8_BAR;
.LBB0_530:
	s_add_u32 s14, s68, 0x2a02400
	s_mov_b64 s[16:17], 0x80
	s_addc_u32 s15, s69, 0
	s_lshl_b32 s3, s3, 5
	s_add_i32 m0, s37, 0x18000
	v_lshl_add_u64 v[6:7], v[6:7], 0, s[16:17]
	s_lshl_b32 s20, s1, 13
	s_and_b32 s3, s3, 0x60
	s_waitcnt vmcnt(2)
	s_barrier
	global_load_lds_dwordx4 v[6:7], off
	v_lshl_add_u64 v[4:5], v[4:5], 0, s[16:17]
	s_add_i32 m0, s37, 0x1a000
	s_add_i32 s42, s37, 0x8000
	s_add_i32 s43, s37, 0xa000
	global_load_lds_dwordx4 v[4:5], off
	v_lshl_add_u64 v[0:1], v[0:1], 0, s[16:17]
	s_mov_b32 m0, s42
	s_add_u32 s18, s26, 0x20080
	global_load_lds_dwordx4 v[0:1], off
	v_lshl_add_u64 v[0:1], v[2:3], 0, s[16:17]
	s_mov_b32 m0, s43
	s_addc_u32 s19, s27, 0
	global_load_lds_dwordx4 v[0:1], off
	s_add_i32 m0, s37, 0x1c000
	global_load_lds_dwordx4 v132, s[18:19]
	v_lshl_add_u64 v[0:1], s[18:19], 0, v[134:135]
	s_add_i32 m0, s37, 0x1e000
	s_cmpk_lt_u32 s2, 0x100
	global_load_lds_dwordx4 v[0:1], off
	v_lshlrev_b32_e32 v1, 2, v163
	v_lshl_or_b32 v0, v163, 6, v164
	v_and_b32_e32 v1, 32, v1
	s_waitcnt vmcnt(6)
	v_bitop3_b32 v0, v0, s20, v1 bitop3:0xde
	v_lshl_or_b32 v151, s3, 7, v165
	s_cselect_b64 s[18:19], -1, 0
	s_add_i32 s45, 0, 0x10000
	s_add_i32 s46, 0, 0x14000
	s_sext_i32_i8 s50, s0
	v_lshl_or_b32 v150, s1, 6, v163
	s_ashr_i32 s44, s90, 31
	v_or_b32_e32 v152, s3, v162
	v_add3_u32 v136, v154, v160, v161
	v_mov_b32_e32 v137, v133
	v_add3_u32 v138, v153, v160, v161
	v_mov_b32_e32 v139, v133
	v_mov_b64_e32 v[140:141], 0x100
	v_mov_b64_e32 v[142:143], 0xff
	v_add_u32_e32 v153, s45, v151
	v_add_u32_e32 v154, s46, v151
	v_add_u32_e32 v155, 0, v0
	s_movk_i32 s47, 0x3400
	s_barrier
	s_branch .LBB0_533

; #define PG8_STAGE(bufoff, gbase, voff) do { _Pragma("unroll") for (int _i = 0; _i < 2; ++_i) \
;         __builtin_amdgcn_global_load_lds((const unsigned*)((const char*)(gbase) + (voff)[_i]), (PG8_LAS unsigned*)(lds + (bufoff) + ldsw + _i * 8192), 16, 0, 0); } while (0)
; #define PG8_LDA(dst, b, h) do { _Pragma("unroll") for (int m = 0; m < 4; ++m) _Pragma("unroll") for (int k = 0; k < 2; ++k) dst[m][k] = *(const PG8_LAS bf16x8*)(lds + PG8_SA(b, h) + aoff + m * 2048 + k * 1024); } while (0)
; #define PG8_LDB(dst, b, h) do { _Pragma("unroll") for (int n = 0; n < 2; ++n) _Pragma("unroll") for (int k = 0; k < 2; ++k) dst[n][k] = *(const PG8_LAS bf16x8*)(lds + PG8_SB(b, h) + boff + n * 2048 + k * 1024); } while (0)
; #define PG8_MMA(ai, bj, At, Bt) do { __builtin_amdgcn_s_setprio(1); _Pragma("unroll") for (int m = 0; m < 4; ++m) _Pragma("unroll") for (int n = 0; n < 2; ++n) _Pragma("unroll") for (int k = 0; k < 2; ++k) \
;         acc[ai][bj][m][n] = __builtin_amdgcn_mfma_f32_16x16x32_bf16(Bt[n][k], At[m][k], acc[ai][bj][m][n], 0, 0, 0); __builtin_amdgcn_s_setprio(0); } while (0)
; #define PG8_WAIT_V(n) asm volatile("s_waitcnt vmcnt(" #n ")" ::: "memory")
; #define PG8_WAIT_L(n) asm volatile("s_waitcnt lgkmcnt(" #n ")" ::: "memory")
; #define PG8_BAR __builtin_amdgcn_s_barrier()
; template <class Epi, class Sched, bool ALIGN_EPI = false, bool SP2 = false>
; __device__ __forceinline__ void gemm_phase(PG8_LAS unsigned char* lds, const Gemm g, const Sched& S, const Epi& E) {
;     ...
;             const char* a1 = cA + (size_t)(t + 1) * kstep;
;             const char* a2 = last ? nA : cA + (size_t)(t + 2) * kstep; const char* b2 = last ? nB : cB + (size_t)(t + 2) * kstep;
;             const char* a3 = a2 + kstep; const char* b3 = b2 + kstep;
;             if (last && has_next) S.a_ready(nxt);
;             if constexpr (SP2) {
;             PG8_LDB(B0, 0, 0); PG8_LDB(B1, 0, 1); PG8_SCHED; PG8_LDA(At, 0, 0); PG8_STAGE(PG8_SA(1, 1), a1 + hstepA, voffA);
;             PG8_WAIT_V(8); PG8_WAIT_L(0); PG8_BAR; PG8_MMA(0, 0, At, B0); PG8_MMA(0, 1, At, B1); PG8_BAR; PG8_SCHED;
;             PG8_LDA(At, 0, 1); PG8_STAGE(PG8_SB(0, 0), b2, voffB); PG8_STAGE(PG8_SB(0, 1), b2 + hstepB, voffB); PG8_STAGE(PG8_SA(0, 0), a2, voffA);
;             PG8_WAIT_V(8); PG8_WAIT_L(0); PG8_BAR; PG8_MMA(1, 0, At, B0); PG8_MMA(1, 1, At, B1); PG8_BAR; PG8_SCHED;
.LBB0_542:
	ds_read_b128 v[144:147], v153
	ds_read_b128 v[156:159], v153 offset:1024
	ds_read_b128 v[160:163], v153 offset:2048
	ds_read_b128 v[164:167], v153 offset:3072
	ds_read_b128 v[168:171], v154
	ds_read_b128 v[172:175], v154 offset:1024
	ds_read_b128 v[178:181], v154 offset:2048
	ds_read_b128 v[182:185], v154 offset:3072
	s_add_u32 s26, s2, 0xffe60080
	s_addc_u32 s27, s3, -1
	s_cmp_eq_u32 s54, 4
	s_cselect_b32 s29, s23, s27
	s_cselect_b32 s28, s22, s26
	s_cselect_b32 s27, s21, s53
	s_cselect_b32 s26, s51, s52
	s_add_i32 m0, s37, 0xc000
	ds_read_b128 v[186:189], v155
	ds_read_b128 v[190:193], v155 offset:1024
	ds_read_b128 v[194:197], v155 offset:2048
	ds_read_b128 v[202:205], v155 offset:3072
	ds_read_b128 v[206:209], v155 offset:4096
	ds_read_b128 v[210:213], v155 offset:5120
	ds_read_b128 v[214:217], v155 offset:6144
	ds_read_b128 v[218:221], v155 offset:7168
	global_load_lds_dwordx4 v136, s[2:3]
	s_add_i32 m0, s37, 0xe000
	s_nop 0
	global_load_lds_dwordx4 v138, s[2:3]
	s_waitcnt vmcnt(8)
	s_waitcnt lgkmcnt(0)
	s_barrier
	s_setprio 1
	s_waitcnt lgkmcnt(0)
	v_mfma_f32_16x16x32_bf16 v[124:127], v[144:147], v[186:189], v[124:127]
	v_mfma_f32_16x16x32_bf16 v[120:123], v[160:163], v[186:189], v[120:123]
	v_mfma_f32_16x16x32_bf16 v[108:111], v[144:147], v[194:197], v[108:111]
	v_mfma_f32_16x16x32_bf16 v[104:107], v[160:163], v[194:197], v[104:107]
	v_mfma_f32_16x16x32_bf16 v[92:95], v[144:147], v[206:209], v[92:95]
	v_mfma_f32_16x16x32_bf16 v[88:91], v[160:163], v[206:209], v[88:91]
	v_mfma_f32_16x16x32_bf16 v[76:79], v[144:147], v[214:217], v[76:79]
	v_mfma_f32_16x16x32_bf16 v[72:75], v[160:163], v[214:217], v[72:75]
	v_mfma_f32_16x16x32_bf16 v[124:127], v[156:159], v[190:193], v[124:127]
	v_mfma_f32_16x16x32_bf16 v[120:123], v[164:167], v[190:193], v[120:123]
	v_mfma_f32_16x16x32_bf16 v[108:111], v[156:159], v[202:205], v[108:111]
	v_mfma_f32_16x16x32_bf16 v[104:107], v[164:167], v[202:205], v[104:107]
	v_mfma_f32_16x16x32_bf16 v[92:95], v[156:159], v[210:213], v[92:95]
	v_mfma_f32_16x16x32_bf16 v[88:91], v[164:167], v[210:213], v[88:91]
	v_mfma_f32_16x16x32_bf16 v[76:79], v[156:159], v[218:221], v[76:79]
	v_mfma_f32_16x16x32_bf16 v[72:75], v[164:167], v[218:221], v[72:75]
	s_setprio 0
	s_setprio 1
	v_mfma_f32_16x16x32_bf16 v[116:119], v[168:171], v[186:189], v[116:119]
	v_mfma_f32_16x16x32_bf16 v[112:115], v[178:181], v[186:189], v[112:115]
	v_mfma_f32_16x16x32_bf16 v[100:103], v[168:171], v[194:197], v[100:103]
	v_mfma_f32_16x16x32_bf16 v[96:99], v[178:181], v[194:197], v[96:99]
	v_mfma_f32_16x16x32_bf16 v[84:87], v[168:171], v[206:209], v[84:87]
	v_mfma_f32_16x16x32_bf16 v[80:83], v[178:181], v[206:209], v[80:83]
	v_mfma_f32_16x16x32_bf16 v[68:71], v[168:171], v[214:217], v[68:71]
	v_mfma_f32_16x16x32_bf16 v[64:67], v[178:181], v[214:217], v[64:67]
	v_mfma_f32_16x16x32_bf16 v[116:119], v[172:175], v[190:193], v[116:119]
	v_mfma_f32_16x16x32_bf16 v[112:115], v[182:185], v[190:193], v[112:115]
	v_mfma_f32_16x16x32_bf16 v[100:103], v[172:175], v[202:205], v[100:103]
	v_mfma_f32_16x16x32_bf16 v[96:99], v[182:185], v[202:205], v[96:99]
	v_mfma_f32_16x16x32_bf16 v[84:87], v[172:175], v[210:213], v[84:87]
	v_mfma_f32_16x16x32_bf16 v[80:83], v[182:185], v[210:213], v[80:83]
	v_mfma_f32_16x16x32_bf16 v[68:71], v[172:175], v[218:221], v[68:71]
	v_mfma_f32_16x16x32_bf16 v[64:67], v[182:185], v[218:221], v[64:67]
	s_setprio 0
	s_barrier
	s_add_i32 s55, s45, s36
	v_lshl_add_u64 v[148:149], s[26:27], 0, v[132:133]
	s_mov_b32 m0, s55
	ds_read_b128 v[186:189], v155 offset:16384
	ds_read_b128 v[190:193], v155 offset:17408
	ds_read_b128 v[194:197], v155 offset:18432
	ds_read_b128 v[202:205], v155 offset:19456
	ds_read_b128 v[206:209], v155 offset:20480
	ds_read_b128 v[210:213], v155 offset:21504
	ds_read_b128 v[214:217], v155 offset:22528
	ds_read_b128 v[218:221], v155 offset:23552
	global_load_lds_dwordx4 v[148:149], off
	s_add_i32 m0, s55, 0x2000
	s_add_u32 s56, s26, 0x20000
	v_lshl_add_u64 v[198:199], s[26:27], 0, v[134:135]
	s_addc_u32 s57, s27, 0
	s_add_i32 s55, s46, s36
	global_load_lds_dwordx4 v[198:199], off
	s_mov_b32 m0, s55
	v_lshl_add_u64 v[224:225], s[28:29], 0, v[130:131]
	global_load_lds_dwordx4 v132, s[56:57]
	s_add_i32 m0, s55, 0x2000
	s_nop 0
	global_load_lds_dwordx4 v134, s[56:57]
	v_lshl_add_u64 v[222:223], s[28:29], 0, v[128:129]
	s_mov_b32 m0, s37
	s_nop 0
	global_load_lds_dwordx4 v[222:223], off
	s_mov_b32 m0, s38
	s_nop 0
	global_load_lds_dwordx4 v[224:225], off
	s_waitcnt vmcnt(8)
	s_waitcnt lgkmcnt(0)
	s_barrier
; #define PG8_STAGE(bufoff, gbase, voff) do { _Pragma("unroll") for (int _i = 0; _i < 2; ++_i) \
;         __builtin_amdgcn_global_load_lds((const unsigned*)((const char*)(gbase) + (voff)[_i]), (PG8_LAS unsigned*)(lds + (bufoff) + ldsw + _i * 8192), 16, 0, 0); } while (0)
; #define PG8_LDA(dst, b, h) do { _Pragma("unroll") for (int m = 0; m < 4; ++m) _Pragma("unroll") for (int k = 0; k < 2; ++k) dst[m][k] = *(const PG8_LAS bf16x8*)(lds + PG8_SA(b, h) + aoff + m * 2048 + k * 1024); } while (0)
; #define PG8_LDB(dst, b, h) do { _Pragma("unroll") for (int n = 0; n < 2; ++n) _Pragma("unroll") for (int k = 0; k < 2; ++k) dst[n][k] = *(const PG8_LAS bf16x8*)(lds + PG8_SB(b, h) + boff + n * 2048 + k * 1024); } while (0)
; #define PG8_MMA(ai, bj, At, Bt) do { __builtin_amdgcn_s_setprio(1); _Pragma("unroll") for (int m = 0; m < 4; ++m) _Pragma("unroll") for (int n = 0; n < 2; ++n) _Pragma("unroll") for (int k = 0; k < 2; ++k) \
;         acc[ai][bj][m][n] = __builtin_amdgcn_mfma_f32_16x16x32_bf16(Bt[n][k], At[m][k], acc[ai][bj][m][n], 0, 0, 0); __builtin_amdgcn_s_setprio(0); } while (0)
; #define PG8_WAIT_V(n) asm volatile("s_waitcnt vmcnt(" #n ")" ::: "memory")
; #define PG8_WAIT_L(n) asm volatile("s_waitcnt lgkmcnt(" #n ")" ::: "memory")
; #define PG8_BAR __builtin_amdgcn_s_barrier()
; #define PG8_SCHED __builtin_amdgcn_sched_barrier(0)
; template <class Epi, class Sched, bool ALIGN_EPI = false, bool SP2 = false>
; __device__ __forceinline__ void gemm_phase(PG8_LAS unsigned char* lds, const Gemm g, const Sched& S, const Epi& E) {
;     ...
;             PG8_WAIT_V(8); PG8_WAIT_L(0); PG8_BAR; PG8_MMA(1, 0, At, B0); PG8_MMA(1, 1, At, B1); PG8_BAR; PG8_SCHED;
;             PG8_LDB(B0, 1, 0); PG8_LDB(B1, 1, 1); PG8_SCHED; PG8_LDA(At, 1, 0); PG8_STAGE(PG8_SA(0, 1), a2 + hstepA, voffA);
;             PG8_WAIT_V(8); PG8_WAIT_L(0); PG8_BAR; PG8_MMA(0, 0, At, B0); PG8_MMA(0, 1, At, B1); PG8_BAR; PG8_SCHED;
	s_setprio 1
	s_waitcnt lgkmcnt(0)
	v_mfma_f32_16x16x32_bf16 v[60:63], v[144:147], v[186:189], v[60:63]
	v_mfma_f32_16x16x32_bf16 v[56:59], v[160:163], v[186:189], v[56:59]
	v_mfma_f32_16x16x32_bf16 v[44:47], v[144:147], v[194:197], v[44:47]
	v_mfma_f32_16x16x32_bf16 v[40:43], v[160:163], v[194:197], v[40:43]
	v_mfma_f32_16x16x32_bf16 v[28:31], v[144:147], v[206:209], v[28:31]
	v_mfma_f32_16x16x32_bf16 v[24:27], v[160:163], v[206:209], v[24:27]
	v_mfma_f32_16x16x32_bf16 v[12:15], v[144:147], v[214:217], v[12:15]
	v_mfma_f32_16x16x32_bf16 v[8:11], v[160:163], v[214:217], v[8:11]
	v_mfma_f32_16x16x32_bf16 v[60:63], v[156:159], v[190:193], v[60:63]
	v_mfma_f32_16x16x32_bf16 v[56:59], v[164:167], v[190:193], v[56:59]
	v_mfma_f32_16x16x32_bf16 v[44:47], v[156:159], v[202:205], v[44:47]
	v_mfma_f32_16x16x32_bf16 v[40:43], v[164:167], v[202:205], v[40:43]
	v_mfma_f32_16x16x32_bf16 v[28:31], v[156:159], v[210:213], v[28:31]
	v_mfma_f32_16x16x32_bf16 v[24:27], v[164:167], v[210:213], v[24:27]
	v_mfma_f32_16x16x32_bf16 v[12:15], v[156:159], v[218:221], v[12:15]
	v_mfma_f32_16x16x32_bf16 v[8:11], v[164:167], v[218:221], v[8:11]
	s_setprio 0
	s_setprio 1
	v_mfma_f32_16x16x32_bf16 v[52:55], v[168:171], v[186:189], v[52:55]
	v_mfma_f32_16x16x32_bf16 v[48:51], v[178:181], v[186:189], v[48:51]
	v_mfma_f32_16x16x32_bf16 v[36:39], v[168:171], v[194:197], v[36:39]
	v_mfma_f32_16x16x32_bf16 v[32:35], v[178:181], v[194:197], v[32:35]
	v_mfma_f32_16x16x32_bf16 v[20:23], v[168:171], v[206:209], v[20:23]
	v_mfma_f32_16x16x32_bf16 v[16:19], v[178:181], v[206:209], v[16:19]
	v_mfma_f32_16x16x32_bf16 v[4:7], v[168:171], v[214:217], v[4:7]
	v_mfma_f32_16x16x32_bf16 v[0:3], v[178:181], v[214:217], v[0:3]
	v_mfma_f32_16x16x32_bf16 v[52:55], v[172:175], v[190:193], v[52:55]
	v_mfma_f32_16x16x32_bf16 v[48:51], v[182:185], v[190:193], v[48:51]
	v_mfma_f32_16x16x32_bf16 v[36:39], v[172:175], v[202:205], v[36:39]
	v_mfma_f32_16x16x32_bf16 v[32:35], v[182:185], v[202:205], v[32:35]
	v_mfma_f32_16x16x32_bf16 v[20:23], v[172:175], v[210:213], v[20:23]
	v_mfma_f32_16x16x32_bf16 v[16:19], v[182:185], v[210:213], v[16:19]
	v_mfma_f32_16x16x32_bf16 v[4:7], v[172:175], v[218:221], v[4:7]
	v_mfma_f32_16x16x32_bf16 v[0:3], v[182:185], v[218:221], v[0:3]
	s_setprio 0
	s_barrier
	s_add_i32 s55, 0, 0x18000
	s_add_i32 s56, 0, 0x1c000
	v_add_u32_e32 v164, s55, v151
	v_add_u32_e32 v177, s56, v151
	ds_read_b128 v[144:147], v164
	ds_read_b128 v[156:159], v164 offset:1024
	ds_read_b128 v[160:163], v164 offset:2048
	ds_read_b128 v[164:167], v164 offset:3072
	ds_read_b128 v[168:171], v177
	ds_read_b128 v[172:175], v177 offset:1024
	ds_read_b128 v[178:181], v177 offset:2048
	ds_read_b128 v[182:185], v177 offset:3072
	s_add_u32 s28, s28, 0x1a0000
	s_addc_u32 s29, s29, 0
	s_mov_b32 m0, s39
	ds_read_b128 v[186:189], v155 offset:32768
	ds_read_b128 v[190:193], v155 offset:33792
	ds_read_b128 v[194:197], v155 offset:34816
	ds_read_b128 v[202:205], v155 offset:35840
	ds_read_b128 v[206:209], v155 offset:36864
	ds_read_b128 v[210:213], v155 offset:37888
	ds_read_b128 v[214:217], v155 offset:38912
	ds_read_b128 v[218:221], v155 offset:39936
	global_load_lds_dwordx4 v128, s[28:29]
	v_lshl_add_u64 v[226:227], s[28:29], 0, v[130:131]
	s_mov_b32 m0, s40
	s_nop 0
	global_load_lds_dwordx4 v[226:227], off
	s_waitcnt vmcnt(8)
	s_waitcnt lgkmcnt(0)
	s_barrier
	s_setprio 1
	s_waitcnt lgkmcnt(0)
	v_mfma_f32_16x16x32_bf16 v[124:127], v[144:147], v[186:189], v[124:127]
	v_mfma_f32_16x16x32_bf16 v[120:123], v[160:163], v[186:189], v[120:123]
	v_mfma_f32_16x16x32_bf16 v[108:111], v[144:147], v[194:197], v[108:111]
	v_mfma_f32_16x16x32_bf16 v[104:107], v[160:163], v[194:197], v[104:107]
	v_mfma_f32_16x16x32_bf16 v[92:95], v[144:147], v[206:209], v[92:95]
	v_mfma_f32_16x16x32_bf16 v[88:91], v[160:163], v[206:209], v[88:91]
	v_mfma_f32_16x16x32_bf16 v[76:79], v[144:147], v[214:217], v[76:79]
	v_mfma_f32_16x16x32_bf16 v[72:75], v[160:163], v[214:217], v[72:75]
	v_mfma_f32_16x16x32_bf16 v[124:127], v[156:159], v[190:193], v[124:127]
	v_mfma_f32_16x16x32_bf16 v[120:123], v[164:167], v[190:193], v[120:123]
	v_mfma_f32_16x16x32_bf16 v[108:111], v[156:159], v[202:205], v[108:111]
	v_mfma_f32_16x16x32_bf16 v[104:107], v[164:167], v[202:205], v[104:107]
	v_mfma_f32_16x16x32_bf16 v[92:95], v[156:159], v[210:213], v[92:95]
	v_mfma_f32_16x16x32_bf16 v[88:91], v[164:167], v[210:213], v[88:91]
	v_mfma_f32_16x16x32_bf16 v[76:79], v[156:159], v[218:221], v[76:79]
	v_mfma_f32_16x16x32_bf16 v[72:75], v[164:167], v[218:221], v[72:75]
	s_setprio 0
	s_setprio 1
	v_mfma_f32_16x16x32_bf16 v[116:119], v[168:171], v[186:189], v[116:119]
	v_mfma_f32_16x16x32_bf16 v[112:115], v[178:181], v[186:189], v[112:115]
	v_mfma_f32_16x16x32_bf16 v[100:103], v[168:171], v[194:197], v[100:103]
	v_mfma_f32_16x16x32_bf16 v[96:99], v[178:181], v[194:197], v[96:99]
	v_mfma_f32_16x16x32_bf16 v[84:87], v[168:171], v[206:209], v[84:87]
	v_mfma_f32_16x16x32_bf16 v[80:83], v[178:181], v[206:209], v[80:83]
	v_mfma_f32_16x16x32_bf16 v[68:71], v[168:171], v[214:217], v[68:71]
	v_mfma_f32_16x16x32_bf16 v[64:67], v[178:181], v[214:217], v[64:67]
	v_mfma_f32_16x16x32_bf16 v[116:119], v[172:175], v[190:193], v[116:119]
	v_mfma_f32_16x16x32_bf16 v[112:115], v[182:185], v[190:193], v[112:115]
	v_mfma_f32_16x16x32_bf16 v[100:103], v[172:175], v[202:205], v[100:103]
	v_mfma_f32_16x16x32_bf16 v[96:99], v[182:185], v[202:205], v[96:99]
	v_mfma_f32_16x16x32_bf16 v[84:87], v[172:175], v[210:213], v[84:87]
	v_mfma_f32_16x16x32_bf16 v[80:83], v[182:185], v[210:213], v[80:83]
	v_mfma_f32_16x16x32_bf16 v[68:71], v[172:175], v[218:221], v[68:71]
	v_mfma_f32_16x16x32_bf16 v[64:67], v[182:185], v[218:221], v[64:67]
	s_setprio 0
	s_barrier
; #define PG8_STAGE(bufoff, gbase, voff) do { _Pragma("unroll") for (int _i = 0; _i < 2; ++_i) \
;         __builtin_amdgcn_global_load_lds((const unsigned*)((const char*)(gbase) + (voff)[_i]), (PG8_LAS unsigned*)(lds + (bufoff) + ldsw + _i * 8192), 16, 0, 0); } while (0)
; #define PG8_LDA(dst, b, h) do { _Pragma("unroll") for (int m = 0; m < 4; ++m) _Pragma("unroll") for (int k = 0; k < 2; ++k) dst[m][k] = *(const PG8_LAS bf16x8*)(lds + PG8_SA(b, h) + aoff + m * 2048 + k * 1024); } while (0)
; #define PG8_MMA(ai, bj, At, Bt) do { __builtin_amdgcn_s_setprio(1); _Pragma("unroll") for (int m = 0; m < 4; ++m) _Pragma("unroll") for (int n = 0; n < 2; ++n) _Pragma("unroll") for (int k = 0; k < 2; ++k) \
;         acc[ai][bj][m][n] = __builtin_amdgcn_mfma_f32_16x16x32_bf16(Bt[n][k], At[m][k], acc[ai][bj][m][n], 0, 0, 0); __builtin_amdgcn_s_setprio(0); } while (0)
; #define PG8_WAIT_V(n) asm volatile("s_waitcnt vmcnt(" #n ")" ::: "memory")
; #define PG8_WAIT_L(n) asm volatile("s_waitcnt lgkmcnt(" #n ")" ::: "memory")
; #define PG8_BAR __builtin_amdgcn_s_barrier()
; #define PG8_SCHED __builtin_amdgcn_sched_barrier(0)
; template <class Epi, class Sched, bool ALIGN_EPI = false, bool SP2 = false>
; __device__ __forceinline__ void gemm_phase(PG8_LAS unsigned char* lds, const Gemm g, const Sched& S, const Epi& E) {
;     ...
;             PG8_LDA(At, 1, 1); PG8_STAGE(PG8_SB(1, 0), b3, voffB); PG8_STAGE(PG8_SB(1, 1), b3 + hstepB, voffB); PG8_STAGE(PG8_SA(1, 0), a3, voffA);
;             PG8_WAIT_V(8); PG8_WAIT_L(0); PG8_BAR; PG8_MMA(1, 0, At, B0); PG8_MMA(1, 1, At, B1); PG8_BAR; PG8_SCHED;
	s_add_i32 s28, s55, s36
	v_lshl_add_u64 v[148:149], v[148:149], 0, s[16:17]
	s_mov_b32 m0, s28
	ds_read_b128 v[186:189], v155 offset:49152
	ds_read_b128 v[190:193], v155 offset:50176
	ds_read_b128 v[194:197], v155 offset:51200
	ds_read_b128 v[202:205], v155 offset:52224
	ds_read_b128 v[206:209], v155 offset:53248
	ds_read_b128 v[210:213], v155 offset:54272
	ds_read_b128 v[214:217], v155 offset:55296
	ds_read_b128 v[218:221], v155 offset:56320
	global_load_lds_dwordx4 v[148:149], off
	s_add_i32 m0, s28, 0x2000
	s_add_u32 s26, s26, 0x20080
	v_lshl_add_u64 v[148:149], v[198:199], 0, s[16:17]
	s_addc_u32 s27, s27, 0
	s_add_i32 s28, s56, s36
	global_load_lds_dwordx4 v[148:149], off
	s_mov_b32 m0, s28
	s_nop 0
	global_load_lds_dwordx4 v132, s[26:27]
	s_add_i32 m0, s28, 0x2000
	s_nop 0
	global_load_lds_dwordx4 v134, s[26:27]
	v_lshl_add_u64 v[148:149], v[222:223], 0, s[16:17]
	s_mov_b32 m0, s42
	s_nop 0
	global_load_lds_dwordx4 v[148:149], off
	v_lshl_add_u64 v[148:149], v[224:225], 0, s[16:17]
	s_mov_b32 m0, s43
	s_nop 0
	global_load_lds_dwordx4 v[148:149], off
	s_waitcnt vmcnt(8)
	s_waitcnt lgkmcnt(0)
	s_barrier
	s_setprio 1
	s_waitcnt lgkmcnt(0)
	v_mfma_f32_16x16x32_bf16 v[60:63], v[144:147], v[186:189], v[60:63]
	v_mfma_f32_16x16x32_bf16 v[56:59], v[160:163], v[186:189], v[56:59]
	v_mfma_f32_16x16x32_bf16 v[44:47], v[144:147], v[194:197], v[44:47]
	v_mfma_f32_16x16x32_bf16 v[40:43], v[160:163], v[194:197], v[40:43]
	v_mfma_f32_16x16x32_bf16 v[28:31], v[144:147], v[206:209], v[28:31]
	v_mfma_f32_16x16x32_bf16 v[24:27], v[160:163], v[206:209], v[24:27]
	v_mfma_f32_16x16x32_bf16 v[12:15], v[144:147], v[214:217], v[12:15]
	v_mfma_f32_16x16x32_bf16 v[8:11], v[160:163], v[214:217], v[8:11]
	v_mfma_f32_16x16x32_bf16 v[60:63], v[156:159], v[190:193], v[60:63]
	v_mfma_f32_16x16x32_bf16 v[56:59], v[164:167], v[190:193], v[56:59]
	v_mfma_f32_16x16x32_bf16 v[44:47], v[156:159], v[202:205], v[44:47]
	v_mfma_f32_16x16x32_bf16 v[40:43], v[164:167], v[202:205], v[40:43]
	v_mfma_f32_16x16x32_bf16 v[28:31], v[156:159], v[210:213], v[28:31]
	v_mfma_f32_16x16x32_bf16 v[24:27], v[164:167], v[210:213], v[24:27]
	v_mfma_f32_16x16x32_bf16 v[12:15], v[156:159], v[218:221], v[12:15]
	v_mfma_f32_16x16x32_bf16 v[8:11], v[164:167], v[218:221], v[8:11]
	s_setprio 0
	s_setprio 1
	v_mfma_f32_16x16x32_bf16 v[52:55], v[168:171], v[186:189], v[52:55]
	v_mfma_f32_16x16x32_bf16 v[48:51], v[178:181], v[186:189], v[48:51]
	v_mfma_f32_16x16x32_bf16 v[36:39], v[168:171], v[194:197], v[36:39]
	v_mfma_f32_16x16x32_bf16 v[32:35], v[178:181], v[194:197], v[32:35]
	v_mfma_f32_16x16x32_bf16 v[20:23], v[168:171], v[206:209], v[20:23]
	v_mfma_f32_16x16x32_bf16 v[16:19], v[178:181], v[206:209], v[16:19]
	v_mfma_f32_16x16x32_bf16 v[4:7], v[168:171], v[214:217], v[4:7]
	v_mfma_f32_16x16x32_bf16 v[0:3], v[178:181], v[214:217], v[0:3]
	v_mfma_f32_16x16x32_bf16 v[52:55], v[172:175], v[190:193], v[52:55]
	v_mfma_f32_16x16x32_bf16 v[48:51], v[182:185], v[190:193], v[48:51]
	v_mfma_f32_16x16x32_bf16 v[36:39], v[172:175], v[202:205], v[36:39]
	v_mfma_f32_16x16x32_bf16 v[32:35], v[182:185], v[202:205], v[32:35]
	v_mfma_f32_16x16x32_bf16 v[20:23], v[172:175], v[210:213], v[20:23]
	v_mfma_f32_16x16x32_bf16 v[16:19], v[182:185], v[210:213], v[16:19]
	v_mfma_f32_16x16x32_bf16 v[4:7], v[172:175], v[218:221], v[4:7]
	v_mfma_f32_16x16x32_bf16 v[0:3], v[182:185], v[218:221], v[0:3]
	s_setprio 0
	s_barrier
	s_add_i32 s54, s54, 2
	s_add_u32 s2, s2, 0x100
	s_addc_u32 s3, s3, 0
	s_add_u32 s52, s52, 0x100
	s_addc_u32 s53, s53, 0
	s_cmp_gt_u32 s54, 5
	s_cbranch_scc0 .LBB0_542
	s_and_b64 vcc, exec, s[18:19]
	s_cbranch_vccz .LBB0_545
	s_barrier

; #define PG8_STAGE(bufoff, gbase, voff) do { _Pragma("unroll") for (int _i = 0; _i < 2; ++_i) \
;         __builtin_amdgcn_global_load_lds((const unsigned*)((const char*)(gbase) + (voff)[_i]), (PG8_LAS unsigned*)(lds + (bufoff) + ldsw + _i * 8192), 16, 0, 0); } while (0)
; #define PG8_WAIT_V(n) asm volatile("s_waitcnt vmcnt(" #n ")" ::: "memory")
; #define PG8_BAR __builtin_amdgcn_s_barrier()
; template <class Epi, class Sched, bool ALIGN_EPI = false, bool SP2 = false>
; __device__ __forceinline__ void gemm_phase(PG8_LAS unsigned char* lds, const Gemm g, const Sched& S, const Epi& E) {
;     ...
;     f32x4 acc[2][2][4][2];
; #pragma unroll
;     for (int a = 0; a < 2; ++a)
; #pragma unroll
;         for (int b = 0; b < 2; ++b)
; #pragma unroll
;             for (int m = 0; m < 4; ++m)
; #pragma unroll
;                 for (int n = 0; n < 2; ++n) acc[a][b][m][n] = (f32x4){0.f, 0.f, 0.f, 0.f};
;     bf16x8 At[4][2], B0[2][2], B1[2][2];
;     const char* cA = (const char*)g.A + (size_t)cur.pm * tstepA; const char* cB = (const char*)g.Bt + (size_t)cur.pn * tstepB;
;     S.a_ready(cur);
;     if constexpr (SP2) {
;         PG8_STAGE(PG8_SB(0, 0), cB, voffB); PG8_STAGE(PG8_SB(0, 1), cB + hstepB, voffB); PG8_STAGE(PG8_SA(0, 0), cA, voffA); PG8_STAGE(PG8_SA(0, 1), cA + hstepA, voffA);
;         if (wr == 1) PG8_BAR;
;         PG8_WAIT_V(2); PG8_BAR;
;         PG8_STAGE(PG8_SB(1, 0), cB + kstep, voffB); PG8_STAGE(PG8_SA(1, 0), cA + kstep, voffA); PG8_STAGE(PG8_SB(1, 1), cB + hstepB + kstep, voffB);
;         PG8_WAIT_V(6); PG8_BAR;
.LBB0_611:
	v_and_b32_e32 v145, 15, v176
	v_and_b32_e32 v12, 48, v176
	v_lshlrev_b32_e32 v14, 2, v176
	s_sext_i32_i8 s14, s0
	v_lshl_or_b32 v13, v145, 6, v12
	s_lshl_b32 s0, s33, 13
	v_and_b32_e32 v14, 32, v14
	s_mov_b64 s[18:19], 0x80
	s_and_b32 s17, s15, 3
	v_bitop3_b32 v13, v13, s0, v14 bitop3:0xde
	v_lshlrev_b32_e32 v15, 6, v176
	s_movk_i32 s0, 0x3c0
	s_add_i32 m0, s41, 0x18000
	v_lshl_add_u64 v[6:7], v[6:7], 0, s[18:19]
	s_lshl_b32 s45, s33, 6
	v_and_or_b32 v12, v15, s0, v12
	s_lshl_b32 s0, s17, 12
	s_waitcnt vmcnt(2)
	s_barrier
	global_load_lds_dwordx4 v[6:7], off
	v_lshl_add_u64 v[4:5], v[4:5], 0, s[18:19]
	s_add_i32 m0, s41, 0x1a000
	s_add_i32 s47, s41, 0x8000
	s_add_i32 s48, s41, 0xa000
	global_load_lds_dwordx4 v[4:5], off
	v_lshl_add_u64 v[2:3], v[2:3], 0, s[18:19]
	s_mov_b32 m0, s47
	s_add_u32 s2, s28, 0x40080
	global_load_lds_dwordx4 v[2:3], off
	v_lshl_add_u64 v[0:1], v[0:1], 0, s[18:19]
	s_mov_b32 m0, s48
	s_addc_u32 s3, s29, 0
	global_load_lds_dwordx4 v[0:1], off
	s_add_i32 m0, s41, 0x1c000
	global_load_lds_dwordx4 v128, s[2:3]
	v_lshl_add_u64 v[0:1], s[2:3], 0, v[130:131]
	s_add_i32 m0, s41, 0x1e000
	v_lshlrev_b32_e32 v2, 11, v10
	global_load_lds_dwordx4 v[0:1], off
	v_lshlrev_b32_e32 v0, 8, v176
	v_and_b32_e32 v0, 0x38000, v0
	v_or3_b32 v0, v8, v0, v2
	v_bitop3_b32 v147, s0, v12, v14 bitop3:0xf6
	s_mov_b64 s[0:1], 0x40080
	v_add_u32_e32 v0, v0, v9
	v_mov_b32_e32 v1, v129
	v_lshl_add_u64 v[132:133], v[0:1], 0, s[0:1]
	v_lshlrev_b32_e32 v0, 4, v11
	v_and_b32_e32 v0, 0x78000, v0
	s_waitcnt vmcnt(6)
	v_or3_b32 v0, v8, v0, v2
	v_add_u32_e32 v0, v0, v9
	v_lshrrev_b32_e32 v146, 2, v176
	v_or_b32_e32 v144, s45, v145
	v_lshl_add_u64 v[134:135], v[0:1], 0, s[0:1]
	v_mov_b64_e32 v[136:137], 0x100
	v_mov_b64_e32 v[138:139], 0xff
	s_add_i32 s49, 0, 0x10000
	s_add_i32 s50, 0, 0x14000
	v_add_u32_e32 v148, 0, v13
	v_mov_b32_e32 v16, v129
	v_mov_b32_e32 v17, v129
	v_mov_b32_e32 v18, v129
	v_mov_b32_e32 v19, v129
	v_mov_b32_e32 v28, v129
	v_mov_b32_e32 v29, v129
	v_mov_b32_e32 v30, v129
	v_mov_b32_e32 v31, v129
	v_mov_b32_e32 v56, v129
	v_mov_b32_e32 v57, v129
	v_mov_b32_e32 v58, v129
	v_mov_b32_e32 v59, v129
	v_mov_b32_e32 v60, v129
	v_mov_b32_e32 v61, v129
	v_mov_b32_e32 v62, v129
	v_mov_b32_e32 v63, v129
	v_mov_b32_e32 v32, v129
	v_mov_b32_e32 v33, v129
	v_mov_b32_e32 v34, v129
	v_mov_b32_e32 v35, v129
	s_waitcnt vmcnt(0)
	v_mov_b32_e32 v76, v129
	v_mov_b32_e32 v77, v129
	v_mov_b32_e32 v78, v129
	v_mov_b32_e32 v79, v129
	v_mov_b32_e32 v24, v129
	v_mov_b32_e32 v25, v129
	v_mov_b32_e32 v26, v129
	v_mov_b32_e32 v27, v129
	v_mov_b32_e32 v64, v129
	v_mov_b32_e32 v65, v129
	v_mov_b32_e32 v66, v129
	v_mov_b32_e32 v67, v129
	v_mov_b32_e32 v40, v129
	v_mov_b32_e32 v41, v129
	v_mov_b32_e32 v42, v129
	v_mov_b32_e32 v43, v129
	v_mov_b32_e32 v44, v129
	v_mov_b32_e32 v45, v129
	v_mov_b32_e32 v46, v129
	v_mov_b32_e32 v47, v129
	v_mov_b32_e32 v68, v129
	v_mov_b32_e32 v69, v129
	v_mov_b32_e32 v70, v129
	v_mov_b32_e32 v71, v129
	v_mov_b32_e32 v72, v129
	v_mov_b32_e32 v73, v129
	v_mov_b32_e32 v74, v129
	v_mov_b32_e32 v75, v129
	v_mov_b32_e32 v84, v129
	v_mov_b32_e32 v85, v129
	v_mov_b32_e32 v86, v129
	v_mov_b32_e32 v87, v129
	v_mov_b32_e32 v88, v129
	v_mov_b32_e32 v89, v129
	v_mov_b32_e32 v90, v129
	v_mov_b32_e32 v91, v129
	v_mov_b32_e32 v96, v129
	v_mov_b32_e32 v97, v129
	v_mov_b32_e32 v98, v129
	v_mov_b32_e32 v99, v129
	v_mov_b32_e32 v104, v129
	v_mov_b32_e32 v105, v129
	v_mov_b32_e32 v106, v129
	v_mov_b32_e32 v107, v129
	v_mov_b32_e32 v12, v129
	v_mov_b32_e32 v13, v129
	v_mov_b32_e32 v14, v129
	v_mov_b32_e32 v15, v129
	v_mov_b32_e32 v48, v129
	v_mov_b32_e32 v49, v129
	v_mov_b32_e32 v50, v129
	v_mov_b32_e32 v51, v129
	v_mov_b32_e32 v8, v129
	v_mov_b32_e32 v9, v129
	v_mov_b32_e32 v10, v129
	v_mov_b32_e32 v11, v129
	v_mov_b32_e32 v36, v129
	v_mov_b32_e32 v37, v129
	v_mov_b32_e32 v38, v129
	v_mov_b32_e32 v39, v129
	v_mov_b32_e32 v4, v129
	v_mov_b32_e32 v5, v129
	v_mov_b32_e32 v6, v129
	v_mov_b32_e32 v7, v129
	v_mov_b32_e32 v20, v129
	v_mov_b32_e32 v21, v129
	v_mov_b32_e32 v22, v129
	v_mov_b32_e32 v23, v129
	v_mov_b32_e32 v0, v129
	v_mov_b32_e32 v2, v129
	v_mov_b32_e32 v3, v129
	v_mov_b32_e32 v52, v129
	v_mov_b32_e32 v53, v129
	v_mov_b32_e32 v54, v129
	v_mov_b32_e32 v55, v129
	v_mov_b32_e32 v112, v129
	v_mov_b32_e32 v113, v129
	v_mov_b32_e32 v114, v129
	v_mov_b32_e32 v115, v129
	v_mov_b32_e32 v124, v129
	v_mov_b32_e32 v125, v129
	v_mov_b32_e32 v126, v129
	v_mov_b32_e32 v127, v129
	v_mov_b32_e32 v100, v129
	v_mov_b32_e32 v101, v129
	v_mov_b32_e32 v102, v129
	v_mov_b32_e32 v103, v129
	v_mov_b32_e32 v120, v129
	v_mov_b32_e32 v121, v129
	v_mov_b32_e32 v122, v129
	v_mov_b32_e32 v123, v129
	v_mov_b32_e32 v92, v129
	v_mov_b32_e32 v93, v129
	v_mov_b32_e32 v94, v129
	v_mov_b32_e32 v95, v129
	v_mov_b32_e32 v116, v129
	v_mov_b32_e32 v117, v129
	v_mov_b32_e32 v118, v129
	v_mov_b32_e32 v119, v129
	v_mov_b32_e32 v80, v129
	v_mov_b32_e32 v81, v129
	v_mov_b32_e32 v82, v129
	v_mov_b32_e32 v83, v129
	v_mov_b32_e32 v108, v129
	v_mov_b32_e32 v109, v129
	v_mov_b32_e32 v110, v129
	v_mov_b32_e32 v111, v129
	s_barrier
	s_branch .LBB0_614

; #define PG8_STAGE(bufoff, gbase, voff) do { _Pragma("unroll") for (int _i = 0; _i < 2; ++_i) \
;         __builtin_amdgcn_global_load_lds((const unsigned*)((const char*)(gbase) + (voff)[_i]), (PG8_LAS unsigned*)(lds + (bufoff) + ldsw + _i * 8192), 16, 0, 0); } while (0)
; #define PG8_LDA(dst, b, h) do { _Pragma("unroll") for (int m = 0; m < 4; ++m) _Pragma("unroll") for (int k = 0; k < 2; ++k) dst[m][k] = *(const PG8_LAS bf16x8*)(lds + PG8_SA(b, h) + aoff + m * 2048 + k * 1024); } while (0)
; #define PG8_LDB(dst, b, h) do { _Pragma("unroll") for (int n = 0; n < 2; ++n) _Pragma("unroll") for (int k = 0; k < 2; ++k) dst[n][k] = *(const PG8_LAS bf16x8*)(lds + PG8_SB(b, h) + boff + n * 2048 + k * 1024); } while (0)
; #define PG8_MMA(ai, bj, At, Bt) do { __builtin_amdgcn_s_setprio(1); _Pragma("unroll") for (int m = 0; m < 4; ++m) _Pragma("unroll") for (int n = 0; n < 2; ++n) _Pragma("unroll") for (int k = 0; k < 2; ++k) \
;         acc[ai][bj][m][n] = __builtin_amdgcn_mfma_f32_16x16x32_bf16(Bt[n][k], At[m][k], acc[ai][bj][m][n], 0, 0, 0); __builtin_amdgcn_s_setprio(0); } while (0)
; #define PG8_WAIT_V(n) asm volatile("s_waitcnt vmcnt(" #n ")" ::: "memory")
; #define PG8_WAIT_L(n) asm volatile("s_waitcnt lgkmcnt(" #n ")" ::: "memory")
; #define PG8_BAR __builtin_amdgcn_s_barrier()
; template <class Epi, class Sched, bool ALIGN_EPI = false, bool SP2 = false>
; __device__ __forceinline__ void gemm_phase(PG8_LAS unsigned char* lds, const Gemm g, const Sched& S, const Epi& E) {
;     ...
;             const char* a1 = cA + (size_t)(t + 1) * kstep;
;             const char* a2 = last ? nA : cA + (size_t)(t + 2) * kstep; const char* b2 = last ? nB : cB + (size_t)(t + 2) * kstep;
;             const char* a3 = a2 + kstep; const char* b3 = b2 + kstep;
;             if (last && has_next) S.a_ready(nxt);
;             if constexpr (SP2) {
;             PG8_LDB(B0, 0, 0); PG8_LDB(B1, 0, 1); PG8_SCHED; PG8_LDA(At, 0, 0); PG8_STAGE(PG8_SA(1, 1), a1 + hstepA, voffA);
;             PG8_WAIT_V(8); PG8_WAIT_L(0); PG8_BAR; PG8_MMA(0, 0, At, B0); PG8_MMA(0, 1, At, B1); PG8_BAR; PG8_SCHED;
;             PG8_LDA(At, 0, 1); PG8_STAGE(PG8_SB(0, 0), b2, voffB); PG8_STAGE(PG8_SB(0, 1), b2 + hstepB, voffB); PG8_STAGE(PG8_SA(0, 0), a2, voffA);
;             PG8_WAIT_V(8); PG8_WAIT_L(0); PG8_BAR; PG8_MMA(1, 0, At, B0); PG8_MMA(1, 1, At, B1); PG8_BAR; PG8_SCHED;
.LBB0_621:
	v_add_u32_e32 v149, s49, v147
	ds_read_b128 v[150:153], v149
	ds_read_b128 v[154:157], v149 offset:1024
	ds_read_b128 v[158:161], v149 offset:2048
	ds_read_b128 v[162:165], v149 offset:3072
	v_add_u32_e32 v149, s50, v147
	s_add_u32 s30, s4, s28
	ds_read_b128 v[166:169], v149
	ds_read_b128 v[170:173], v149 offset:1024
	ds_read_b128 v[178:181], v149 offset:2048
	ds_read_b128 v[182:185], v149 offset:3072
	s_addc_u32 s31, s5, s29
	s_add_u32 s30, s30, 0x100
	s_addc_u32 s31, s31, 0
	s_add_u32 s57, s52, s28
	s_addc_u32 s58, s53, s29
	s_cmpk_eq_i32 s28, 0x700
	s_cselect_b32 s35, s23, s31
	s_cselect_b32 s34, s54, s30
	s_cselect_b32 s31, s21, s58
	s_cselect_b32 s30, s55, s57
	v_lshl_add_u64 v[174:175], v[140:141], 0, s[28:29]
	s_add_i32 m0, s41, 0xc000
	ds_read_b128 v[186:189], v148
	ds_read_b128 v[190:193], v148 offset:1024
	ds_read_b128 v[194:197], v148 offset:2048
	ds_read_b128 v[202:205], v148 offset:3072
	ds_read_b128 v[206:209], v148 offset:4096
	ds_read_b128 v[210:213], v148 offset:5120
	ds_read_b128 v[214:217], v148 offset:6144
	ds_read_b128 v[218:221], v148 offset:7168
	global_load_lds_dwordx4 v[174:175], off
	v_lshl_add_u64 v[174:175], v[142:143], 0, s[28:29]
	s_add_i32 m0, s41, 0xe000
	s_nop 0
	global_load_lds_dwordx4 v[174:175], off
	s_waitcnt vmcnt(8)
	s_waitcnt lgkmcnt(0)
	s_barrier
	s_setprio 1
	s_waitcnt lgkmcnt(0)
	v_mfma_f32_16x16x32_bf16 v[108:111], v[150:153], v[186:189], v[108:111]
	v_mfma_f32_16x16x32_bf16 v[80:83], v[158:161], v[186:189], v[80:83]
	v_mfma_f32_16x16x32_bf16 v[116:119], v[150:153], v[194:197], v[116:119]
	v_mfma_f32_16x16x32_bf16 v[92:95], v[158:161], v[194:197], v[92:95]
	v_mfma_f32_16x16x32_bf16 v[120:123], v[150:153], v[206:209], v[120:123]
	v_mfma_f32_16x16x32_bf16 v[100:103], v[158:161], v[206:209], v[100:103]
	v_mfma_f32_16x16x32_bf16 v[124:127], v[150:153], v[214:217], v[124:127]
	v_mfma_f32_16x16x32_bf16 v[112:115], v[158:161], v[214:217], v[112:115]
	v_mfma_f32_16x16x32_bf16 v[108:111], v[154:157], v[190:193], v[108:111]
	v_mfma_f32_16x16x32_bf16 v[80:83], v[162:165], v[190:193], v[80:83]
	v_mfma_f32_16x16x32_bf16 v[116:119], v[154:157], v[202:205], v[116:119]
	v_mfma_f32_16x16x32_bf16 v[92:95], v[162:165], v[202:205], v[92:95]
	v_mfma_f32_16x16x32_bf16 v[120:123], v[154:157], v[210:213], v[120:123]
	v_mfma_f32_16x16x32_bf16 v[100:103], v[162:165], v[210:213], v[100:103]
	v_mfma_f32_16x16x32_bf16 v[124:127], v[154:157], v[218:221], v[124:127]
	v_mfma_f32_16x16x32_bf16 v[112:115], v[162:165], v[218:221], v[112:115]
	s_setprio 0
	s_setprio 1
	v_mfma_f32_16x16x32_bf16 v[52:55], v[166:169], v[186:189], v[52:55]
	v_mfma_f32_16x16x32_bf16 v[0:3], v[178:181], v[186:189], v[0:3]
	v_mfma_f32_16x16x32_bf16 v[20:23], v[166:169], v[194:197], v[20:23]
	v_mfma_f32_16x16x32_bf16 v[4:7], v[178:181], v[194:197], v[4:7]
	v_mfma_f32_16x16x32_bf16 v[36:39], v[166:169], v[206:209], v[36:39]
	v_mfma_f32_16x16x32_bf16 v[8:11], v[178:181], v[206:209], v[8:11]
	v_mfma_f32_16x16x32_bf16 v[48:51], v[166:169], v[214:217], v[48:51]
	v_mfma_f32_16x16x32_bf16 v[12:15], v[178:181], v[214:217], v[12:15]
	v_mfma_f32_16x16x32_bf16 v[52:55], v[170:173], v[190:193], v[52:55]
	v_mfma_f32_16x16x32_bf16 v[0:3], v[182:185], v[190:193], v[0:3]
	v_mfma_f32_16x16x32_bf16 v[20:23], v[170:173], v[202:205], v[20:23]
	v_mfma_f32_16x16x32_bf16 v[4:7], v[182:185], v[202:205], v[4:7]
	v_mfma_f32_16x16x32_bf16 v[36:39], v[170:173], v[210:213], v[36:39]
	v_mfma_f32_16x16x32_bf16 v[8:11], v[182:185], v[210:213], v[8:11]
	v_mfma_f32_16x16x32_bf16 v[48:51], v[170:173], v[218:221], v[48:51]
	v_mfma_f32_16x16x32_bf16 v[12:15], v[182:185], v[218:221], v[12:15]
	s_setprio 0
	s_barrier
	s_add_i32 s57, s49, s40
	v_lshl_add_u64 v[174:175], s[30:31], 0, v[128:129]
	s_mov_b32 m0, s57
	ds_read_b128 v[186:189], v148 offset:16384
	ds_read_b128 v[190:193], v148 offset:17408
	ds_read_b128 v[194:197], v148 offset:18432
	ds_read_b128 v[202:205], v148 offset:19456
	ds_read_b128 v[206:209], v148 offset:20480
	ds_read_b128 v[210:213], v148 offset:21504
	ds_read_b128 v[214:217], v148 offset:22528
	ds_read_b128 v[218:221], v148 offset:23552
	global_load_lds_dwordx4 v[174:175], off
	s_add_i32 m0, s57, 0x2000
	s_add_u32 s58, s30, 0x40000
	v_lshl_add_u64 v[198:199], s[30:31], 0, v[130:131]
	s_addc_u32 s59, s31, 0
	s_add_i32 s57, s50, s40
	global_load_lds_dwordx4 v[198:199], off
	s_mov_b32 m0, s57
	v_lshl_add_u64 v[224:225], s[34:35], 0, v[130:131]
	global_load_lds_dwordx4 v128, s[58:59]
	s_add_i32 m0, s57, 0x2000
	s_nop 0
	global_load_lds_dwordx4 v130, s[58:59]
	v_lshl_add_u64 v[222:223], s[34:35], 0, v[128:129]
	s_mov_b32 m0, s41
	s_nop 0
	global_load_lds_dwordx4 v[222:223], off
	s_mov_b32 m0, s42
	s_nop 0
	global_load_lds_dwordx4 v[224:225], off
	s_waitcnt vmcnt(8)
	s_waitcnt lgkmcnt(0)
	s_barrier
; #define PG8_STAGE(bufoff, gbase, voff) do { _Pragma("unroll") for (int _i = 0; _i < 2; ++_i) \
;         __builtin_amdgcn_global_load_lds((const unsigned*)((const char*)(gbase) + (voff)[_i]), (PG8_LAS unsigned*)(lds + (bufoff) + ldsw + _i * 8192), 16, 0, 0); } while (0)
; #define PG8_LDA(dst, b, h) do { _Pragma("unroll") for (int m = 0; m < 4; ++m) _Pragma("unroll") for (int k = 0; k < 2; ++k) dst[m][k] = *(const PG8_LAS bf16x8*)(lds + PG8_SA(b, h) + aoff + m * 2048 + k * 1024); } while (0)
; #define PG8_LDB(dst, b, h) do { _Pragma("unroll") for (int n = 0; n < 2; ++n) _Pragma("unroll") for (int k = 0; k < 2; ++k) dst[n][k] = *(const PG8_LAS bf16x8*)(lds + PG8_SB(b, h) + boff + n * 2048 + k * 1024); } while (0)
; #define PG8_MMA(ai, bj, At, Bt) do { __builtin_amdgcn_s_setprio(1); _Pragma("unroll") for (int m = 0; m < 4; ++m) _Pragma("unroll") for (int n = 0; n < 2; ++n) _Pragma("unroll") for (int k = 0; k < 2; ++k) \
;         acc[ai][bj][m][n] = __builtin_amdgcn_mfma_f32_16x16x32_bf16(Bt[n][k], At[m][k], acc[ai][bj][m][n], 0, 0, 0); __builtin_amdgcn_s_setprio(0); } while (0)
; #define PG8_WAIT_V(n) asm volatile("s_waitcnt vmcnt(" #n ")" ::: "memory")
; #define PG8_WAIT_L(n) asm volatile("s_waitcnt lgkmcnt(" #n ")" ::: "memory")
; #define PG8_BAR __builtin_amdgcn_s_barrier()
; #define PG8_SCHED __builtin_amdgcn_sched_barrier(0)
; template <class Epi, class Sched, bool ALIGN_EPI = false, bool SP2 = false>
; __device__ __forceinline__ void gemm_phase(PG8_LAS unsigned char* lds, const Gemm g, const Sched& S, const Epi& E) {
;     ...
;             PG8_WAIT_V(8); PG8_WAIT_L(0); PG8_BAR; PG8_MMA(1, 0, At, B0); PG8_MMA(1, 1, At, B1); PG8_BAR; PG8_SCHED;
;             PG8_LDB(B0, 1, 0); PG8_LDB(B1, 1, 1); PG8_SCHED; PG8_LDA(At, 1, 0); PG8_STAGE(PG8_SA(0, 1), a2 + hstepA, voffA);
;             PG8_WAIT_V(8); PG8_WAIT_L(0); PG8_BAR; PG8_MMA(0, 0, At, B0); PG8_MMA(0, 1, At, B1); PG8_BAR; PG8_SCHED;
	s_setprio 1
	s_waitcnt lgkmcnt(0)
	v_mfma_f32_16x16x32_bf16 v[104:107], v[150:153], v[186:189], v[104:107]
	v_mfma_f32_16x16x32_bf16 v[96:99], v[158:161], v[186:189], v[96:99]
	v_mfma_f32_16x16x32_bf16 v[88:91], v[150:153], v[194:197], v[88:91]
	v_mfma_f32_16x16x32_bf16 v[84:87], v[158:161], v[194:197], v[84:87]
	v_mfma_f32_16x16x32_bf16 v[72:75], v[150:153], v[206:209], v[72:75]
	v_mfma_f32_16x16x32_bf16 v[68:71], v[158:161], v[206:209], v[68:71]
	v_mfma_f32_16x16x32_bf16 v[44:47], v[150:153], v[214:217], v[44:47]
	v_mfma_f32_16x16x32_bf16 v[40:43], v[158:161], v[214:217], v[40:43]
	v_mfma_f32_16x16x32_bf16 v[104:107], v[154:157], v[190:193], v[104:107]
	v_mfma_f32_16x16x32_bf16 v[96:99], v[162:165], v[190:193], v[96:99]
	v_mfma_f32_16x16x32_bf16 v[88:91], v[154:157], v[202:205], v[88:91]
	v_mfma_f32_16x16x32_bf16 v[84:87], v[162:165], v[202:205], v[84:87]
	v_mfma_f32_16x16x32_bf16 v[72:75], v[154:157], v[210:213], v[72:75]
	v_mfma_f32_16x16x32_bf16 v[68:71], v[162:165], v[210:213], v[68:71]
	v_mfma_f32_16x16x32_bf16 v[44:47], v[154:157], v[218:221], v[44:47]
	v_mfma_f32_16x16x32_bf16 v[40:43], v[162:165], v[218:221], v[40:43]
	s_setprio 0
	s_setprio 1
	v_mfma_f32_16x16x32_bf16 v[64:67], v[166:169], v[186:189], v[64:67]
	v_mfma_f32_16x16x32_bf16 v[24:27], v[178:181], v[186:189], v[24:27]
	v_mfma_f32_16x16x32_bf16 v[76:79], v[166:169], v[194:197], v[76:79]
	v_mfma_f32_16x16x32_bf16 v[32:35], v[178:181], v[194:197], v[32:35]
	v_mfma_f32_16x16x32_bf16 v[60:63], v[166:169], v[206:209], v[60:63]
	v_mfma_f32_16x16x32_bf16 v[56:59], v[178:181], v[206:209], v[56:59]
	v_mfma_f32_16x16x32_bf16 v[28:31], v[166:169], v[214:217], v[28:31]
	v_mfma_f32_16x16x32_bf16 v[16:19], v[178:181], v[214:217], v[16:19]
	v_mfma_f32_16x16x32_bf16 v[64:67], v[170:173], v[190:193], v[64:67]
	v_mfma_f32_16x16x32_bf16 v[24:27], v[182:185], v[190:193], v[24:27]
	v_mfma_f32_16x16x32_bf16 v[76:79], v[170:173], v[202:205], v[76:79]
	v_mfma_f32_16x16x32_bf16 v[32:35], v[182:185], v[202:205], v[32:35]
	v_mfma_f32_16x16x32_bf16 v[60:63], v[170:173], v[210:213], v[60:63]
	v_mfma_f32_16x16x32_bf16 v[56:59], v[182:185], v[210:213], v[56:59]
	v_mfma_f32_16x16x32_bf16 v[28:31], v[170:173], v[218:221], v[28:31]
	v_mfma_f32_16x16x32_bf16 v[16:19], v[182:185], v[218:221], v[16:19]
	s_setprio 0
	s_barrier
	s_add_i32 s57, 0, 0x18000
	v_add_u32_e32 v149, s57, v147
	s_add_i32 s58, 0, 0x1c000
	ds_read_b128 v[150:153], v149
	ds_read_b128 v[154:157], v149 offset:1024
	ds_read_b128 v[158:161], v149 offset:2048
	ds_read_b128 v[162:165], v149 offset:3072
	v_add_u32_e32 v149, s58, v147
	ds_read_b128 v[166:169], v149
	ds_read_b128 v[170:173], v149 offset:1024
	ds_read_b128 v[178:181], v149 offset:2048
	ds_read_b128 v[182:185], v149 offset:3072
	s_add_u32 s34, s34, 0x40000
	s_addc_u32 s35, s35, 0
	s_mov_b32 m0, s43
	ds_read_b128 v[186:189], v148 offset:32768
	ds_read_b128 v[190:193], v148 offset:33792
	ds_read_b128 v[194:197], v148 offset:34816
	ds_read_b128 v[202:205], v148 offset:35840
	ds_read_b128 v[206:209], v148 offset:36864
	ds_read_b128 v[210:213], v148 offset:37888
	ds_read_b128 v[214:217], v148 offset:38912
	ds_read_b128 v[218:221], v148 offset:39936
	global_load_lds_dwordx4 v128, s[34:35]
	v_lshl_add_u64 v[226:227], s[34:35], 0, v[130:131]
	s_mov_b32 m0, s44
	s_nop 0
	global_load_lds_dwordx4 v[226:227], off
	s_waitcnt vmcnt(8)
	s_waitcnt lgkmcnt(0)
	s_barrier
	s_setprio 1
	s_waitcnt lgkmcnt(0)
	v_mfma_f32_16x16x32_bf16 v[108:111], v[150:153], v[186:189], v[108:111]
	v_mfma_f32_16x16x32_bf16 v[80:83], v[158:161], v[186:189], v[80:83]
	v_mfma_f32_16x16x32_bf16 v[116:119], v[150:153], v[194:197], v[116:119]
	v_mfma_f32_16x16x32_bf16 v[92:95], v[158:161], v[194:197], v[92:95]
	v_mfma_f32_16x16x32_bf16 v[120:123], v[150:153], v[206:209], v[120:123]
	v_mfma_f32_16x16x32_bf16 v[100:103], v[158:161], v[206:209], v[100:103]
	v_mfma_f32_16x16x32_bf16 v[124:127], v[150:153], v[214:217], v[124:127]
	v_mfma_f32_16x16x32_bf16 v[112:115], v[158:161], v[214:217], v[112:115]
	v_mfma_f32_16x16x32_bf16 v[108:111], v[154:157], v[190:193], v[108:111]
	v_mfma_f32_16x16x32_bf16 v[80:83], v[162:165], v[190:193], v[80:83]
	v_mfma_f32_16x16x32_bf16 v[116:119], v[154:157], v[202:205], v[116:119]
	v_mfma_f32_16x16x32_bf16 v[92:95], v[162:165], v[202:205], v[92:95]
	v_mfma_f32_16x16x32_bf16 v[120:123], v[154:157], v[210:213], v[120:123]
	v_mfma_f32_16x16x32_bf16 v[100:103], v[162:165], v[210:213], v[100:103]
	v_mfma_f32_16x16x32_bf16 v[124:127], v[154:157], v[218:221], v[124:127]
	v_mfma_f32_16x16x32_bf16 v[112:115], v[162:165], v[218:221], v[112:115]
	s_setprio 0
	s_setprio 1
	v_mfma_f32_16x16x32_bf16 v[52:55], v[166:169], v[186:189], v[52:55]
	v_mfma_f32_16x16x32_bf16 v[0:3], v[178:181], v[186:189], v[0:3]
	v_mfma_f32_16x16x32_bf16 v[20:23], v[166:169], v[194:197], v[20:23]
	v_mfma_f32_16x16x32_bf16 v[4:7], v[178:181], v[194:197], v[4:7]
	v_mfma_f32_16x16x32_bf16 v[36:39], v[166:169], v[206:209], v[36:39]
	v_mfma_f32_16x16x32_bf16 v[8:11], v[178:181], v[206:209], v[8:11]
	v_mfma_f32_16x16x32_bf16 v[48:51], v[166:169], v[214:217], v[48:51]
	v_mfma_f32_16x16x32_bf16 v[12:15], v[178:181], v[214:217], v[12:15]
	v_mfma_f32_16x16x32_bf16 v[52:55], v[170:173], v[190:193], v[52:55]
	v_mfma_f32_16x16x32_bf16 v[0:3], v[182:185], v[190:193], v[0:3]
	v_mfma_f32_16x16x32_bf16 v[20:23], v[170:173], v[202:205], v[20:23]
	v_mfma_f32_16x16x32_bf16 v[4:7], v[182:185], v[202:205], v[4:7]
	v_mfma_f32_16x16x32_bf16 v[36:39], v[170:173], v[210:213], v[36:39]
	v_mfma_f32_16x16x32_bf16 v[8:11], v[182:185], v[210:213], v[8:11]
	v_mfma_f32_16x16x32_bf16 v[48:51], v[170:173], v[218:221], v[48:51]
	v_mfma_f32_16x16x32_bf16 v[12:15], v[182:185], v[218:221], v[12:15]
	s_setprio 0
	s_barrier
; #define PG8_WAIT_V(n) asm volatile("s_waitcnt vmcnt(" #n ")" ::: "memory")
; template <class Epi, class Sched, bool ALIGN_EPI = false, bool SP2 = false>
; __device__ __forceinline__ void gemm_phase(PG8_LAS unsigned char* lds, const Gemm g, const Sched& S, const Epi& E) {
;     ...
;             PG8_LDA(At, 1, 1); PG8_STAGE(PG8_SB(1, 0), b3, voffB); PG8_STAGE(PG8_SB(1, 1), b3 + hstepB, voffB); PG8_STAGE(PG8_SA(1, 0), a3, voffA);
;             PG8_WAIT_V(8); PG8_WAIT_L(0); PG8_BAR; PG8_MMA(1, 0, At, B0); PG8_MMA(1, 1, At, B1); PG8_BAR; PG8_SCHED;
;             } else {
;             PG8_LDB(B0, 0, 0); PG8_SCHED; PG8_LDA(At, 0, 0); PG8_STAGE(PG8_SA(1, 1), a1 + hstepA, voffA);
;             PG8_WAIT_L(8); PG8_BAR; PG8_WAIT_L(0); PG8_MMA(0, 0, At, B0); PG8_BAR; PG8_SCHED;
;             PG8_LDB(B1, 0, 1); PG8_STAGE(PG8_SB(0, 0), b2, voffB);
;             PG8_BAR; PG8_WAIT_L(0); PG8_MMA(0, 1, At, B1); PG8_BAR;
;             PG8_LDA(At, 0, 1); PG8_STAGE(PG8_SA(0, 0), a2, voffA);
;             PG8_BAR; PG8_WAIT_L(0); PG8_MMA(1, 0, At, B0); PG8_BAR; PG8_SCHED;
;             PG8_STAGE(PG8_SB(0, 1), b2 + hstepB, voffB);
;             PG8_WAIT_V(6); PG8_BAR; PG8_MMA(1, 1, At, B1); PG8_BAR;
;             PG8_LDB(B0, 1, 0); PG8_SCHED; PG8_LDA(At, 1, 0); PG8_STAGE(PG8_SA(0, 1), a2 + hstepA, voffA);
;             PG8_WAIT_L(8); PG8_BAR; PG8_WAIT_L(0); PG8_MMA(0, 0, At, B0); PG8_BAR; PG8_SCHED;
;             PG8_LDB(B1, 1, 1); PG8_STAGE(PG8_SB(1, 0), b3, voffB);
;             PG8_BAR; PG8_WAIT_L(0); PG8_MMA(0, 1, At, B1); PG8_BAR;
;             PG8_LDA(At, 1, 1); PG8_STAGE(PG8_SA(1, 0), a3, voffA);
;             PG8_BAR; PG8_WAIT_L(0); PG8_MMA(1, 0, At, B0); PG8_BAR; PG8_SCHED;
;             PG8_STAGE(PG8_SB(1, 1), b3 + hstepB, voffB);
;             PG8_WAIT_V(6); PG8_BAR; PG8_MMA(1, 1, At, B1); PG8_BAR;
;             }
;         }
;         if constexpr (ALIGN_EPI) { if (wr == 0) PG8_BAR; }
;         if constexpr (!Epi::AFTER_DRAIN) { E(acc, cur, wr, wc, fr, fq); S.done(cur); }
;         if (!has_next) break;
; #pragma unroll
;         for (int a = 0; a < 2; ++a)
; #pragma unroll
;             for (int b = 0; b < 2; ++b)
; #pragma unroll
;                 for (int m = 0; m < 4; ++m)
; #pragma unroll
;                     for (int n = 0; n < 2; ++n) acc[a][b][m][n] = (f32x4){0.f, 0.f, 0.f, 0.f};
;         cur = nxt; cA = nA; cB = nB; ++ui;
	s_add_i32 s34, s57, s40
	v_lshl_add_u64 v[174:175], v[174:175], 0, s[18:19]
	s_mov_b32 m0, s34
	ds_read_b128 v[186:189], v148 offset:49152
	ds_read_b128 v[190:193], v148 offset:50176
	ds_read_b128 v[194:197], v148 offset:51200
	ds_read_b128 v[202:205], v148 offset:52224
	ds_read_b128 v[206:209], v148 offset:53248
	ds_read_b128 v[210:213], v148 offset:54272
	ds_read_b128 v[214:217], v148 offset:55296
	ds_read_b128 v[218:221], v148 offset:56320
	global_load_lds_dwordx4 v[174:175], off
	s_add_i32 m0, s34, 0x2000
	s_add_u32 s30, s30, 0x40080
	v_lshl_add_u64 v[174:175], v[198:199], 0, s[18:19]
	s_addc_u32 s31, s31, 0
	s_add_i32 s34, s58, s40
	global_load_lds_dwordx4 v[174:175], off
	s_mov_b32 m0, s34
	s_nop 0
	global_load_lds_dwordx4 v128, s[30:31]
	s_add_i32 m0, s34, 0x2000
	s_nop 0
	global_load_lds_dwordx4 v130, s[30:31]
	v_lshl_add_u64 v[174:175], v[222:223], 0, s[18:19]
	s_mov_b32 m0, s47
	s_nop 0
	global_load_lds_dwordx4 v[174:175], off
	v_lshl_add_u64 v[174:175], v[224:225], 0, s[18:19]
	s_mov_b32 m0, s48
	s_nop 0
	global_load_lds_dwordx4 v[174:175], off
	s_waitcnt vmcnt(8)
	s_waitcnt lgkmcnt(0)
	s_barrier
	s_setprio 1
	s_waitcnt lgkmcnt(0)
	v_mfma_f32_16x16x32_bf16 v[104:107], v[150:153], v[186:189], v[104:107]
	v_mfma_f32_16x16x32_bf16 v[96:99], v[158:161], v[186:189], v[96:99]
	v_mfma_f32_16x16x32_bf16 v[88:91], v[150:153], v[194:197], v[88:91]
	v_mfma_f32_16x16x32_bf16 v[84:87], v[158:161], v[194:197], v[84:87]
	v_mfma_f32_16x16x32_bf16 v[72:75], v[150:153], v[206:209], v[72:75]
	v_mfma_f32_16x16x32_bf16 v[68:71], v[158:161], v[206:209], v[68:71]
	v_mfma_f32_16x16x32_bf16 v[44:47], v[150:153], v[214:217], v[44:47]
	v_mfma_f32_16x16x32_bf16 v[40:43], v[158:161], v[214:217], v[40:43]
	v_mfma_f32_16x16x32_bf16 v[104:107], v[154:157], v[190:193], v[104:107]
	v_mfma_f32_16x16x32_bf16 v[96:99], v[162:165], v[190:193], v[96:99]
	v_mfma_f32_16x16x32_bf16 v[88:91], v[154:157], v[202:205], v[88:91]
	v_mfma_f32_16x16x32_bf16 v[84:87], v[162:165], v[202:205], v[84:87]
	v_mfma_f32_16x16x32_bf16 v[72:75], v[154:157], v[210:213], v[72:75]
	v_mfma_f32_16x16x32_bf16 v[68:71], v[162:165], v[210:213], v[68:71]
	v_mfma_f32_16x16x32_bf16 v[44:47], v[154:157], v[218:221], v[44:47]
	v_mfma_f32_16x16x32_bf16 v[40:43], v[162:165], v[218:221], v[40:43]
	s_setprio 0
	s_setprio 1
	v_mfma_f32_16x16x32_bf16 v[64:67], v[166:169], v[186:189], v[64:67]
	v_mfma_f32_16x16x32_bf16 v[24:27], v[178:181], v[186:189], v[24:27]
	v_mfma_f32_16x16x32_bf16 v[76:79], v[166:169], v[194:197], v[76:79]
	v_mfma_f32_16x16x32_bf16 v[32:35], v[178:181], v[194:197], v[32:35]
	v_mfma_f32_16x16x32_bf16 v[60:63], v[166:169], v[206:209], v[60:63]
	v_mfma_f32_16x16x32_bf16 v[56:59], v[178:181], v[206:209], v[56:59]
	v_mfma_f32_16x16x32_bf16 v[28:31], v[166:169], v[214:217], v[28:31]
	v_mfma_f32_16x16x32_bf16 v[16:19], v[178:181], v[214:217], v[16:19]
	v_mfma_f32_16x16x32_bf16 v[64:67], v[170:173], v[190:193], v[64:67]
	v_mfma_f32_16x16x32_bf16 v[24:27], v[182:185], v[190:193], v[24:27]
	v_mfma_f32_16x16x32_bf16 v[76:79], v[170:173], v[202:205], v[76:79]
	v_mfma_f32_16x16x32_bf16 v[32:35], v[182:185], v[202:205], v[32:35]
	v_mfma_f32_16x16x32_bf16 v[60:63], v[170:173], v[210:213], v[60:63]
	v_mfma_f32_16x16x32_bf16 v[56:59], v[182:185], v[210:213], v[56:59]
	v_mfma_f32_16x16x32_bf16 v[28:31], v[170:173], v[218:221], v[28:31]
	v_mfma_f32_16x16x32_bf16 v[16:19], v[182:185], v[218:221], v[16:19]
	s_setprio 0
	s_barrier
	s_add_i32 s56, s56, 2
	s_add_u32 s28, s28, 0x100
	s_addc_u32 s29, s29, 0
	s_cmp_gt_u32 s56, 13
	s_cbranch_scc0 .LBB0_621
	s_add_u32 s28, s52, 0xffffff00
	s_addc_u32 s29, s53, -1
	s_andn2_b64 vcc, exec, s[2:3]
	s_cbranch_vccnz .LBB0_612
	v_mov_b32_e32 v16, 0
	s_mov_b32 s14, s20
	s_mov_b32 s16, s22
	s_mov_b64 s[4:5], s[26:27]
	s_mov_b32 s46, s51
	v_mov_b32_e32 v17, v16
	v_mov_b32_e32 v18, v16
	v_mov_b32_e32 v19, v16
	v_mov_b32_e32 v28, v16
	v_mov_b32_e32 v29, v16
	v_mov_b32_e32 v30, v16
	v_mov_b32_e32 v31, v16
	v_mov_b32_e32 v56, v16
	v_mov_b32_e32 v57, v16
	v_mov_b32_e32 v58, v16
	v_mov_b32_e32 v59, v16
	v_mov_b32_e32 v60, v16
	v_mov_b32_e32 v61, v16
	v_mov_b32_e32 v62, v16
	v_mov_b32_e32 v63, v16
	v_mov_b32_e32 v32, v16
	v_mov_b32_e32 v33, v16
	v_mov_b32_e32 v34, v16
	v_mov_b32_e32 v35, v16
	v_mov_b32_e32 v76, v16
	v_mov_b32_e32 v77, v16
	v_mov_b32_e32 v78, v16
	v_mov_b32_e32 v79, v16
	v_mov_b32_e32 v24, v16
	v_mov_b32_e32 v25, v16
	v_mov_b32_e32 v26, v16
	v_mov_b32_e32 v27, v16
	v_mov_b32_e32 v64, v16
	v_mov_b32_e32 v65, v16
	v_mov_b32_e32 v66, v16
	v_mov_b32_e32 v67, v16
	v_mov_b32_e32 v40, v16
	v_mov_b32_e32 v41, v16
	v_mov_b32_e32 v42, v16
	v_mov_b32_e32 v43, v16
	v_mov_b32_e32 v44, v16
	v_mov_b32_e32 v45, v16
	v_mov_b32_e32 v46, v16
	v_mov_b32_e32 v47, v16
	v_mov_b32_e32 v68, v16
	v_mov_b32_e32 v69, v16
	v_mov_b32_e32 v70, v16
	v_mov_b32_e32 v71, v16
	v_mov_b32_e32 v72, v16
	v_mov_b32_e32 v73, v16
	v_mov_b32_e32 v74, v16
	v_mov_b32_e32 v75, v16
	v_mov_b32_e32 v84, v16
	v_mov_b32_e32 v85, v16
	v_mov_b32_e32 v86, v16
	v_mov_b32_e32 v87, v16
	v_mov_b32_e32 v88, v16
	v_mov_b32_e32 v89, v16
	v_mov_b32_e32 v90, v16
	v_mov_b32_e32 v91, v16
	v_mov_b32_e32 v96, v16
	v_mov_b32_e32 v97, v16
	v_mov_b32_e32 v98, v16
	v_mov_b32_e32 v99, v16
	v_mov_b32_e32 v104, v16
	v_mov_b32_e32 v105, v16
	v_mov_b32_e32 v106, v16
	v_mov_b32_e32 v107, v16
	v_mov_b32_e32 v12, v16
	v_mov_b32_e32 v13, v16
	v_mov_b32_e32 v14, v16
	v_mov_b32_e32 v15, v16
	v_mov_b32_e32 v48, v16
	v_mov_b32_e32 v49, v16
	v_mov_b32_e32 v50, v16
	v_mov_b32_e32 v51, v16
	v_mov_b32_e32 v8, v16
	v_mov_b32_e32 v9, v16
	v_mov_b32_e32 v10, v16
	v_mov_b32_e32 v11, v16
	v_mov_b32_e32 v36, v16
	v_mov_b32_e32 v37, v16
	v_mov_b32_e32 v38, v16
	v_mov_b32_e32 v39, v16
	v_mov_b32_e32 v4, v16
	v_mov_b32_e32 v5, v16
	v_mov_b32_e32 v6, v16
	v_mov_b32_e32 v7, v16
	v_mov_b32_e32 v20, v16
	v_mov_b32_e32 v21, v16
	v_mov_b32_e32 v22, v16
	v_mov_b32_e32 v23, v16
	v_mov_b32_e32 v0, v16
	v_mov_b32_e32 v1, v16
	v_mov_b32_e32 v2, v16
	v_mov_b32_e32 v3, v16
	v_mov_b32_e32 v52, v16
	v_mov_b32_e32 v53, v16
	v_mov_b32_e32 v54, v16
	v_mov_b32_e32 v55, v16
	v_mov_b32_e32 v112, v16
	v_mov_b32_e32 v113, v16
	v_mov_b32_e32 v114, v16
	v_mov_b32_e32 v115, v16
	v_mov_b32_e32 v124, v16
	v_mov_b32_e32 v125, v16
	v_mov_b32_e32 v126, v16
	v_mov_b32_e32 v127, v16
	v_mov_b32_e32 v100, v16
	v_mov_b32_e32 v101, v16
	v_mov_b32_e32 v102, v16
	v_mov_b32_e32 v103, v16
	v_mov_b32_e32 v120, v16
	v_mov_b32_e32 v121, v16
	v_mov_b32_e32 v122, v16
	v_mov_b32_e32 v123, v16
	v_mov_b32_e32 v92, v16
	v_mov_b32_e32 v93, v16
	v_mov_b32_e32 v94, v16
	v_mov_b32_e32 v95, v16
	v_mov_b32_e32 v116, v16
	v_mov_b32_e32 v117, v16
	v_mov_b32_e32 v118, v16
	v_mov_b32_e32 v119, v16
	v_mov_b32_e32 v80, v16
	v_mov_b32_e32 v81, v16
	v_mov_b32_e32 v82, v16
	v_mov_b32_e32 v83, v16
	v_mov_b32_e32 v108, v16
	v_mov_b32_e32 v109, v16
	v_mov_b32_e32 v110, v16
	v_mov_b32_e32 v111, v16
	s_andn2_b64 vcc, exec, s[0:1]
	s_cbranch_vccnz .LBB0_613

; #define PG8_BAR __builtin_amdgcn_s_barrier()
;     __device__ __forceinline__ void operator()(const f32x4 (&acc)[2][2][4][2], const Unit& u, int wr, int wc, int fr, int fq) const {
;         typedef unsigned u32x2v __attribute__((ext_vector_type(2)));
;         const int nup = 2 * dff;
;         if (fr >= 14) {
; #pragma unroll
;             for (int ai = 0; ai < 2; ++ai)
; #pragma unroll
;                 for (int bj = 0; bj < 2; ++bj)
; #pragma unroll
;                     for (int n = 0; n < 2; ++n) *(PG8_LAS f32x4*)(hx + (((2 * ai + wr) * 2 + (fr - 14)) * 2 + bj) * 128 + wc * 32 + 8 * fq + 4 * n) = acc[ai][bj][3][n];
;         }
;         asm volatile("s_waitcnt lgkmcnt(0)\n\ts_barrier" ::: "memory");
;         const int row_base = 254 * u.pm - 2, colh = u.pn * 128 + wc * 32 + 8 * fq;
; #pragma unroll
;         for (int n = 0; n < 2; ++n) {
;             const int c = colh + 4 * n;
;             const f32x4 w0a = *(const f32x4*)(wcv + c), w1a = *(const f32x4*)(wcv + nup + c), w2a = *(const f32x4*)(wcv + 2 * nup + c), ba = *(const f32x4*)(bcv + c);
;             const f32x4 w0g = *(const f32x4*)(wcv + dff + c), w1g = *(const f32x4*)(wcv + nup + dff + c), w2g = *(const f32x4*)(wcv + 2 * nup + dff + c), bg = *(const f32x4*)(bcv + dff + c);
; #pragma unroll
;             for (int ai = 0; ai < 2; ++ai) {
;                 const int sidx = 2 * ai + wr;
;                 f32x4 h1[2], h2[2];
; #pragma unroll
;                 for (int bj = 0; bj < 2; ++bj) {
;                     if (sidx > 0) { h1[bj] = *(const PG8_LAS f32x4*)(hx + (((sidx - 1) * 2 + 1) * 2 + bj) * 128 + wc * 32 + 8 * fq + 4 * n);
;                                     h2[bj] = *(const PG8_LAS f32x4*)(hx + (((sidx - 1) * 2 + (fr ? 1 : 0)) * 2 + bj) * 128 + wc * 32 + 8 * fq + 4 * n); }
; template <class Epi, class Sched, bool ALIGN_EPI = false, bool SP2 = false>
; __device__ __forceinline__ void gemm_phase(PG8_LAS unsigned char* lds, const Gemm g, const Sched& S, const Epi& E) {
;     ...
;         PG8_STAGE(PG8_SB(0, 0), cB, voffB); PG8_STAGE(PG8_SB(0, 1), cB + hstepB, voffB); PG8_STAGE(PG8_SA(0, 0), cA, voffA); PG8_STAGE(PG8_SA(0, 1), cA + hstepA, voffA);
;         if (wr == 1) PG8_BAR;
;         PG8_WAIT_V(2); PG8_BAR;
;         PG8_STAGE(PG8_SB(1, 0), cB + kstep, voffB); PG8_STAGE(PG8_SA(1, 0), cA + kstep, voffA); PG8_STAGE(PG8_SB(1, 1), cB + hstepB + kstep, voffB);
;         PG8_WAIT_V(6); PG8_BAR;
.LBB0_731:
	v_bfe_u32 v13, v176, 4, 2
	v_and_b32_e32 v12, 15, v176
	v_lshlrev_b32_e32 v15, 4, v13
	v_lshlrev_b32_e32 v17, 2, v176
	v_lshl_or_b32 v16, v12, 6, v15
	s_lshl_b32 s2, s0, 13
	v_and_b32_e32 v17, 32, v17
	s_mov_b64 s[84:85], 0x80
	s_and_b32 s1, s1, 3
	v_bitop3_b32 v16, v16, s2, v17 bitop3:0xde
	v_lshlrev_b32_e32 v18, 6, v176
	s_movk_i32 s2, 0x3c0
	s_add_i32 m0, s83, 0x18000
	v_lshl_add_u64 v[6:7], v[6:7], 0, s[84:85]
	v_and_or_b32 v15, v18, s2, v15
	s_lshl_b32 s2, s1, 12
	s_waitcnt vmcnt(2)
	s_barrier
	global_load_lds_dwordx4 v[6:7], off
	v_lshl_add_u64 v[4:5], v[4:5], 0, s[84:85]
	s_add_i32 m0, s83, 0x1a000
	s_add_i32 s33, s83, 0x8000
	s_add_i32 s61, s83, 0xa000
	v_bitop3_b32 v201, s2, v15, v17 bitop3:0xf6
	global_load_lds_dwordx4 v[4:5], off
	v_lshl_add_u64 v[2:3], v[2:3], 0, s[84:85]
	s_mov_b32 m0, s33
	s_add_u32 s2, s10, 0x40080
	global_load_lds_dwordx4 v[2:3], off
	v_lshl_add_u64 v[0:1], v[0:1], 0, s[84:85]
	s_mov_b32 m0, s61
	s_addc_u32 s3, s11, 0
	global_load_lds_dwordx4 v[0:1], off
	s_add_i32 m0, s83, 0x1c000
	global_load_lds_dwordx4 v180, s[2:3]
	v_lshl_add_u64 v[0:1], s[2:3], 0, v[184:185]
	s_add_i32 m0, s83, 0x1e000
	s_cmpk_lt_u32 s4, 0x100
	global_load_lds_dwordx4 v[0:1], off
	s_cselect_b64 s[2:3], -1, 0
	v_writelane_b32 v242, s2, 32
	s_cmpk_gt_u32 s4, 0xff
	v_lshl_or_b32 v177, s0, 6, v12
	v_writelane_b32 v242, s3, 33
	v_cmp_lt_u32_e64 s[2:3], 13, v12
	s_cselect_b64 s[88:89], -1, 0
	s_lshl_b32 s0, s0, 11
	v_writelane_b32 v242, s2, 34
	v_cmp_lt_u32_e64 s[4:5], 1, v177
	v_lshlrev_b32_e32 v4, 8, v176
	v_writelane_b32 v242, s3, 35
	s_add_i32 s3, s0, 0xfffffc00
	v_writelane_b32 v242, s3, 36
	v_writelane_b32 v242, s4, 37
	s_ashr_i32 s3, s90, 31
	s_lshl_b32 s2, s1, 7
	v_writelane_b32 v242, s5, 38
	s_mov_b32 s4, s90
	v_writelane_b32 v242, s4, 39
	s_add_i32 s2, s2, 0
	v_and_b32_e32 v4, 0x38000, v4
	v_writelane_b32 v242, s5, 40
	v_writelane_b32 v242, s3, 41
	s_ashr_i32 s3, s97, 31
	v_writelane_b32 v242, s3, 42
	s_add_i32 s3, s2, 0x20000
	v_readlane_b32 s16, v242, 0
	v_readlane_b32 s17, v242, 1
	v_readlane_b32 s18, v242, 2
	v_readlane_b32 s19, v242, 3
	v_readlane_b32 s28, v242, 12
	v_readlane_b32 s29, v242, 13
	s_add_i32 s2, s2, 0x21000
	v_readlane_b32 s30, v242, 14
	v_readlane_b32 s31, v242, 15
	s_mov_b64 s[16:17], s[28:29]
	s_add_u32 s4, s16, 0x5800
	s_addc_u32 s5, s17, 0
	v_readlane_b32 s20, v242, 4
	v_readlane_b32 s21, v242, 5
	v_readlane_b32 s22, v242, 6
	v_readlane_b32 s23, v242, 7
	v_readlane_b32 s24, v242, 8
	v_readlane_b32 s25, v242, 9
	v_readlane_b32 s26, v242, 10
	v_readlane_b32 s27, v242, 11
	v_writelane_b32 v242, s4, 43
	v_lshlrev_b32_e32 v5, 11, v10
	v_lshl_add_u32 v1, v12, 10, s0
	v_writelane_b32 v242, s5, 44
	s_add_u32 s4, s16, 0xb000
	s_addc_u32 s5, s17, 0
	v_writelane_b32 v242, s4, 45
	s_mov_b64 s[18:19], s[30:31]
	v_or3_b32 v4, v8, v4, v5
	v_writelane_b32 v242, s5, 46
	s_add_u32 s4, s16, 0x2c00
	s_addc_u32 s5, s17, 0
	v_writelane_b32 v242, s4, 47
	v_lshlrev_b32_e32 v0, 5, v13
	v_add_u32_e32 v1, 0xffffc800, v1
	v_writelane_b32 v242, s5, 48
	s_add_u32 s4, s16, 0x8400
	s_addc_u32 s5, s17, 0
	s_add_u32 s76, s16, 0xdc00
	s_addc_u32 s77, s17, 0
	v_mov_b32_e32 v2, 0xfffffc00
	v_mov_b32_e32 v3, 0xfffff800
	v_cmp_eq_u32_e32 vcc, 0, v12
	s_add_u32 s74, s18, 0x2c00
	v_add_u32_e32 v186, v4, v9
	v_lshlrev_b32_e32 v4, 4, v11
	s_waitcnt vmcnt(6)
	v_cndmask_b32_e32 v2, v2, v3, vcc
	v_add_u32_e32 v3, s3, v1
	s_addc_u32 s75, s19, 0
	v_add_u32_e32 v209, s3, v0
	s_add_i32 s3, s3, s0
	v_and_b32_e32 v4, 0x78000, v4
	v_lshlrev_b32_e32 v14, 3, v13
	v_add_u32_e32 v1, s2, v1
	v_add3_u32 v210, s3, v2, v0
	v_add_u32_e32 v211, s0, v209
	v_add_u32_e32 v2, v209, v2
	v_or3_b32 v4, v8, v4, v5
	s_add_i32 s92, 0, 0x10000
	s_add_i32 s93, 0, 0x14000
	v_or_b32_e32 v202, 16, v177
	v_or_b32_e32 v203, 32, v177
	v_or_b32_e32 v204, 48, v177
	v_add_u32_e32 v205, 0x80, v177
	v_add_u32_e32 v206, 0x90, v177
	v_add_u32_e32 v207, 0xa0, v177
	v_add_u32_e32 v208, 0xb0, v177
	v_writelane_b32 v242, s4, 49
	v_add_u32_e32 v212, 0xfffffe00, v211
	v_add_u32_e32 v213, 0xfffffe10, v211
	v_lshl_or_b32 v214, s1, 5, v14
	v_mov_b32_e32 v187, v181
	v_add_u32_e32 v188, v4, v9
	v_mov_b32_e32 v189, v181
	v_mov_b64_e32 v[190:191], 0x596
	v_mov_b64_e32 v[192:193], 0x595
	v_add_u32_e32 v215, s92, v201
	v_add_u32_e32 v216, s93, v201
	v_add_u32_e32 v217, 0, v16
	v_add_u32_e32 v218, v3, v0
	v_add_u32_e32 v219, v1, v0
	s_mov_b32 s72, 0xbf38aa3b
	s_mov_b32 s80, 0x3e6d3388
	s_mov_b32 s60, 0x3f07dc22
	s_mov_b32 s56, 0xbf3a00e3
	s_mov_b32 s58, 0x3f35f0e3
	s_mov_b32 s82, 0xbe11a98e
	s_mov_b32 s86, 0x3e027906
	s_movk_i32 s94, 0x1600
	v_add_u32_e32 v220, s0, v2
	s_mov_b32 s95, 0
	s_barrier
	v_writelane_b32 v242, s5, 50
	s_branch .LBB0_734

; #define PG8_STAGE(bufoff, gbase, voff) do { _Pragma("unroll") for (int _i = 0; _i < 2; ++_i) \
;         __builtin_amdgcn_global_load_lds((const unsigned*)((const char*)(gbase) + (voff)[_i]), (PG8_LAS unsigned*)(lds + (bufoff) + ldsw + _i * 8192), 16, 0, 0); } while (0)
; #define PG8_LDA(dst, b, h) do { _Pragma("unroll") for (int m = 0; m < 4; ++m) _Pragma("unroll") for (int k = 0; k < 2; ++k) dst[m][k] = *(const PG8_LAS bf16x8*)(lds + PG8_SA(b, h) + aoff + m * 2048 + k * 1024); } while (0)
; #define PG8_LDB(dst, b, h) do { _Pragma("unroll") for (int n = 0; n < 2; ++n) _Pragma("unroll") for (int k = 0; k < 2; ++k) dst[n][k] = *(const PG8_LAS bf16x8*)(lds + PG8_SB(b, h) + boff + n * 2048 + k * 1024); } while (0)
; #define PG8_MMA(ai, bj, At, Bt) do { __builtin_amdgcn_s_setprio(1); _Pragma("unroll") for (int m = 0; m < 4; ++m) _Pragma("unroll") for (int n = 0; n < 2; ++n) _Pragma("unroll") for (int k = 0; k < 2; ++k) \
;         acc[ai][bj][m][n] = __builtin_amdgcn_mfma_f32_16x16x32_bf16(Bt[n][k], At[m][k], acc[ai][bj][m][n], 0, 0, 0); __builtin_amdgcn_s_setprio(0); } while (0)
; #define PG8_WAIT_V(n) asm volatile("s_waitcnt vmcnt(" #n ")" ::: "memory")
; #define PG8_WAIT_L(n) asm volatile("s_waitcnt lgkmcnt(" #n ")" ::: "memory")
; #define PG8_BAR __builtin_amdgcn_s_barrier()
; template <class Epi, class Sched, bool ALIGN_EPI = false, bool SP2 = false>
; __device__ __forceinline__ void gemm_phase(PG8_LAS unsigned char* lds, const Gemm g, const Sched& S, const Epi& E) {
;     ...
;             const char* a1 = cA + (size_t)(t + 1) * kstep;
;             const char* a2 = last ? nA : cA + (size_t)(t + 2) * kstep; const char* b2 = last ? nB : cB + (size_t)(t + 2) * kstep;
;             const char* a3 = a2 + kstep; const char* b3 = b2 + kstep;
;             if (last && has_next) S.a_ready(nxt);
;             if constexpr (SP2) {
;             PG8_LDB(B0, 0, 0); PG8_LDB(B1, 0, 1); PG8_SCHED; PG8_LDA(At, 0, 0); PG8_STAGE(PG8_SA(1, 1), a1 + hstepA, voffA);
;             PG8_WAIT_V(8); PG8_WAIT_L(0); PG8_BAR; PG8_MMA(0, 0, At, B0); PG8_MMA(0, 1, At, B1); PG8_BAR; PG8_SCHED;
;             PG8_LDA(At, 0, 1); PG8_STAGE(PG8_SB(0, 0), b2, voffB); PG8_STAGE(PG8_SB(0, 1), b2 + hstepB, voffB); PG8_STAGE(PG8_SA(0, 0), a2, voffA);
;             PG8_WAIT_V(8); PG8_WAIT_L(0); PG8_BAR; PG8_MMA(1, 0, At, B0); PG8_MMA(1, 1, At, B1); PG8_BAR; PG8_SCHED;
.LBB0_743:
	ds_read_b128 v[96:99], v215
	ds_read_b128 v[100:103], v215 offset:1024
	ds_read_b128 v[104:107], v215 offset:2048
	ds_read_b128 v[108:111], v215 offset:3072
	ds_read_b128 v[112:115], v216
	ds_read_b128 v[116:119], v216 offset:1024
	ds_read_b128 v[120:123], v216 offset:2048
	ds_read_b128 v[124:127], v216 offset:3072
	s_add_u32 s10, s0, 0xfffc0080
	s_addc_u32 s11, s1, -1
	s_cmp_eq_u32 s17, 12
	s_cselect_b32 s13, s5, s11
	s_cselect_b32 s12, s4, s10
	s_cselect_b32 s11, s3, s16
	s_cselect_b32 s10, s7, s15
	s_add_i32 m0, s83, 0xc000
	ds_read_b128 v[160:163], v217
	ds_read_b128 v[164:167], v217 offset:1024
	ds_read_b128 v[168:171], v217 offset:2048
	ds_read_b128 v[172:175], v217 offset:3072
	ds_read_b128 v[194:197], v217 offset:4096
	ds_read_b128 v[222:225], v217 offset:5120
	ds_read_b128 v[226:229], v217 offset:6144
	ds_read_b128 v[230:233], v217 offset:7168
	global_load_lds_dwordx4 v186, s[0:1]
	s_add_i32 m0, s83, 0xe000
	s_nop 0
	global_load_lds_dwordx4 v188, s[0:1]
	s_waitcnt vmcnt(8)
	s_waitcnt lgkmcnt(0)
	s_barrier
	s_setprio 1
	s_waitcnt lgkmcnt(0)
	v_mfma_f32_16x16x32_bf16 v[156:159], v[96:99], v[160:163], v[156:159]
	v_mfma_f32_16x16x32_bf16 v[60:63], v[104:107], v[160:163], v[60:63]
	v_mfma_f32_16x16x32_bf16 v[148:151], v[96:99], v[168:171], v[148:151]
	v_mfma_f32_16x16x32_bf16 v[52:55], v[104:107], v[168:171], v[52:55]
	v_mfma_f32_16x16x32_bf16 v[136:139], v[96:99], v[194:197], v[136:139]
	v_mfma_f32_16x16x32_bf16 v[40:43], v[104:107], v[194:197], v[40:43]
	v_mfma_f32_16x16x32_bf16 v[140:143], v[96:99], v[226:229], v[140:143]
	v_mfma_f32_16x16x32_bf16 v[44:47], v[104:107], v[226:229], v[44:47]
	v_mfma_f32_16x16x32_bf16 v[156:159], v[100:103], v[164:167], v[156:159]
	v_mfma_f32_16x16x32_bf16 v[60:63], v[108:111], v[164:167], v[60:63]
	v_mfma_f32_16x16x32_bf16 v[148:151], v[100:103], v[172:175], v[148:151]
	v_mfma_f32_16x16x32_bf16 v[52:55], v[108:111], v[172:175], v[52:55]
	v_mfma_f32_16x16x32_bf16 v[136:139], v[100:103], v[222:225], v[136:139]
	v_mfma_f32_16x16x32_bf16 v[40:43], v[108:111], v[222:225], v[40:43]
	v_mfma_f32_16x16x32_bf16 v[140:143], v[100:103], v[230:233], v[140:143]
	v_mfma_f32_16x16x32_bf16 v[44:47], v[108:111], v[230:233], v[44:47]
	s_setprio 0
	s_setprio 1
	v_mfma_f32_16x16x32_bf16 v[152:155], v[112:115], v[160:163], v[152:155]
	v_mfma_f32_16x16x32_bf16 v[56:59], v[120:123], v[160:163], v[56:59]
	v_mfma_f32_16x16x32_bf16 v[144:147], v[112:115], v[168:171], v[144:147]
	v_mfma_f32_16x16x32_bf16 v[48:51], v[120:123], v[168:171], v[48:51]
	v_mfma_f32_16x16x32_bf16 v[128:131], v[112:115], v[194:197], v[128:131]
	v_mfma_f32_16x16x32_bf16 v[32:35], v[120:123], v[194:197], v[32:35]
	v_mfma_f32_16x16x32_bf16 v[132:135], v[112:115], v[226:229], v[132:135]
	v_mfma_f32_16x16x32_bf16 v[36:39], v[120:123], v[226:229], v[36:39]
	v_mfma_f32_16x16x32_bf16 v[152:155], v[116:119], v[164:167], v[152:155]
	v_mfma_f32_16x16x32_bf16 v[56:59], v[124:127], v[164:167], v[56:59]
	v_mfma_f32_16x16x32_bf16 v[144:147], v[116:119], v[172:175], v[144:147]
	v_mfma_f32_16x16x32_bf16 v[48:51], v[124:127], v[172:175], v[48:51]
	v_mfma_f32_16x16x32_bf16 v[128:131], v[116:119], v[222:225], v[128:131]
	v_mfma_f32_16x16x32_bf16 v[32:35], v[124:127], v[222:225], v[32:35]
	v_mfma_f32_16x16x32_bf16 v[132:135], v[116:119], v[230:233], v[132:135]
	v_mfma_f32_16x16x32_bf16 v[36:39], v[124:127], v[230:233], v[36:39]
	s_setprio 0
	s_barrier
	s_add_i32 s18, s92, s81
	v_lshl_add_u64 v[198:199], s[10:11], 0, v[180:181]
	s_mov_b32 m0, s18
	ds_read_b128 v[160:163], v217 offset:16384
	ds_read_b128 v[164:167], v217 offset:17408
	ds_read_b128 v[168:171], v217 offset:18432
	ds_read_b128 v[172:175], v217 offset:19456
	ds_read_b128 v[194:197], v217 offset:20480
	ds_read_b128 v[222:225], v217 offset:21504
	ds_read_b128 v[226:229], v217 offset:22528
	ds_read_b128 v[230:233], v217 offset:23552
	global_load_lds_dwordx4 v[198:199], off
	s_add_i32 m0, s18, 0x2000
	s_add_u32 s18, s10, 0x40000
	v_lshl_add_u64 v[234:235], s[10:11], 0, v[184:185]
	s_addc_u32 s19, s11, 0
	s_add_i32 s20, s93, s81
	global_load_lds_dwordx4 v[234:235], off
	s_mov_b32 m0, s20
	v_lshl_add_u64 v[238:239], s[12:13], 0, v[182:183]
	global_load_lds_dwordx4 v180, s[18:19]
	s_add_i32 m0, s20, 0x2000
	s_nop 0
	global_load_lds_dwordx4 v184, s[18:19]
	v_lshl_add_u64 v[236:237], s[12:13], 0, v[178:179]
	s_mov_b32 m0, s83
	s_nop 0
	global_load_lds_dwordx4 v[236:237], off
	s_mov_b32 m0, s87
	s_nop 0
	global_load_lds_dwordx4 v[238:239], off
	s_waitcnt vmcnt(8)
	s_waitcnt lgkmcnt(0)
	s_barrier
; #define PG8_STAGE(bufoff, gbase, voff) do { _Pragma("unroll") for (int _i = 0; _i < 2; ++_i) \
;         __builtin_amdgcn_global_load_lds((const unsigned*)((const char*)(gbase) + (voff)[_i]), (PG8_LAS unsigned*)(lds + (bufoff) + ldsw + _i * 8192), 16, 0, 0); } while (0)
; #define PG8_LDA(dst, b, h) do { _Pragma("unroll") for (int m = 0; m < 4; ++m) _Pragma("unroll") for (int k = 0; k < 2; ++k) dst[m][k] = *(const PG8_LAS bf16x8*)(lds + PG8_SA(b, h) + aoff + m * 2048 + k * 1024); } while (0)
; #define PG8_LDB(dst, b, h) do { _Pragma("unroll") for (int n = 0; n < 2; ++n) _Pragma("unroll") for (int k = 0; k < 2; ++k) dst[n][k] = *(const PG8_LAS bf16x8*)(lds + PG8_SB(b, h) + boff + n * 2048 + k * 1024); } while (0)
; #define PG8_MMA(ai, bj, At, Bt) do { __builtin_amdgcn_s_setprio(1); _Pragma("unroll") for (int m = 0; m < 4; ++m) _Pragma("unroll") for (int n = 0; n < 2; ++n) _Pragma("unroll") for (int k = 0; k < 2; ++k) \
;         acc[ai][bj][m][n] = __builtin_amdgcn_mfma_f32_16x16x32_bf16(Bt[n][k], At[m][k], acc[ai][bj][m][n], 0, 0, 0); __builtin_amdgcn_s_setprio(0); } while (0)
; #define PG8_WAIT_V(n) asm volatile("s_waitcnt vmcnt(" #n ")" ::: "memory")
; #define PG8_WAIT_L(n) asm volatile("s_waitcnt lgkmcnt(" #n ")" ::: "memory")
; #define PG8_BAR __builtin_amdgcn_s_barrier()
; #define PG8_SCHED __builtin_amdgcn_sched_barrier(0)
; template <class Epi, class Sched, bool ALIGN_EPI = false, bool SP2 = false>
; __device__ __forceinline__ void gemm_phase(PG8_LAS unsigned char* lds, const Gemm g, const Sched& S, const Epi& E) {
;     ...
;             PG8_WAIT_V(8); PG8_WAIT_L(0); PG8_BAR; PG8_MMA(1, 0, At, B0); PG8_MMA(1, 1, At, B1); PG8_BAR; PG8_SCHED;
;             PG8_LDB(B0, 1, 0); PG8_LDB(B1, 1, 1); PG8_SCHED; PG8_LDA(At, 1, 0); PG8_STAGE(PG8_SA(0, 1), a2 + hstepA, voffA);
;             PG8_WAIT_V(8); PG8_WAIT_L(0); PG8_BAR; PG8_MMA(0, 0, At, B0); PG8_MMA(0, 1, At, B1); PG8_BAR; PG8_SCHED;
	s_setprio 1
	s_waitcnt lgkmcnt(0)
	v_mfma_f32_16x16x32_bf16 v[92:95], v[96:99], v[160:163], v[92:95]
	v_mfma_f32_16x16x32_bf16 v[28:31], v[104:107], v[160:163], v[28:31]
	v_mfma_f32_16x16x32_bf16 v[84:87], v[96:99], v[168:171], v[84:87]
	v_mfma_f32_16x16x32_bf16 v[20:23], v[104:107], v[168:171], v[20:23]
	v_mfma_f32_16x16x32_bf16 v[72:75], v[96:99], v[194:197], v[72:75]
	v_mfma_f32_16x16x32_bf16 v[8:11], v[104:107], v[194:197], v[8:11]
	v_mfma_f32_16x16x32_bf16 v[76:79], v[96:99], v[226:229], v[76:79]
	v_mfma_f32_16x16x32_bf16 v[12:15], v[104:107], v[226:229], v[12:15]
	v_mfma_f32_16x16x32_bf16 v[92:95], v[100:103], v[164:167], v[92:95]
	v_mfma_f32_16x16x32_bf16 v[28:31], v[108:111], v[164:167], v[28:31]
	v_mfma_f32_16x16x32_bf16 v[84:87], v[100:103], v[172:175], v[84:87]
	v_mfma_f32_16x16x32_bf16 v[20:23], v[108:111], v[172:175], v[20:23]
	v_mfma_f32_16x16x32_bf16 v[72:75], v[100:103], v[222:225], v[72:75]
	v_mfma_f32_16x16x32_bf16 v[8:11], v[108:111], v[222:225], v[8:11]
	v_mfma_f32_16x16x32_bf16 v[76:79], v[100:103], v[230:233], v[76:79]
	v_mfma_f32_16x16x32_bf16 v[12:15], v[108:111], v[230:233], v[12:15]
	s_setprio 0
	s_setprio 1
	v_mfma_f32_16x16x32_bf16 v[88:91], v[112:115], v[160:163], v[88:91]
	v_mfma_f32_16x16x32_bf16 v[24:27], v[120:123], v[160:163], v[24:27]
	v_mfma_f32_16x16x32_bf16 v[80:83], v[112:115], v[168:171], v[80:83]
	v_mfma_f32_16x16x32_bf16 v[16:19], v[120:123], v[168:171], v[16:19]
	v_mfma_f32_16x16x32_bf16 v[64:67], v[112:115], v[194:197], v[64:67]
	v_mfma_f32_16x16x32_bf16 v[0:3], v[120:123], v[194:197], v[0:3]
	v_mfma_f32_16x16x32_bf16 v[68:71], v[112:115], v[226:229], v[68:71]
	v_mfma_f32_16x16x32_bf16 v[4:7], v[120:123], v[226:229], v[4:7]
	v_mfma_f32_16x16x32_bf16 v[88:91], v[116:119], v[164:167], v[88:91]
	v_mfma_f32_16x16x32_bf16 v[24:27], v[124:127], v[164:167], v[24:27]
	v_mfma_f32_16x16x32_bf16 v[80:83], v[116:119], v[172:175], v[80:83]
	v_mfma_f32_16x16x32_bf16 v[16:19], v[124:127], v[172:175], v[16:19]
	v_mfma_f32_16x16x32_bf16 v[64:67], v[116:119], v[222:225], v[64:67]
	v_mfma_f32_16x16x32_bf16 v[0:3], v[124:127], v[222:225], v[0:3]
	v_mfma_f32_16x16x32_bf16 v[68:71], v[116:119], v[230:233], v[68:71]
	v_mfma_f32_16x16x32_bf16 v[4:7], v[124:127], v[230:233], v[4:7]
	s_setprio 0
	s_barrier
	s_add_i32 s18, 0, 0x18000
	s_add_i32 s19, 0, 0x1c000
	v_add_u32_e32 v108, s18, v201
	v_add_u32_e32 v124, s19, v201
	ds_read_b128 v[96:99], v108
	ds_read_b128 v[100:103], v108 offset:1024
	ds_read_b128 v[104:107], v108 offset:2048
	ds_read_b128 v[108:111], v108 offset:3072
	ds_read_b128 v[112:115], v124
	ds_read_b128 v[116:119], v124 offset:1024
	ds_read_b128 v[120:123], v124 offset:2048
	ds_read_b128 v[124:127], v124 offset:3072
	s_add_u32 s12, s12, 0x40000
	s_addc_u32 s13, s13, 0
	s_mov_b32 m0, s57
	ds_read_b128 v[160:163], v217 offset:32768
	ds_read_b128 v[164:167], v217 offset:33792
	ds_read_b128 v[168:171], v217 offset:34816
	ds_read_b128 v[172:175], v217 offset:35840
	ds_read_b128 v[194:197], v217 offset:36864
	ds_read_b128 v[222:225], v217 offset:37888
	ds_read_b128 v[226:229], v217 offset:38912
	ds_read_b128 v[230:233], v217 offset:39936
	global_load_lds_dwordx4 v178, s[12:13]
	v_lshl_add_u64 v[240:241], s[12:13], 0, v[182:183]
	s_mov_b32 m0, s59
	s_nop 0
	global_load_lds_dwordx4 v[240:241], off
	s_waitcnt vmcnt(8)
	s_waitcnt lgkmcnt(0)
	s_barrier
	s_setprio 1
	s_waitcnt lgkmcnt(0)
	v_mfma_f32_16x16x32_bf16 v[156:159], v[96:99], v[160:163], v[156:159]
	v_mfma_f32_16x16x32_bf16 v[60:63], v[104:107], v[160:163], v[60:63]
	v_mfma_f32_16x16x32_bf16 v[148:151], v[96:99], v[168:171], v[148:151]
	v_mfma_f32_16x16x32_bf16 v[52:55], v[104:107], v[168:171], v[52:55]
	v_mfma_f32_16x16x32_bf16 v[136:139], v[96:99], v[194:197], v[136:139]
	v_mfma_f32_16x16x32_bf16 v[40:43], v[104:107], v[194:197], v[40:43]
	v_mfma_f32_16x16x32_bf16 v[140:143], v[96:99], v[226:229], v[140:143]
	v_mfma_f32_16x16x32_bf16 v[44:47], v[104:107], v[226:229], v[44:47]
	v_mfma_f32_16x16x32_bf16 v[156:159], v[100:103], v[164:167], v[156:159]
	v_mfma_f32_16x16x32_bf16 v[60:63], v[108:111], v[164:167], v[60:63]
	v_mfma_f32_16x16x32_bf16 v[148:151], v[100:103], v[172:175], v[148:151]
	v_mfma_f32_16x16x32_bf16 v[52:55], v[108:111], v[172:175], v[52:55]
	v_mfma_f32_16x16x32_bf16 v[136:139], v[100:103], v[222:225], v[136:139]
	v_mfma_f32_16x16x32_bf16 v[40:43], v[108:111], v[222:225], v[40:43]
	v_mfma_f32_16x16x32_bf16 v[140:143], v[100:103], v[230:233], v[140:143]
	v_mfma_f32_16x16x32_bf16 v[44:47], v[108:111], v[230:233], v[44:47]
	s_setprio 0
	s_setprio 1
	v_mfma_f32_16x16x32_bf16 v[152:155], v[112:115], v[160:163], v[152:155]
	v_mfma_f32_16x16x32_bf16 v[56:59], v[120:123], v[160:163], v[56:59]
	v_mfma_f32_16x16x32_bf16 v[144:147], v[112:115], v[168:171], v[144:147]
	v_mfma_f32_16x16x32_bf16 v[48:51], v[120:123], v[168:171], v[48:51]
	v_mfma_f32_16x16x32_bf16 v[128:131], v[112:115], v[194:197], v[128:131]
	v_mfma_f32_16x16x32_bf16 v[32:35], v[120:123], v[194:197], v[32:35]
	v_mfma_f32_16x16x32_bf16 v[132:135], v[112:115], v[226:229], v[132:135]
	v_mfma_f32_16x16x32_bf16 v[36:39], v[120:123], v[226:229], v[36:39]
	v_mfma_f32_16x16x32_bf16 v[152:155], v[116:119], v[164:167], v[152:155]
	v_mfma_f32_16x16x32_bf16 v[56:59], v[124:127], v[164:167], v[56:59]
	v_mfma_f32_16x16x32_bf16 v[144:147], v[116:119], v[172:175], v[144:147]
	v_mfma_f32_16x16x32_bf16 v[48:51], v[124:127], v[172:175], v[48:51]
	v_mfma_f32_16x16x32_bf16 v[128:131], v[116:119], v[222:225], v[128:131]
	v_mfma_f32_16x16x32_bf16 v[32:35], v[124:127], v[222:225], v[32:35]
	v_mfma_f32_16x16x32_bf16 v[132:135], v[116:119], v[230:233], v[132:135]
	v_mfma_f32_16x16x32_bf16 v[36:39], v[124:127], v[230:233], v[36:39]
	s_setprio 0
	s_barrier
; #define PG8_STAGE(bufoff, gbase, voff) do { _Pragma("unroll") for (int _i = 0; _i < 2; ++_i) \
;         __builtin_amdgcn_global_load_lds((const unsigned*)((const char*)(gbase) + (voff)[_i]), (PG8_LAS unsigned*)(lds + (bufoff) + ldsw + _i * 8192), 16, 0, 0); } while (0)
; #define PG8_LDA(dst, b, h) do { _Pragma("unroll") for (int m = 0; m < 4; ++m) _Pragma("unroll") for (int k = 0; k < 2; ++k) dst[m][k] = *(const PG8_LAS bf16x8*)(lds + PG8_SA(b, h) + aoff + m * 2048 + k * 1024); } while (0)
; #define PG8_MMA(ai, bj, At, Bt) do { __builtin_amdgcn_s_setprio(1); _Pragma("unroll") for (int m = 0; m < 4; ++m) _Pragma("unroll") for (int n = 0; n < 2; ++n) _Pragma("unroll") for (int k = 0; k < 2; ++k) \
;         acc[ai][bj][m][n] = __builtin_amdgcn_mfma_f32_16x16x32_bf16(Bt[n][k], At[m][k], acc[ai][bj][m][n], 0, 0, 0); __builtin_amdgcn_s_setprio(0); } while (0)
; #define PG8_WAIT_V(n) asm volatile("s_waitcnt vmcnt(" #n ")" ::: "memory")
; #define PG8_WAIT_L(n) asm volatile("s_waitcnt lgkmcnt(" #n ")" ::: "memory")
; #define PG8_BAR __builtin_amdgcn_s_barrier()
; #define PG8_SCHED __builtin_amdgcn_sched_barrier(0)
; template <class Epi, class Sched, bool ALIGN_EPI = false, bool SP2 = false>
; __device__ __forceinline__ void gemm_phase(PG8_LAS unsigned char* lds, const Gemm g, const Sched& S, const Epi& E) {
;     ...
;             PG8_LDA(At, 1, 1); PG8_STAGE(PG8_SB(1, 0), b3, voffB); PG8_STAGE(PG8_SB(1, 1), b3 + hstepB, voffB); PG8_STAGE(PG8_SA(1, 0), a3, voffA);
;             PG8_WAIT_V(8); PG8_WAIT_L(0); PG8_BAR; PG8_MMA(1, 0, At, B0); PG8_MMA(1, 1, At, B1); PG8_BAR; PG8_SCHED;
	s_add_i32 s12, s18, s81
	v_lshl_add_u64 v[198:199], v[198:199], 0, s[84:85]
	s_mov_b32 m0, s12
	ds_read_b128 v[160:163], v217 offset:49152
	ds_read_b128 v[164:167], v217 offset:50176
	ds_read_b128 v[168:171], v217 offset:51200
	ds_read_b128 v[172:175], v217 offset:52224
	ds_read_b128 v[194:197], v217 offset:53248
	ds_read_b128 v[222:225], v217 offset:54272
	ds_read_b128 v[226:229], v217 offset:55296
	ds_read_b128 v[230:233], v217 offset:56320
	global_load_lds_dwordx4 v[198:199], off
	s_add_i32 m0, s12, 0x2000
	s_add_u32 s10, s10, 0x40080
	v_lshl_add_u64 v[198:199], v[234:235], 0, s[84:85]
	s_addc_u32 s11, s11, 0
	s_add_i32 s12, s19, s81
	global_load_lds_dwordx4 v[198:199], off
	s_mov_b32 m0, s12
	s_nop 0
	global_load_lds_dwordx4 v180, s[10:11]
	s_add_i32 m0, s12, 0x2000
	s_nop 0
	global_load_lds_dwordx4 v184, s[10:11]
	v_lshl_add_u64 v[198:199], v[236:237], 0, s[84:85]
	s_mov_b32 m0, s33
	s_nop 0
	global_load_lds_dwordx4 v[198:199], off
	v_lshl_add_u64 v[198:199], v[238:239], 0, s[84:85]
	s_mov_b32 m0, s61
	s_nop 0
	global_load_lds_dwordx4 v[198:199], off
	s_waitcnt vmcnt(8)
	s_waitcnt lgkmcnt(0)
	s_barrier
	s_setprio 1
	s_waitcnt lgkmcnt(0)
	v_mfma_f32_16x16x32_bf16 v[92:95], v[96:99], v[160:163], v[92:95]
	v_mfma_f32_16x16x32_bf16 v[28:31], v[104:107], v[160:163], v[28:31]
	v_mfma_f32_16x16x32_bf16 v[84:87], v[96:99], v[168:171], v[84:87]
	v_mfma_f32_16x16x32_bf16 v[20:23], v[104:107], v[168:171], v[20:23]
	v_mfma_f32_16x16x32_bf16 v[72:75], v[96:99], v[194:197], v[72:75]
	v_mfma_f32_16x16x32_bf16 v[8:11], v[104:107], v[194:197], v[8:11]
	v_mfma_f32_16x16x32_bf16 v[76:79], v[96:99], v[226:229], v[76:79]
	v_mfma_f32_16x16x32_bf16 v[12:15], v[104:107], v[226:229], v[12:15]
	v_mfma_f32_16x16x32_bf16 v[92:95], v[100:103], v[164:167], v[92:95]
	v_mfma_f32_16x16x32_bf16 v[28:31], v[108:111], v[164:167], v[28:31]
	v_mfma_f32_16x16x32_bf16 v[84:87], v[100:103], v[172:175], v[84:87]
	v_mfma_f32_16x16x32_bf16 v[20:23], v[108:111], v[172:175], v[20:23]
	v_mfma_f32_16x16x32_bf16 v[72:75], v[100:103], v[222:225], v[72:75]
	v_mfma_f32_16x16x32_bf16 v[8:11], v[108:111], v[222:225], v[8:11]
	v_mfma_f32_16x16x32_bf16 v[76:79], v[100:103], v[230:233], v[76:79]
	v_mfma_f32_16x16x32_bf16 v[12:15], v[108:111], v[230:233], v[12:15]
	s_setprio 0
	s_setprio 1
	v_mfma_f32_16x16x32_bf16 v[88:91], v[112:115], v[160:163], v[88:91]
	v_mfma_f32_16x16x32_bf16 v[24:27], v[120:123], v[160:163], v[24:27]
	v_mfma_f32_16x16x32_bf16 v[80:83], v[112:115], v[168:171], v[80:83]
	v_mfma_f32_16x16x32_bf16 v[16:19], v[120:123], v[168:171], v[16:19]
	v_mfma_f32_16x16x32_bf16 v[64:67], v[112:115], v[194:197], v[64:67]
	v_mfma_f32_16x16x32_bf16 v[0:3], v[120:123], v[194:197], v[0:3]
	v_mfma_f32_16x16x32_bf16 v[68:71], v[112:115], v[226:229], v[68:71]
	v_mfma_f32_16x16x32_bf16 v[4:7], v[120:123], v[226:229], v[4:7]
	v_mfma_f32_16x16x32_bf16 v[88:91], v[116:119], v[164:167], v[88:91]
	v_mfma_f32_16x16x32_bf16 v[24:27], v[124:127], v[164:167], v[24:27]
	v_mfma_f32_16x16x32_bf16 v[80:83], v[116:119], v[172:175], v[80:83]
	v_mfma_f32_16x16x32_bf16 v[16:19], v[124:127], v[172:175], v[16:19]
	v_mfma_f32_16x16x32_bf16 v[64:67], v[116:119], v[222:225], v[64:67]
	v_mfma_f32_16x16x32_bf16 v[0:3], v[124:127], v[222:225], v[0:3]
	v_mfma_f32_16x16x32_bf16 v[68:71], v[116:119], v[230:233], v[68:71]
	v_mfma_f32_16x16x32_bf16 v[4:7], v[124:127], v[230:233], v[4:7]
	s_setprio 0
	s_barrier
	s_add_i32 s17, s17, 2
	s_add_u32 s0, s0, 0x100
	s_addc_u32 s1, s1, 0
	s_add_u32 s15, s15, 0x100
	s_addc_u32 s16, s16, 0
	s_cmp_gt_u32 s17, 13
	s_cbranch_scc0 .LBB0_743
	v_readlane_b32 s0, v242, 32
	v_readlane_b32 s1, v242, 33
	s_and_b64 vcc, exec, s[0:1]
	s_cbranch_vccz .LBB0_746
	s_barrier

; #define PG8_STAGE(bufoff, gbase, voff) do { _Pragma("unroll") for (int _i = 0; _i < 2; ++_i) \
;         __builtin_amdgcn_global_load_lds((const unsigned*)((const char*)(gbase) + (voff)[_i]), (PG8_LAS unsigned*)(lds + (bufoff) + ldsw + _i * 8192), 16, 0, 0); } while (0)
; #define PG8_WAIT_V(n) asm volatile("s_waitcnt vmcnt(" #n ")" ::: "memory")
; #define PG8_BAR __builtin_amdgcn_s_barrier()
; template <class Epi, class Sched, bool ALIGN_EPI = false, bool SP2 = false>
; __device__ __forceinline__ void gemm_phase(PG8_LAS unsigned char* lds, const Gemm g, const Sched& S, const Epi& E) {
;     ...
;     f32x4 acc[2][2][4][2];
; #pragma unroll
;     for (int a = 0; a < 2; ++a)
; #pragma unroll
;         for (int b = 0; b < 2; ++b)
; #pragma unroll
;             for (int m = 0; m < 4; ++m)
; #pragma unroll
;                 for (int n = 0; n < 2; ++n) acc[a][b][m][n] = (f32x4){0.f, 0.f, 0.f, 0.f};
;     bf16x8 At[4][2], B0[2][2], B1[2][2];
;     const char* cA = (const char*)g.A + (size_t)cur.pm * tstepA; const char* cB = (const char*)g.Bt + (size_t)cur.pn * tstepB;
;     S.a_ready(cur);
;     if constexpr (SP2) {
;         PG8_STAGE(PG8_SB(0, 0), cB, voffB); PG8_STAGE(PG8_SB(0, 1), cB + hstepB, voffB); PG8_STAGE(PG8_SA(0, 0), cA, voffA); PG8_STAGE(PG8_SA(0, 1), cA + hstepA, voffA);
;         if (wr == 1) PG8_BAR;
;         PG8_WAIT_V(2); PG8_BAR;
;         PG8_STAGE(PG8_SB(1, 0), cB + kstep, voffB); PG8_STAGE(PG8_SA(1, 0), cA + kstep, voffA); PG8_STAGE(PG8_SB(1, 1), cB + hstepB + kstep, voffB);
;         PG8_WAIT_V(6); PG8_BAR;
.LBB0_860:
	v_and_b32_e32 v144, 15, v176
	v_and_b32_e32 v12, 48, v176
	v_lshlrev_b32_e32 v14, 2, v176
	s_sext_i32_i8 s6, s0
	v_lshl_or_b32 v13, v144, 6, v12
	s_lshl_b32 s0, s22, 13
	v_and_b32_e32 v14, 32, v14
	s_mov_b64 s[10:11], 0x80
	s_and_b32 s23, s7, 3
	v_bitop3_b32 v13, v13, s0, v14 bitop3:0xde
	v_lshlrev_b32_e32 v15, 6, v176
	s_movk_i32 s0, 0x3c0
	s_add_i32 m0, s28, 0x18000
	v_lshl_add_u64 v[6:7], v[6:7], 0, s[10:11]
	s_lshl_b32 s33, s22, 6
	v_and_or_b32 v12, v15, s0, v12
	s_lshl_b32 s0, s23, 12
	s_waitcnt vmcnt(2)
	s_barrier
	global_load_lds_dwordx4 v[6:7], off
	v_lshl_add_u64 v[4:5], v[4:5], 0, s[10:11]
	s_add_i32 m0, s28, 0x1a000
	s_add_i32 s35, s28, 0x8000
	s_add_i32 s36, s28, 0xa000
	global_load_lds_dwordx4 v[4:5], off
	v_lshl_add_u64 v[2:3], v[2:3], 0, s[10:11]
	s_mov_b32 m0, s35
	s_add_u32 s2, s14, 0xb0080
	global_load_lds_dwordx4 v[2:3], off
	v_lshl_add_u64 v[0:1], v[0:1], 0, s[10:11]
	s_mov_b32 m0, s36
	s_addc_u32 s3, s15, 0
	global_load_lds_dwordx4 v[0:1], off
	s_add_i32 m0, s28, 0x1c000
	global_load_lds_dwordx4 v128, s[2:3]
	v_lshl_add_u64 v[0:1], s[2:3], 0, v[130:131]
	s_add_i32 m0, s28, 0x1e000
	v_bitop3_b32 v146, s0, v12, v14 bitop3:0xf6
	global_load_lds_dwordx4 v[0:1], off
	s_mov_b64 s[0:1], 0xb0080
	s_waitcnt vmcnt(6)
	v_add3_u32 v0, v10, v8, v9
	v_mov_b32_e32 v1, v129
	v_lshl_add_u64 v[132:133], v[0:1], 0, s[0:1]
	v_add3_u32 v0, v11, v8, v9
	v_lshrrev_b32_e32 v145, 2, v176
	v_or_b32_e32 v152, s33, v144
	v_lshl_add_u64 v[134:135], v[0:1], 0, s[0:1]
	v_mov_b64_e32 v[136:137], 0x100
	v_mov_b64_e32 v[138:139], 0xff
	s_add_i32 s37, 0, 0x10000
	s_add_i32 s38, 0, 0x14000
	v_add_u32_e32 v147, 0, v13
	v_mov_b32_e32 v0, v129
	v_mov_b32_e32 v2, v129
	v_mov_b32_e32 v3, v129
	v_mov_b32_e32 v4, v129
	v_mov_b32_e32 v5, v129
	v_mov_b32_e32 v6, v129
	v_mov_b32_e32 v7, v129
	v_mov_b32_e32 v20, v129
	v_mov_b32_e32 v21, v129
	v_mov_b32_e32 v22, v129
	v_mov_b32_e32 v23, v129
	v_mov_b32_e32 v24, v129
	v_mov_b32_e32 v25, v129
	v_mov_b32_e32 v26, v129
	v_mov_b32_e32 v27, v129
	v_mov_b32_e32 v48, v129
	v_mov_b32_e32 v49, v129
	v_mov_b32_e32 v50, v129
	v_mov_b32_e32 v51, v129
	v_mov_b32_e32 v56, v129
	v_mov_b32_e32 v57, v129
	v_mov_b32_e32 v58, v129
	v_mov_b32_e32 v59, v129
	v_mov_b32_e32 v80, v129
	v_mov_b32_e32 v81, v129
	v_mov_b32_e32 v82, v129
	v_mov_b32_e32 v83, v129
	v_mov_b32_e32 v84, v129
	v_mov_b32_e32 v85, v129
	v_mov_b32_e32 v86, v129
	v_mov_b32_e32 v87, v129
	v_mov_b32_e32 v8, v129
	v_mov_b32_e32 v9, v129
	v_mov_b32_e32 v10, v129
	v_mov_b32_e32 v11, v129
	v_mov_b32_e32 v12, v129
	v_mov_b32_e32 v13, v129
	v_mov_b32_e32 v14, v129
	v_mov_b32_e32 v15, v129
	v_mov_b32_e32 v28, v129
	v_mov_b32_e32 v29, v129
	v_mov_b32_e32 v30, v129
	v_mov_b32_e32 v31, v129
	v_mov_b32_e32 v36, v129
	v_mov_b32_e32 v37, v129
	v_mov_b32_e32 v38, v129
	v_mov_b32_e32 v39, v129
	s_waitcnt vmcnt(0)
	v_mov_b32_e32 v64, v129
	v_mov_b32_e32 v65, v129
	v_mov_b32_e32 v66, v129
	v_mov_b32_e32 v67, v129
	v_mov_b32_e32 v68, v129
	v_mov_b32_e32 v69, v129
	v_mov_b32_e32 v70, v129
	v_mov_b32_e32 v71, v129
	v_mov_b32_e32 v96, v129
	v_mov_b32_e32 v97, v129
	v_mov_b32_e32 v98, v129
	v_mov_b32_e32 v99, v129
	v_mov_b32_e32 v100, v129
	v_mov_b32_e32 v101, v129
	v_mov_b32_e32 v102, v129
	v_mov_b32_e32 v103, v129
	v_mov_b32_e32 v60, v129
	v_mov_b32_e32 v61, v129
	v_mov_b32_e32 v62, v129
	v_mov_b32_e32 v63, v129
	v_mov_b32_e32 v92, v129
	v_mov_b32_e32 v93, v129
	v_mov_b32_e32 v94, v129
	v_mov_b32_e32 v95, v129
	v_mov_b32_e32 v44, v129
	v_mov_b32_e32 v45, v129
	v_mov_b32_e32 v46, v129
	v_mov_b32_e32 v47, v129
	v_mov_b32_e32 v76, v129
	v_mov_b32_e32 v77, v129
	v_mov_b32_e32 v78, v129
	v_mov_b32_e32 v79, v129
	v_mov_b32_e32 v32, v129
	v_mov_b32_e32 v33, v129
	v_mov_b32_e32 v34, v129
	v_mov_b32_e32 v35, v129
	v_mov_b32_e32 v52, v129
	v_mov_b32_e32 v53, v129
	v_mov_b32_e32 v54, v129
	v_mov_b32_e32 v55, v129
	v_mov_b32_e32 v16, v129
	v_mov_b32_e32 v17, v129
	v_mov_b32_e32 v18, v129
	v_mov_b32_e32 v19, v129
	v_mov_b32_e32 v40, v129
	v_mov_b32_e32 v41, v129
	v_mov_b32_e32 v42, v129
	v_mov_b32_e32 v43, v129
	v_mov_b32_e32 v112, v129
	v_mov_b32_e32 v113, v129
	v_mov_b32_e32 v114, v129
	v_mov_b32_e32 v115, v129
	v_mov_b32_e32 v120, v129
	v_mov_b32_e32 v121, v129
	v_mov_b32_e32 v122, v129
	v_mov_b32_e32 v123, v129
	v_mov_b32_e32 v108, v129
	v_mov_b32_e32 v109, v129
	v_mov_b32_e32 v110, v129
	v_mov_b32_e32 v111, v129
	v_mov_b32_e32 v124, v129
	v_mov_b32_e32 v125, v129
	v_mov_b32_e32 v126, v129
	v_mov_b32_e32 v127, v129
	v_mov_b32_e32 v88, v129
	v_mov_b32_e32 v89, v129
	v_mov_b32_e32 v90, v129
	v_mov_b32_e32 v91, v129
	v_mov_b32_e32 v116, v129
	v_mov_b32_e32 v117, v129
	v_mov_b32_e32 v118, v129
	v_mov_b32_e32 v119, v129
	v_mov_b32_e32 v72, v129
	v_mov_b32_e32 v73, v129
	v_mov_b32_e32 v74, v129
	v_mov_b32_e32 v75, v129
	v_mov_b32_e32 v104, v129
	v_mov_b32_e32 v105, v129
	v_mov_b32_e32 v106, v129
	v_mov_b32_e32 v107, v129
	s_barrier
	s_branch .LBB0_863

; #define PG8_STAGE(bufoff, gbase, voff) do { _Pragma("unroll") for (int _i = 0; _i < 2; ++_i) \
;         __builtin_amdgcn_global_load_lds((const unsigned*)((const char*)(gbase) + (voff)[_i]), (PG8_LAS unsigned*)(lds + (bufoff) + ldsw + _i * 8192), 16, 0, 0); } while (0)
; #define PG8_LDA(dst, b, h) do { _Pragma("unroll") for (int m = 0; m < 4; ++m) _Pragma("unroll") for (int k = 0; k < 2; ++k) dst[m][k] = *(const PG8_LAS bf16x8*)(lds + PG8_SA(b, h) + aoff + m * 2048 + k * 1024); } while (0)
; #define PG8_LDB(dst, b, h) do { _Pragma("unroll") for (int n = 0; n < 2; ++n) _Pragma("unroll") for (int k = 0; k < 2; ++k) dst[n][k] = *(const PG8_LAS bf16x8*)(lds + PG8_SB(b, h) + boff + n * 2048 + k * 1024); } while (0)
; #define PG8_MMA(ai, bj, At, Bt) do { __builtin_amdgcn_s_setprio(1); _Pragma("unroll") for (int m = 0; m < 4; ++m) _Pragma("unroll") for (int n = 0; n < 2; ++n) _Pragma("unroll") for (int k = 0; k < 2; ++k) \
;         acc[ai][bj][m][n] = __builtin_amdgcn_mfma_f32_16x16x32_bf16(Bt[n][k], At[m][k], acc[ai][bj][m][n], 0, 0, 0); __builtin_amdgcn_s_setprio(0); } while (0)
; #define PG8_WAIT_V(n) asm volatile("s_waitcnt vmcnt(" #n ")" ::: "memory")
; #define PG8_WAIT_L(n) asm volatile("s_waitcnt lgkmcnt(" #n ")" ::: "memory")
; #define PG8_BAR __builtin_amdgcn_s_barrier()
; template <class Epi, class Sched, bool ALIGN_EPI = false, bool SP2 = false>
; __device__ __forceinline__ void gemm_phase(PG8_LAS unsigned char* lds, const Gemm g, const Sched& S, const Epi& E) {
;     ...
;             const char* a1 = cA + (size_t)(t + 1) * kstep;
;             const char* a2 = last ? nA : cA + (size_t)(t + 2) * kstep; const char* b2 = last ? nB : cB + (size_t)(t + 2) * kstep;
;             const char* a3 = a2 + kstep; const char* b3 = b2 + kstep;
;             if (last && has_next) S.a_ready(nxt);
;             if constexpr (SP2) {
;             PG8_LDB(B0, 0, 0); PG8_LDB(B1, 0, 1); PG8_SCHED; PG8_LDA(At, 0, 0); PG8_STAGE(PG8_SA(1, 1), a1 + hstepA, voffA);
;             PG8_WAIT_V(8); PG8_WAIT_L(0); PG8_BAR; PG8_MMA(0, 0, At, B0); PG8_MMA(0, 1, At, B1); PG8_BAR; PG8_SCHED;
;             PG8_LDA(At, 0, 1); PG8_STAGE(PG8_SB(0, 0), b2, voffB); PG8_STAGE(PG8_SB(0, 1), b2 + hstepB, voffB); PG8_STAGE(PG8_SA(0, 0), a2, voffA);
;             PG8_WAIT_V(8); PG8_WAIT_L(0); PG8_BAR; PG8_MMA(1, 0, At, B0); PG8_MMA(1, 1, At, B1); PG8_BAR; PG8_SCHED;
.LBB0_874:
	v_add_u32_e32 v153, s37, v146
	ds_read_b128 v[148:151], v153
	ds_read_b128 v[154:157], v153 offset:1024
	ds_read_b128 v[158:161], v153 offset:2048
	ds_read_b128 v[162:165], v153 offset:3072
	v_add_u32_e32 v153, s38, v146
	s_add_u32 s16, s8, s14
	ds_read_b128 v[166:169], v153
	ds_read_b128 v[170:173], v153 offset:1024
	ds_read_b128 v[178:181], v153 offset:2048
	ds_read_b128 v[182:185], v153 offset:3072
	s_addc_u32 s17, s9, s15
	s_add_u32 s16, s16, 0x100
	s_addc_u32 s17, s17, 0
	s_add_u32 s45, s42, s14
	s_addc_u32 s46, s43, s15
	s_cmpk_eq_i32 s14, 0x1500
	s_cselect_b32 s19, s13, s17
	s_cselect_b32 s18, s12, s16
	s_cselect_b32 s17, s5, s46
	s_cselect_b32 s16, s4, s45
	v_lshl_add_u64 v[174:175], v[140:141], 0, s[14:15]
	s_add_i32 m0, s28, 0xc000
	ds_read_b128 v[186:189], v147
	ds_read_b128 v[190:193], v147 offset:1024
	ds_read_b128 v[194:197], v147 offset:2048
	ds_read_b128 v[202:205], v147 offset:3072
	ds_read_b128 v[206:209], v147 offset:4096
	ds_read_b128 v[210:213], v147 offset:5120
	ds_read_b128 v[214:217], v147 offset:6144
	ds_read_b128 v[218:221], v147 offset:7168
	global_load_lds_dwordx4 v[174:175], off
	v_lshl_add_u64 v[174:175], v[142:143], 0, s[14:15]
	s_add_i32 m0, s28, 0xe000
	s_nop 0
	global_load_lds_dwordx4 v[174:175], off
	s_waitcnt vmcnt(8)
	s_waitcnt lgkmcnt(0)
	s_barrier
	s_setprio 1
	s_waitcnt lgkmcnt(0)
	v_mfma_f32_16x16x32_bf16 v[104:107], v[148:151], v[186:189], v[104:107]
	v_mfma_f32_16x16x32_bf16 v[72:75], v[158:161], v[186:189], v[72:75]
	v_mfma_f32_16x16x32_bf16 v[116:119], v[148:151], v[194:197], v[116:119]
	v_mfma_f32_16x16x32_bf16 v[88:91], v[158:161], v[194:197], v[88:91]
	v_mfma_f32_16x16x32_bf16 v[124:127], v[148:151], v[206:209], v[124:127]
	v_mfma_f32_16x16x32_bf16 v[108:111], v[158:161], v[206:209], v[108:111]
	v_mfma_f32_16x16x32_bf16 v[120:123], v[148:151], v[214:217], v[120:123]
	v_mfma_f32_16x16x32_bf16 v[112:115], v[158:161], v[214:217], v[112:115]
	v_mfma_f32_16x16x32_bf16 v[104:107], v[154:157], v[190:193], v[104:107]
	v_mfma_f32_16x16x32_bf16 v[72:75], v[162:165], v[190:193], v[72:75]
	v_mfma_f32_16x16x32_bf16 v[116:119], v[154:157], v[202:205], v[116:119]
	v_mfma_f32_16x16x32_bf16 v[88:91], v[162:165], v[202:205], v[88:91]
	v_mfma_f32_16x16x32_bf16 v[124:127], v[154:157], v[210:213], v[124:127]
	v_mfma_f32_16x16x32_bf16 v[108:111], v[162:165], v[210:213], v[108:111]
	v_mfma_f32_16x16x32_bf16 v[120:123], v[154:157], v[218:221], v[120:123]
	v_mfma_f32_16x16x32_bf16 v[112:115], v[162:165], v[218:221], v[112:115]
	s_setprio 0
	s_setprio 1
	v_mfma_f32_16x16x32_bf16 v[40:43], v[166:169], v[186:189], v[40:43]
	v_mfma_f32_16x16x32_bf16 v[16:19], v[178:181], v[186:189], v[16:19]
	v_mfma_f32_16x16x32_bf16 v[52:55], v[166:169], v[194:197], v[52:55]
	v_mfma_f32_16x16x32_bf16 v[32:35], v[178:181], v[194:197], v[32:35]
	v_mfma_f32_16x16x32_bf16 v[76:79], v[166:169], v[206:209], v[76:79]
	v_mfma_f32_16x16x32_bf16 v[44:47], v[178:181], v[206:209], v[44:47]
	v_mfma_f32_16x16x32_bf16 v[92:95], v[166:169], v[214:217], v[92:95]
	v_mfma_f32_16x16x32_bf16 v[60:63], v[178:181], v[214:217], v[60:63]
	v_mfma_f32_16x16x32_bf16 v[40:43], v[170:173], v[190:193], v[40:43]
	v_mfma_f32_16x16x32_bf16 v[16:19], v[182:185], v[190:193], v[16:19]
	v_mfma_f32_16x16x32_bf16 v[52:55], v[170:173], v[202:205], v[52:55]
	v_mfma_f32_16x16x32_bf16 v[32:35], v[182:185], v[202:205], v[32:35]
	v_mfma_f32_16x16x32_bf16 v[76:79], v[170:173], v[210:213], v[76:79]
	v_mfma_f32_16x16x32_bf16 v[44:47], v[182:185], v[210:213], v[44:47]
	v_mfma_f32_16x16x32_bf16 v[92:95], v[170:173], v[218:221], v[92:95]
	v_mfma_f32_16x16x32_bf16 v[60:63], v[182:185], v[218:221], v[60:63]
	s_setprio 0
	s_barrier
	s_add_i32 s45, s37, s27
	v_lshl_add_u64 v[174:175], s[16:17], 0, v[128:129]
	s_mov_b32 m0, s45
	ds_read_b128 v[186:189], v147 offset:16384
	ds_read_b128 v[190:193], v147 offset:17408
	ds_read_b128 v[194:197], v147 offset:18432
	ds_read_b128 v[202:205], v147 offset:19456
	ds_read_b128 v[206:209], v147 offset:20480
	ds_read_b128 v[210:213], v147 offset:21504
	ds_read_b128 v[214:217], v147 offset:22528
	ds_read_b128 v[218:221], v147 offset:23552
	global_load_lds_dwordx4 v[174:175], off
	s_add_i32 m0, s45, 0x2000
	s_add_u32 s46, s16, 0xb0000
	v_lshl_add_u64 v[198:199], s[16:17], 0, v[130:131]
	s_addc_u32 s47, s17, 0
	s_add_i32 s45, s38, s27
	global_load_lds_dwordx4 v[198:199], off
	s_mov_b32 m0, s45
	v_lshl_add_u64 v[224:225], s[18:19], 0, v[130:131]
	global_load_lds_dwordx4 v128, s[46:47]
	s_add_i32 m0, s45, 0x2000
	s_nop 0
	global_load_lds_dwordx4 v130, s[46:47]
	v_lshl_add_u64 v[222:223], s[18:19], 0, v[128:129]
	s_mov_b32 m0, s28
	s_nop 0
	global_load_lds_dwordx4 v[222:223], off
	s_mov_b32 m0, s29
	s_nop 0
	global_load_lds_dwordx4 v[224:225], off
	s_waitcnt vmcnt(8)
	s_waitcnt lgkmcnt(0)
	s_barrier
; #define PG8_STAGE(bufoff, gbase, voff) do { _Pragma("unroll") for (int _i = 0; _i < 2; ++_i) \
;         __builtin_amdgcn_global_load_lds((const unsigned*)((const char*)(gbase) + (voff)[_i]), (PG8_LAS unsigned*)(lds + (bufoff) + ldsw + _i * 8192), 16, 0, 0); } while (0)
; #define PG8_LDA(dst, b, h) do { _Pragma("unroll") for (int m = 0; m < 4; ++m) _Pragma("unroll") for (int k = 0; k < 2; ++k) dst[m][k] = *(const PG8_LAS bf16x8*)(lds + PG8_SA(b, h) + aoff + m * 2048 + k * 1024); } while (0)
; #define PG8_LDB(dst, b, h) do { _Pragma("unroll") for (int n = 0; n < 2; ++n) _Pragma("unroll") for (int k = 0; k < 2; ++k) dst[n][k] = *(const PG8_LAS bf16x8*)(lds + PG8_SB(b, h) + boff + n * 2048 + k * 1024); } while (0)
; #define PG8_MMA(ai, bj, At, Bt) do { __builtin_amdgcn_s_setprio(1); _Pragma("unroll") for (int m = 0; m < 4; ++m) _Pragma("unroll") for (int n = 0; n < 2; ++n) _Pragma("unroll") for (int k = 0; k < 2; ++k) \
;         acc[ai][bj][m][n] = __builtin_amdgcn_mfma_f32_16x16x32_bf16(Bt[n][k], At[m][k], acc[ai][bj][m][n], 0, 0, 0); __builtin_amdgcn_s_setprio(0); } while (0)
; #define PG8_WAIT_V(n) asm volatile("s_waitcnt vmcnt(" #n ")" ::: "memory")
; #define PG8_WAIT_L(n) asm volatile("s_waitcnt lgkmcnt(" #n ")" ::: "memory")
; #define PG8_BAR __builtin_amdgcn_s_barrier()
; #define PG8_SCHED __builtin_amdgcn_sched_barrier(0)
; template <class Epi, class Sched, bool ALIGN_EPI = false, bool SP2 = false>
; __device__ __forceinline__ void gemm_phase(PG8_LAS unsigned char* lds, const Gemm g, const Sched& S, const Epi& E) {
;     ...
;             PG8_WAIT_V(8); PG8_WAIT_L(0); PG8_BAR; PG8_MMA(1, 0, At, B0); PG8_MMA(1, 1, At, B1); PG8_BAR; PG8_SCHED;
;             PG8_LDB(B0, 1, 0); PG8_LDB(B1, 1, 1); PG8_SCHED; PG8_LDA(At, 1, 0); PG8_STAGE(PG8_SA(0, 1), a2 + hstepA, voffA);
;             PG8_WAIT_V(8); PG8_WAIT_L(0); PG8_BAR; PG8_MMA(0, 0, At, B0); PG8_MMA(0, 1, At, B1); PG8_BAR; PG8_SCHED;
	s_setprio 1
	s_waitcnt lgkmcnt(0)
	v_mfma_f32_16x16x32_bf16 v[100:103], v[148:151], v[186:189], v[100:103]
	v_mfma_f32_16x16x32_bf16 v[96:99], v[158:161], v[186:189], v[96:99]
	v_mfma_f32_16x16x32_bf16 v[68:71], v[148:151], v[194:197], v[68:71]
	v_mfma_f32_16x16x32_bf16 v[64:67], v[158:161], v[194:197], v[64:67]
	v_mfma_f32_16x16x32_bf16 v[36:39], v[148:151], v[206:209], v[36:39]
	v_mfma_f32_16x16x32_bf16 v[28:31], v[158:161], v[206:209], v[28:31]
	v_mfma_f32_16x16x32_bf16 v[12:15], v[148:151], v[214:217], v[12:15]
	v_mfma_f32_16x16x32_bf16 v[8:11], v[158:161], v[214:217], v[8:11]
	v_mfma_f32_16x16x32_bf16 v[100:103], v[154:157], v[190:193], v[100:103]
	v_mfma_f32_16x16x32_bf16 v[96:99], v[162:165], v[190:193], v[96:99]
	v_mfma_f32_16x16x32_bf16 v[68:71], v[154:157], v[202:205], v[68:71]
	v_mfma_f32_16x16x32_bf16 v[64:67], v[162:165], v[202:205], v[64:67]
	v_mfma_f32_16x16x32_bf16 v[36:39], v[154:157], v[210:213], v[36:39]
	v_mfma_f32_16x16x32_bf16 v[28:31], v[162:165], v[210:213], v[28:31]
	v_mfma_f32_16x16x32_bf16 v[12:15], v[154:157], v[218:221], v[12:15]
	v_mfma_f32_16x16x32_bf16 v[8:11], v[162:165], v[218:221], v[8:11]
	s_setprio 0
	s_setprio 1
	v_mfma_f32_16x16x32_bf16 v[84:87], v[166:169], v[186:189], v[84:87]
	v_mfma_f32_16x16x32_bf16 v[80:83], v[178:181], v[186:189], v[80:83]
	v_mfma_f32_16x16x32_bf16 v[56:59], v[166:169], v[194:197], v[56:59]
	v_mfma_f32_16x16x32_bf16 v[48:51], v[178:181], v[194:197], v[48:51]
	v_mfma_f32_16x16x32_bf16 v[24:27], v[166:169], v[206:209], v[24:27]
	v_mfma_f32_16x16x32_bf16 v[20:23], v[178:181], v[206:209], v[20:23]
	v_mfma_f32_16x16x32_bf16 v[4:7], v[166:169], v[214:217], v[4:7]
	v_mfma_f32_16x16x32_bf16 v[0:3], v[178:181], v[214:217], v[0:3]
	v_mfma_f32_16x16x32_bf16 v[84:87], v[170:173], v[190:193], v[84:87]
	v_mfma_f32_16x16x32_bf16 v[80:83], v[182:185], v[190:193], v[80:83]
	v_mfma_f32_16x16x32_bf16 v[56:59], v[170:173], v[202:205], v[56:59]
	v_mfma_f32_16x16x32_bf16 v[48:51], v[182:185], v[202:205], v[48:51]
	v_mfma_f32_16x16x32_bf16 v[24:27], v[170:173], v[210:213], v[24:27]
	v_mfma_f32_16x16x32_bf16 v[20:23], v[182:185], v[210:213], v[20:23]
	v_mfma_f32_16x16x32_bf16 v[4:7], v[170:173], v[218:221], v[4:7]
	v_mfma_f32_16x16x32_bf16 v[0:3], v[182:185], v[218:221], v[0:3]
	s_setprio 0
	s_barrier
	s_add_i32 s45, 0, 0x18000
	v_add_u32_e32 v153, s45, v146
	s_add_i32 s46, 0, 0x1c000
	ds_read_b128 v[148:151], v153
	ds_read_b128 v[154:157], v153 offset:1024
	ds_read_b128 v[158:161], v153 offset:2048
	ds_read_b128 v[162:165], v153 offset:3072
	v_add_u32_e32 v153, s46, v146
	ds_read_b128 v[166:169], v153
	ds_read_b128 v[170:173], v153 offset:1024
	ds_read_b128 v[178:181], v153 offset:2048
	ds_read_b128 v[182:185], v153 offset:3072
	s_add_u32 s18, s18, 0xb0000
	s_addc_u32 s19, s19, 0
	s_mov_b32 m0, s30
	ds_read_b128 v[186:189], v147 offset:32768
	ds_read_b128 v[190:193], v147 offset:33792
	ds_read_b128 v[194:197], v147 offset:34816
	ds_read_b128 v[202:205], v147 offset:35840
	ds_read_b128 v[206:209], v147 offset:36864
	ds_read_b128 v[210:213], v147 offset:37888
	ds_read_b128 v[214:217], v147 offset:38912
	ds_read_b128 v[218:221], v147 offset:39936
	global_load_lds_dwordx4 v128, s[18:19]
	v_lshl_add_u64 v[226:227], s[18:19], 0, v[130:131]
	s_mov_b32 m0, s31
	s_nop 0
	global_load_lds_dwordx4 v[226:227], off
	s_waitcnt vmcnt(8)
	s_waitcnt lgkmcnt(0)
	s_barrier
	s_setprio 1
	s_waitcnt lgkmcnt(0)
	v_mfma_f32_16x16x32_bf16 v[104:107], v[148:151], v[186:189], v[104:107]
	v_mfma_f32_16x16x32_bf16 v[72:75], v[158:161], v[186:189], v[72:75]
	v_mfma_f32_16x16x32_bf16 v[116:119], v[148:151], v[194:197], v[116:119]
	v_mfma_f32_16x16x32_bf16 v[88:91], v[158:161], v[194:197], v[88:91]
	v_mfma_f32_16x16x32_bf16 v[124:127], v[148:151], v[206:209], v[124:127]
	v_mfma_f32_16x16x32_bf16 v[108:111], v[158:161], v[206:209], v[108:111]
	v_mfma_f32_16x16x32_bf16 v[120:123], v[148:151], v[214:217], v[120:123]
	v_mfma_f32_16x16x32_bf16 v[112:115], v[158:161], v[214:217], v[112:115]
	v_mfma_f32_16x16x32_bf16 v[104:107], v[154:157], v[190:193], v[104:107]
	v_mfma_f32_16x16x32_bf16 v[72:75], v[162:165], v[190:193], v[72:75]
	v_mfma_f32_16x16x32_bf16 v[116:119], v[154:157], v[202:205], v[116:119]
	v_mfma_f32_16x16x32_bf16 v[88:91], v[162:165], v[202:205], v[88:91]
	v_mfma_f32_16x16x32_bf16 v[124:127], v[154:157], v[210:213], v[124:127]
	v_mfma_f32_16x16x32_bf16 v[108:111], v[162:165], v[210:213], v[108:111]
	v_mfma_f32_16x16x32_bf16 v[120:123], v[154:157], v[218:221], v[120:123]
	v_mfma_f32_16x16x32_bf16 v[112:115], v[162:165], v[218:221], v[112:115]
	s_setprio 0
	s_setprio 1
	v_mfma_f32_16x16x32_bf16 v[40:43], v[166:169], v[186:189], v[40:43]
	v_mfma_f32_16x16x32_bf16 v[16:19], v[178:181], v[186:189], v[16:19]
	v_mfma_f32_16x16x32_bf16 v[52:55], v[166:169], v[194:197], v[52:55]
	v_mfma_f32_16x16x32_bf16 v[32:35], v[178:181], v[194:197], v[32:35]
	v_mfma_f32_16x16x32_bf16 v[76:79], v[166:169], v[206:209], v[76:79]
	v_mfma_f32_16x16x32_bf16 v[44:47], v[178:181], v[206:209], v[44:47]
	v_mfma_f32_16x16x32_bf16 v[92:95], v[166:169], v[214:217], v[92:95]
	v_mfma_f32_16x16x32_bf16 v[60:63], v[178:181], v[214:217], v[60:63]
	v_mfma_f32_16x16x32_bf16 v[40:43], v[170:173], v[190:193], v[40:43]
	v_mfma_f32_16x16x32_bf16 v[16:19], v[182:185], v[190:193], v[16:19]
	v_mfma_f32_16x16x32_bf16 v[52:55], v[170:173], v[202:205], v[52:55]
	v_mfma_f32_16x16x32_bf16 v[32:35], v[182:185], v[202:205], v[32:35]
	v_mfma_f32_16x16x32_bf16 v[76:79], v[170:173], v[210:213], v[76:79]
	v_mfma_f32_16x16x32_bf16 v[44:47], v[182:185], v[210:213], v[44:47]
	v_mfma_f32_16x16x32_bf16 v[92:95], v[170:173], v[218:221], v[92:95]
	v_mfma_f32_16x16x32_bf16 v[60:63], v[182:185], v[218:221], v[60:63]
	s_setprio 0
	s_barrier
; #define PG8_WAIT_V(n) asm volatile("s_waitcnt vmcnt(" #n ")" ::: "memory")
; template <class Epi, class Sched, bool ALIGN_EPI = false, bool SP2 = false>
; __device__ __forceinline__ void gemm_phase(PG8_LAS unsigned char* lds, const Gemm g, const Sched& S, const Epi& E) {
;     ...
;             PG8_LDA(At, 1, 1); PG8_STAGE(PG8_SB(1, 0), b3, voffB); PG8_STAGE(PG8_SB(1, 1), b3 + hstepB, voffB); PG8_STAGE(PG8_SA(1, 0), a3, voffA);
;             PG8_WAIT_V(8); PG8_WAIT_L(0); PG8_BAR; PG8_MMA(1, 0, At, B0); PG8_MMA(1, 1, At, B1); PG8_BAR; PG8_SCHED;
;             } else {
;             PG8_LDB(B0, 0, 0); PG8_SCHED; PG8_LDA(At, 0, 0); PG8_STAGE(PG8_SA(1, 1), a1 + hstepA, voffA);
;             PG8_WAIT_L(8); PG8_BAR; PG8_WAIT_L(0); PG8_MMA(0, 0, At, B0); PG8_BAR; PG8_SCHED;
;             PG8_LDB(B1, 0, 1); PG8_STAGE(PG8_SB(0, 0), b2, voffB);
;             PG8_BAR; PG8_WAIT_L(0); PG8_MMA(0, 1, At, B1); PG8_BAR;
;             PG8_LDA(At, 0, 1); PG8_STAGE(PG8_SA(0, 0), a2, voffA);
;             PG8_BAR; PG8_WAIT_L(0); PG8_MMA(1, 0, At, B0); PG8_BAR; PG8_SCHED;
;             PG8_STAGE(PG8_SB(0, 1), b2 + hstepB, voffB);
;             PG8_WAIT_V(6); PG8_BAR; PG8_MMA(1, 1, At, B1); PG8_BAR;
;             PG8_LDB(B0, 1, 0); PG8_SCHED; PG8_LDA(At, 1, 0); PG8_STAGE(PG8_SA(0, 1), a2 + hstepA, voffA);
;             PG8_WAIT_L(8); PG8_BAR; PG8_WAIT_L(0); PG8_MMA(0, 0, At, B0); PG8_BAR; PG8_SCHED;
;             PG8_LDB(B1, 1, 1); PG8_STAGE(PG8_SB(1, 0), b3, voffB);
;             PG8_BAR; PG8_WAIT_L(0); PG8_MMA(0, 1, At, B1); PG8_BAR;
;             PG8_LDA(At, 1, 1); PG8_STAGE(PG8_SA(1, 0), a3, voffA);
;             PG8_BAR; PG8_WAIT_L(0); PG8_MMA(1, 0, At, B0); PG8_BAR; PG8_SCHED;
;             PG8_STAGE(PG8_SB(1, 1), b3 + hstepB, voffB);
;             PG8_WAIT_V(6); PG8_BAR; PG8_MMA(1, 1, At, B1); PG8_BAR;
;             }
;         }
;         if constexpr (ALIGN_EPI) { if (wr == 0) PG8_BAR; }
;         if constexpr (!Epi::AFTER_DRAIN) { E(acc, cur, wr, wc, fr, fq); S.done(cur); }
;         if (!has_next) break;
; #pragma unroll
;         for (int a = 0; a < 2; ++a)
; #pragma unroll
;             for (int b = 0; b < 2; ++b)
; #pragma unroll
;                 for (int m = 0; m < 4; ++m)
; #pragma unroll
;                     for (int n = 0; n < 2; ++n) acc[a][b][m][n] = (f32x4){0.f, 0.f, 0.f, 0.f};
;         cur = nxt; cA = nA; cB = nB; ++ui;
	s_add_i32 s18, s45, s27
	v_lshl_add_u64 v[174:175], v[174:175], 0, s[10:11]
	s_mov_b32 m0, s18
	ds_read_b128 v[186:189], v147 offset:49152
	ds_read_b128 v[190:193], v147 offset:50176
	ds_read_b128 v[194:197], v147 offset:51200
	ds_read_b128 v[202:205], v147 offset:52224
	ds_read_b128 v[206:209], v147 offset:53248
	ds_read_b128 v[210:213], v147 offset:54272
	ds_read_b128 v[214:217], v147 offset:55296
	ds_read_b128 v[218:221], v147 offset:56320
	global_load_lds_dwordx4 v[174:175], off
	s_add_i32 m0, s18, 0x2000
	s_add_u32 s16, s16, 0xb0080
	v_lshl_add_u64 v[174:175], v[198:199], 0, s[10:11]
	s_addc_u32 s17, s17, 0
	s_add_i32 s18, s46, s27
	global_load_lds_dwordx4 v[174:175], off
	s_mov_b32 m0, s18
	s_nop 0
	global_load_lds_dwordx4 v128, s[16:17]
	s_add_i32 m0, s18, 0x2000
	s_nop 0
	global_load_lds_dwordx4 v130, s[16:17]
	v_lshl_add_u64 v[174:175], v[222:223], 0, s[10:11]
	s_mov_b32 m0, s35
	s_nop 0
	global_load_lds_dwordx4 v[174:175], off
	v_lshl_add_u64 v[174:175], v[224:225], 0, s[10:11]
	s_mov_b32 m0, s36
	s_nop 0
	global_load_lds_dwordx4 v[174:175], off
	s_waitcnt vmcnt(8)
	s_waitcnt lgkmcnt(0)
	s_barrier
	s_setprio 1
	s_waitcnt lgkmcnt(0)
	v_mfma_f32_16x16x32_bf16 v[100:103], v[148:151], v[186:189], v[100:103]
	v_mfma_f32_16x16x32_bf16 v[96:99], v[158:161], v[186:189], v[96:99]
	v_mfma_f32_16x16x32_bf16 v[68:71], v[148:151], v[194:197], v[68:71]
	v_mfma_f32_16x16x32_bf16 v[64:67], v[158:161], v[194:197], v[64:67]
	v_mfma_f32_16x16x32_bf16 v[36:39], v[148:151], v[206:209], v[36:39]
	v_mfma_f32_16x16x32_bf16 v[28:31], v[158:161], v[206:209], v[28:31]
	v_mfma_f32_16x16x32_bf16 v[12:15], v[148:151], v[214:217], v[12:15]
	v_mfma_f32_16x16x32_bf16 v[8:11], v[158:161], v[214:217], v[8:11]
	v_mfma_f32_16x16x32_bf16 v[100:103], v[154:157], v[190:193], v[100:103]
	v_mfma_f32_16x16x32_bf16 v[96:99], v[162:165], v[190:193], v[96:99]
	v_mfma_f32_16x16x32_bf16 v[68:71], v[154:157], v[202:205], v[68:71]
	v_mfma_f32_16x16x32_bf16 v[64:67], v[162:165], v[202:205], v[64:67]
	v_mfma_f32_16x16x32_bf16 v[36:39], v[154:157], v[210:213], v[36:39]
	v_mfma_f32_16x16x32_bf16 v[28:31], v[162:165], v[210:213], v[28:31]
	v_mfma_f32_16x16x32_bf16 v[12:15], v[154:157], v[218:221], v[12:15]
	v_mfma_f32_16x16x32_bf16 v[8:11], v[162:165], v[218:221], v[8:11]
	s_setprio 0
	s_setprio 1
	v_mfma_f32_16x16x32_bf16 v[84:87], v[166:169], v[186:189], v[84:87]
	v_mfma_f32_16x16x32_bf16 v[80:83], v[178:181], v[186:189], v[80:83]
	v_mfma_f32_16x16x32_bf16 v[56:59], v[166:169], v[194:197], v[56:59]
	v_mfma_f32_16x16x32_bf16 v[48:51], v[178:181], v[194:197], v[48:51]
	v_mfma_f32_16x16x32_bf16 v[24:27], v[166:169], v[206:209], v[24:27]
	v_mfma_f32_16x16x32_bf16 v[20:23], v[178:181], v[206:209], v[20:23]
	v_mfma_f32_16x16x32_bf16 v[4:7], v[166:169], v[214:217], v[4:7]
	v_mfma_f32_16x16x32_bf16 v[0:3], v[178:181], v[214:217], v[0:3]
	v_mfma_f32_16x16x32_bf16 v[84:87], v[170:173], v[190:193], v[84:87]
	v_mfma_f32_16x16x32_bf16 v[80:83], v[182:185], v[190:193], v[80:83]
	v_mfma_f32_16x16x32_bf16 v[56:59], v[170:173], v[202:205], v[56:59]
	v_mfma_f32_16x16x32_bf16 v[48:51], v[182:185], v[202:205], v[48:51]
	v_mfma_f32_16x16x32_bf16 v[24:27], v[170:173], v[210:213], v[24:27]
	v_mfma_f32_16x16x32_bf16 v[20:23], v[182:185], v[210:213], v[20:23]
	v_mfma_f32_16x16x32_bf16 v[4:7], v[170:173], v[218:221], v[4:7]
	v_mfma_f32_16x16x32_bf16 v[0:3], v[182:185], v[218:221], v[0:3]
	s_setprio 0
	s_barrier
	s_add_i32 s44, s44, 2
	s_add_u32 s14, s14, 0x100
	s_addc_u32 s15, s15, 0
	s_cmp_gt_u32 s44, 41
	s_cbranch_scc0 .LBB0_874
	s_add_u32 s14, s42, 0xffffff00
	s_addc_u32 s15, s43, -1
	s_and_b64 vcc, exec, s[2:3]
	s_cbranch_vccnz .LBB0_861
	v_mov_b32_e32 v0, 0
	s_mov_b32 s6, s39
	s_mov_b32 s20, s40
	s_mov_b64 s[8:9], s[12:13]
	s_mov_b32 s34, s41
	v_mov_b32_e32 v1, v0
	v_mov_b32_e32 v2, v0
	v_mov_b32_e32 v3, v0
	v_mov_b32_e32 v4, v0
	v_mov_b32_e32 v5, v0
	v_mov_b32_e32 v6, v0
	v_mov_b32_e32 v7, v0
	v_mov_b32_e32 v20, v0
	v_mov_b32_e32 v21, v0
	v_mov_b32_e32 v22, v0
	v_mov_b32_e32 v23, v0
	v_mov_b32_e32 v24, v0
	v_mov_b32_e32 v25, v0
	v_mov_b32_e32 v26, v0
	v_mov_b32_e32 v27, v0
	v_mov_b32_e32 v48, v0
	v_mov_b32_e32 v49, v0
	v_mov_b32_e32 v50, v0
	v_mov_b32_e32 v51, v0
	v_mov_b32_e32 v56, v0
	v_mov_b32_e32 v57, v0
	v_mov_b32_e32 v58, v0
	v_mov_b32_e32 v59, v0
	v_mov_b32_e32 v80, v0
	v_mov_b32_e32 v81, v0
	v_mov_b32_e32 v82, v0
	v_mov_b32_e32 v83, v0
	v_mov_b32_e32 v84, v0
	v_mov_b32_e32 v85, v0
	v_mov_b32_e32 v86, v0
	v_mov_b32_e32 v87, v0
	v_mov_b32_e32 v8, v0
	v_mov_b32_e32 v9, v0
	v_mov_b32_e32 v10, v0
	v_mov_b32_e32 v11, v0
	v_mov_b32_e32 v12, v0
	v_mov_b32_e32 v13, v0
	v_mov_b32_e32 v14, v0
	v_mov_b32_e32 v15, v0
	v_mov_b32_e32 v28, v0
	v_mov_b32_e32 v29, v0
	v_mov_b32_e32 v30, v0
	v_mov_b32_e32 v31, v0
	v_mov_b32_e32 v36, v0
	v_mov_b32_e32 v37, v0
	v_mov_b32_e32 v38, v0
	v_mov_b32_e32 v39, v0
	v_mov_b32_e32 v64, v0
	v_mov_b32_e32 v65, v0
	v_mov_b32_e32 v66, v0
	v_mov_b32_e32 v67, v0
	v_mov_b32_e32 v68, v0
	v_mov_b32_e32 v69, v0
	v_mov_b32_e32 v70, v0
	v_mov_b32_e32 v71, v0
	v_mov_b32_e32 v96, v0
	v_mov_b32_e32 v97, v0
	v_mov_b32_e32 v98, v0
	v_mov_b32_e32 v99, v0
	v_mov_b32_e32 v100, v0
	v_mov_b32_e32 v101, v0
	v_mov_b32_e32 v102, v0
	v_mov_b32_e32 v103, v0
	v_mov_b32_e32 v60, v0
	v_mov_b32_e32 v61, v0
	v_mov_b32_e32 v62, v0
	v_mov_b32_e32 v63, v0
	v_mov_b32_e32 v92, v0
	v_mov_b32_e32 v93, v0
	v_mov_b32_e32 v94, v0
	v_mov_b32_e32 v95, v0
	v_mov_b32_e32 v44, v0
	v_mov_b32_e32 v45, v0
	v_mov_b32_e32 v46, v0
	v_mov_b32_e32 v47, v0
	v_mov_b32_e32 v76, v0
	v_mov_b32_e32 v77, v0
	v_mov_b32_e32 v78, v0
	v_mov_b32_e32 v79, v0
	v_mov_b32_e32 v32, v0
	v_mov_b32_e32 v33, v0
	v_mov_b32_e32 v34, v0
	v_mov_b32_e32 v35, v0
	v_mov_b32_e32 v52, v0
	v_mov_b32_e32 v53, v0
	v_mov_b32_e32 v54, v0
	v_mov_b32_e32 v55, v0
	v_mov_b32_e32 v16, v0
	v_mov_b32_e32 v17, v0
	v_mov_b32_e32 v18, v0
	v_mov_b32_e32 v19, v0
	v_mov_b32_e32 v40, v0
	v_mov_b32_e32 v41, v0
	v_mov_b32_e32 v42, v0
	v_mov_b32_e32 v43, v0
	v_mov_b32_e32 v112, v0
	v_mov_b32_e32 v113, v0
	v_mov_b32_e32 v114, v0
	v_mov_b32_e32 v115, v0
	v_mov_b32_e32 v120, v0
	v_mov_b32_e32 v121, v0
	v_mov_b32_e32 v122, v0
	v_mov_b32_e32 v123, v0
	v_mov_b32_e32 v108, v0
	v_mov_b32_e32 v109, v0
	v_mov_b32_e32 v110, v0
	v_mov_b32_e32 v111, v0
	v_mov_b32_e32 v124, v0
	v_mov_b32_e32 v125, v0
	v_mov_b32_e32 v126, v0
	v_mov_b32_e32 v127, v0
	v_mov_b32_e32 v88, v0
	v_mov_b32_e32 v89, v0
	v_mov_b32_e32 v90, v0
	v_mov_b32_e32 v91, v0
	v_mov_b32_e32 v116, v0
	v_mov_b32_e32 v117, v0
	v_mov_b32_e32 v118, v0
	v_mov_b32_e32 v119, v0
	v_mov_b32_e32 v72, v0
	v_mov_b32_e32 v73, v0
	v_mov_b32_e32 v74, v0
	v_mov_b32_e32 v75, v0
	v_mov_b32_e32 v104, v0
	v_mov_b32_e32 v105, v0
	v_mov_b32_e32 v106, v0
	v_mov_b32_e32 v107, v0
	s_andn2_b64 vcc, exec, s[0:1]
	s_cbranch_vccnz .LBB0_862

; __global__ void __launch_bounds__(NTHR, 2) fwd_kernel(Ptrs P) {
	.amdhsa_kernel _Z10fwd_kernel4Ptrs
		.amdhsa_group_segment_fixed_size 0
		.amdhsa_private_segment_fixed_size 0
		.amdhsa_kernarg_size 432
		.amdhsa_user_sgpr_count 2
		.amdhsa_user_sgpr_dispatch_ptr 0
		.amdhsa_user_sgpr_queue_ptr 0
		.amdhsa_user_sgpr_kernarg_segment_ptr 1
		.amdhsa_user_sgpr_dispatch_id 0
		.amdhsa_user_sgpr_kernarg_preload_length 0
		.amdhsa_user_sgpr_kernarg_preload_offset 0
		.amdhsa_user_sgpr_private_segment_size 0
		.amdhsa_uses_dynamic_stack 0
		.amdhsa_enable_private_segment 0
		.amdhsa_system_sgpr_workgroup_id_x 1
		.amdhsa_system_sgpr_workgroup_id_y 0
		.amdhsa_system_sgpr_workgroup_id_z 0
		.amdhsa_system_sgpr_workgroup_info 0
		.amdhsa_system_vgpr_workitem_id 2
		.amdhsa_next_free_vgpr 256
		.amdhsa_next_free_sgpr 102
		.amdhsa_accum_offset 256
		.amdhsa_reserve_vcc 1
		.amdhsa_float_round_mode_32 0
		.amdhsa_float_round_mode_16_64 0
		.amdhsa_float_denorm_mode_32 3
		.amdhsa_float_denorm_mode_16_64 3
		.amdhsa_dx10_clamp 1
		.amdhsa_ieee_mode 1
		.amdhsa_fp16_overflow 0
		.amdhsa_tg_split 0
		.amdhsa_exception_fp_ieee_invalid_op 0
		.amdhsa_exception_fp_denorm_src 0
		.amdhsa_exception_fp_ieee_div_zero 0
		.amdhsa_exception_fp_ieee_overflow 0
		.amdhsa_exception_fp_ieee_underflow 0
		.amdhsa_exception_fp_ieee_inexact 0
		.amdhsa_exception_int_div_zero 0
	.end_amdhsa_kernel

; __global__ void __launch_bounds__(NTHR, 2) fwd_kernel(Ptrs P) {
amdhsa.kernels:
  - .agpr_count:     0
    .args:
      - .offset:         0
        .size:           176
        .value_kind:     by_value
      - .offset:         176
        .size:           4
        .value_kind:     hidden_block_count_x
      - .offset:         180
        .size:           4
        .value_kind:     hidden_block_count_y
      - .offset:         184
        .size:           4
        .value_kind:     hidden_block_count_z
      - .offset:         188
        .size:           2
        .value_kind:     hidden_group_size_x
      - .offset:         190
        .size:           2
        .value_kind:     hidden_group_size_y
      - .offset:         192
        .size:           2
        .value_kind:     hidden_group_size_z
      - .offset:         194
        .size:           2
        .value_kind:     hidden_remainder_x
      - .offset:         196
        .size:           2
        .value_kind:     hidden_remainder_y
      - .offset:         198
        .size:           2
        .value_kind:     hidden_remainder_z
      - .offset:         216
        .size:           8
        .value_kind:     hidden_global_offset_x
      - .offset:         224
        .size:           8
        .value_kind:     hidden_global_offset_y
      - .offset:         232
        .size:           8
        .value_kind:     hidden_global_offset_z
      - .offset:         240
        .size:           2
        .value_kind:     hidden_grid_dims
      - .offset:         264
        .size:           8
        .value_kind:     hidden_multigrid_sync_arg
      - .offset:         296
        .size:           4
        .value_kind:     hidden_dynamic_lds_size
    .group_segment_fixed_size: 0
    .kernarg_segment_align: 8
    .kernarg_segment_size: 432
    .language:       OpenCL C
    .language_version:
      - 2
      - 0
    .max_flat_workgroup_size: 512
    .name:           _Z10fwd_kernel4Ptrs
    .private_segment_fixed_size: 0
    .sgpr_count:     108
    .sgpr_spill_count: 53
    .symbol:         _Z10fwd_kernel4Ptrs.kd
    .uniform_work_group_size: 1
    .uses_dynamic_stack: false
    .vgpr_count:     256
    .vgpr_spill_count: 0
    .wavefront_size: 64
